# attention max-reduce with one copy: permlane swap works in place on the running value (109 fewer VALU per item)
# speedup vs baseline: 1.0052x; 1.0024x over previous
.LBB0_246:
	s_lshl_b32 s1, s71, 2
	s_and_b32 s22, s1, 0xffffff00
	s_lshr_b32 s0, s71, 3
	s_bfe_u32 s56, s71, 0x30003
	s_or_b32 s24, s22, s72
	s_cmp_lt_i32 s24, 0x8000
	s_movk_i32 s22, 0xfff
	s_cselect_b32 s75, s22, 0x1fff
	s_bfe_u32 s0, s0, 0x10002
	s_andn2_b32 s74, s1, s75
	s_mul_i32 s0, s0, 0x1800000
	s_add_u32 s0, s96, s0
	s_addc_u32 s1, s97, 0
	s_lshl_b32 s22, s71, 4
	s_and_b32 s22, s22, 0x180
	s_add_u32 s22, s0, s22
	v_or_b32_e32 v162, s24, v167
	s_addc_u32 s23, s1, 0
	v_ashrrev_i32_e32 v163, 31, v162
	v_lshl_add_u64 v[12:13], s[22:23], 0, v[158:159]
	v_lshlrev_b64 v[0:1], 9, v[162:163]
	v_lshl_add_u64 v[8:9], v[12:13], 0, v[0:1]
	global_load_dwordx4 v[0:3], v[8:9], off
	v_or_b32_e32 v160, 8, v162
	v_ashrrev_i32_e32 v161, 31, v160
	s_add_u32 s68, s22, 0x3000000
	s_addc_u32 s69, s23, 0
	s_lshl_b32 s98, s74, 9
	s_add_u32 s100, s68, s98
	s_addc_u32 s101, s69, 0
	s_add_u32 s98, s100, 0x3000000
	s_addc_u32 s99, s101, 0
	s_sub_i32 s76, s24, s74
	s_sub_i32 s0, s76, 64
	s_waitcnt vmcnt(7)
	v_add_u32_e32 v20, s0, v172
	v_min_i32_e32 v21, s75, v20
	s_waitcnt vmcnt(6)
	v_add_u32_e32 v24, s0, v173
	v_min_i32_e32 v25, s75, v24
	s_waitcnt vmcnt(5)
	v_add_u32_e32 v28, s0, v182
	v_min_i32_e32 v29, s75, v28
	s_waitcnt vmcnt(2)
	v_add_u32_e32 v40, s0, v166
	v_min_i32_e32 v32, s75, v40
	v_add_u32_e32 v41, 16, v40
	s_movk_i32 s1, 0xffef
	v_min_i32_e32 v41, s75, v41
	v_or_b32_e32 v128, 32, v166
	v_add_u32_e32 v56, s0, v128
	v_add_u32_e32 v149, s76, v155
	v_add_u32_e32 v150, s76, v172
	v_add_u32_e32 v151, s76, v173
	v_add_u32_e32 v252, s76, v182
	v_or_b32_e32 v251, s76, v167
	v_subrev_u32_e32 v250, s76, v251
	v_or_b32_e32 v144, 8, v251
	v_subrev_u32_e32 v249, s76, v144
	v_add_u32_e32 v196, 0x60, v155
	v_add_u32_e32 v168, 0x60, v172
	v_add_u32_e32 v193, 0x60, v173
	v_add_u32_e32 v194, 0x60, v182
	v_add_u32_e32 v186, s76, v206
	s_waitcnt vmcnt(0)
	v_lshlrev_b32_e32 v4, 16, v0
	v_and_b32_e32 v5, 0xffff0000, v0
	v_lshlrev_b32_e32 v0, 16, v1
	v_and_b32_e32 v1, 0xffff0000, v1
	v_pk_mul_f32 v[4:5], v[4:5], s[58:59] op_sel_hi:[1,0]
	v_pk_mul_f32 v[0:1], v[0:1], s[58:59] op_sel_hi:[1,0]
	v_cvt_pk_bf16_f32 v4, v4, v5
	v_cvt_pk_bf16_f32 v5, v0, v1
	v_lshlrev_b32_e32 v0, 16, v2
	v_and_b32_e32 v1, 0xffff0000, v2
	v_pk_mul_f32 v[0:1], v[0:1], s[58:59] op_sel_hi:[1,0]
	s_nop 0
	v_cvt_pk_bf16_f32 v6, v0, v1
	v_lshlrev_b32_e32 v0, 16, v3
	v_and_b32_e32 v1, 0xffff0000, v3
	v_pk_mul_f32 v[0:1], v[0:1], s[58:59] op_sel_hi:[1,0]
	s_nop 0
	v_cvt_pk_bf16_f32 v7, v0, v1
	global_load_dwordx4 v[0:3], v[8:9], off offset:64
	s_waitcnt vmcnt(0)
	v_lshlrev_b32_e32 v8, 16, v0
	v_and_b32_e32 v9, 0xffff0000, v0
	v_lshlrev_b32_e32 v0, 16, v1
	v_and_b32_e32 v1, 0xffff0000, v1
	v_pk_mul_f32 v[8:9], v[8:9], s[58:59] op_sel_hi:[1,0]
	v_pk_mul_f32 v[0:1], v[0:1], s[58:59] op_sel_hi:[1,0]
	v_cvt_pk_bf16_f32 v8, v8, v9
	v_cvt_pk_bf16_f32 v9, v0, v1
	v_lshlrev_b32_e32 v0, 16, v2
	v_and_b32_e32 v1, 0xffff0000, v2
	v_pk_mul_f32 v[0:1], v[0:1], s[58:59] op_sel_hi:[1,0]
	s_nop 0
	v_cvt_pk_bf16_f32 v10, v0, v1
	v_lshlrev_b32_e32 v0, 16, v3
	v_and_b32_e32 v1, 0xffff0000, v3
	v_pk_mul_f32 v[0:1], v[0:1], s[58:59] op_sel_hi:[1,0]
	s_nop 0
	v_cvt_pk_bf16_f32 v11, v0, v1
	v_lshlrev_b64 v[0:1], 9, v[160:161]
	v_lshl_add_u64 v[16:17], v[12:13], 0, v[0:1]
	global_load_dwordx4 v[0:3], v[16:17], off
	s_waitcnt vmcnt(0)
	v_lshlrev_b32_e32 v12, 16, v0
	v_and_b32_e32 v13, 0xffff0000, v0
	v_lshlrev_b32_e32 v0, 16, v1
	v_and_b32_e32 v1, 0xffff0000, v1
	v_pk_mul_f32 v[12:13], v[12:13], s[58:59] op_sel_hi:[1,0]
	v_pk_mul_f32 v[0:1], v[0:1], s[58:59] op_sel_hi:[1,0]
	v_cvt_pk_bf16_f32 v12, v12, v13
	v_cvt_pk_bf16_f32 v13, v0, v1
	v_lshlrev_b32_e32 v0, 16, v2
	v_and_b32_e32 v1, 0xffff0000, v2
	v_pk_mul_f32 v[0:1], v[0:1], s[58:59] op_sel_hi:[1,0]
	s_nop 0
	v_cvt_pk_bf16_f32 v14, v0, v1
	v_lshlrev_b32_e32 v0, 16, v3
	v_and_b32_e32 v1, 0xffff0000, v3
	v_pk_mul_f32 v[0:1], v[0:1], s[58:59] op_sel_hi:[1,0]
	s_nop 0
	v_cvt_pk_bf16_f32 v15, v0, v1
	global_load_dwordx4 v[0:3], v[16:17], off offset:64
	s_waitcnt vmcnt(0)
	v_lshlrev_b32_e32 v16, 16, v0
	v_and_b32_e32 v17, 0xffff0000, v0
	v_pk_mul_f32 v[16:17], v[16:17], s[58:59] op_sel_hi:[1,0]
	s_nop 0
	v_cvt_pk_bf16_f32 v0, v16, v17
	v_lshlrev_b32_e32 v16, 16, v1
	v_and_b32_e32 v17, 0xffff0000, v1
	v_pk_mul_f32 v[16:17], v[16:17], s[58:59] op_sel_hi:[1,0]
	s_nop 0
	v_cvt_pk_bf16_f32 v1, v16, v17
	v_lshlrev_b32_e32 v16, 16, v2
	v_and_b32_e32 v17, 0xffff0000, v2
	v_pk_mul_f32 v[16:17], v[16:17], s[58:59] op_sel_hi:[1,0]
	s_nop 0
	v_cvt_pk_bf16_f32 v2, v16, v17
	v_lshlrev_b32_e32 v16, 16, v3
	v_and_b32_e32 v17, 0xffff0000, v3
	v_pk_mul_f32 v[16:17], v[16:17], s[58:59] op_sel_hi:[1,0]
	s_nop 0
	v_cvt_pk_bf16_f32 v3, v16, v17
	s_mov_b64 s[22:23], 0x6000000
	v_add_u32_e32 v16, s0, v155
	s_sub_i32 s22, 0x80, s76
	s_nop 0
	v_med3_i32 v16, v16, 0, s75
	v_cmp_lt_i32_e32 vcc, -1, v20
	s_nop 1
	v_cndmask_b32_e32 v20, 0, v21, vcc
	v_cmp_lt_i32_e32 vcc, -1, v24
	s_nop 1
	v_cndmask_b32_e32 v24, 0, v25, vcc
	v_cmp_lt_i32_e32 vcc, -1, v28
	s_nop 1
	v_cndmask_b32_e32 v28, 0, v29, vcc
	v_lshl_add_u32 v16, v16, 9, v152
	global_load_dwordx4 v[16:19], v16, s[98:99]
	v_lshl_add_u32 v20, v20, 9, v152
	v_cmp_lt_i32_e32 vcc, -1, v40
	global_load_dwordx4 v[20:23], v20, s[98:99]
	v_lshl_add_u32 v24, v24, 9, v152
	v_cndmask_b32_e32 v32, 0, v32, vcc
	v_cmp_lt_i32_e32 vcc, s1, v40
	global_load_dwordx4 v[24:27], v24, s[98:99]
	v_lshl_add_u32 v28, v28, 9, v152
	v_cndmask_b32_e32 v40, 0, v41, vcc
	global_load_dwordx4 v[28:31], v28, s[98:99]
	v_lshl_add_u32 v36, v32, 9, v158
	v_lshl_add_u32 v40, v40, 9, v158
	s_sub_i32 s1, s76, 32
	global_load_dwordx4 v[32:35], v36, s[100:101]
	s_nop 0
	global_load_dwordx4 v[36:39], v36, s[100:101] offset:64
	s_nop 0
	global_load_dwordx4 v[48:51], v40, s[100:101]
	global_load_dwordx4 v[52:55], v40, s[100:101] offset:64
	v_add_u32_e32 v40, s1, v155
	v_med3_i32 v40, v40, 0, s75
	v_lshl_add_u32 v40, v40, 9, v152
	global_load_dwordx4 v[76:79], v40, s[98:99]
	v_add_u32_e32 v40, s1, v172
	v_med3_i32 v40, v40, 0, s75
	v_lshl_add_u32 v40, v40, 9, v152
	global_load_dwordx4 v[84:87], v40, s[98:99]
	v_add_u32_e32 v40, s1, v173
	v_med3_i32 v40, v40, 0, s75
	v_lshl_add_u32 v40, v40, 9, v152
	global_load_dwordx4 v[88:91], v40, s[98:99]
	v_add_u32_e32 v40, s1, v182
	s_min_i32 s1, s0, 0
	s_sub_i32 s1, 0, s1
	v_med3_i32 v40, v40, 0, s75
	v_lshl_add_u32 v40, v40, 9, v152
	global_load_dwordx4 v[92:95], v40, s[98:99]
	v_min_i32_e32 v40, s75, v56
	v_cmp_lt_i32_e32 vcc, -1, v56
	v_add_u32_e32 v56, 16, v56
	s_nop 0
	v_cndmask_b32_e32 v40, 0, v40, vcc
	v_med3_i32 v56, v56, 0, s75
	v_lshl_add_u32 v44, v40, 9, v158
	v_lshl_add_u32 v60, v56, 9, v158
	global_load_dwordx4 v[40:43], v44, s[100:101]
	s_nop 0
	global_load_dwordx4 v[44:47], v44, s[100:101] offset:64
	s_nop 0
	global_load_dwordx4 v[56:59], v60, s[100:101]
	s_nop 0
	global_load_dwordx4 v[60:63], v60, s[100:101] offset:64
	s_waitcnt vmcnt(15)
	ds_write_b128 v241, v[16:19]
	s_waitcnt vmcnt(14)
	ds_write_b128 v242, v[20:23]
	s_waitcnt vmcnt(13)
	ds_write_b128 v243, v[24:27]
	s_waitcnt vmcnt(12)
	ds_write_b128 v244, v[28:31]
	v_or_b32_e32 v24, 16, v166
	v_add_u32_e32 v24, s76, v24
	v_med3_i32 v16, v149, 0, s75
	v_lshl_add_u32 v16, v16, 9, v152
	global_load_dwordx4 v[64:67], v16, s[98:99]
	s_sub_i32 s0, s75, s0
	v_med3_i32 v16, v150, 0, s75
	v_lshl_add_u32 v16, v16, 9, v152
	global_load_dwordx4 v[68:71], v16, s[98:99]
	v_max_i32_e32 v147, s1, v250
	v_max_i32_e32 v148, s1, v249
	v_med3_i32 v16, v151, 0, s75
	v_lshl_add_u32 v16, v16, 9, v152
	global_load_dwordx4 v[72:75], v16, s[98:99]
	v_med3_i32 v16, v252, 0, s75
	v_lshl_add_u32 v16, v16, 9, v152
	global_load_dwordx4 v[80:83], v16, s[98:99]
	v_add_u32_e32 v16, s76, v166
	v_med3_i32 v16, v16, 0, s75
	v_med3_i32 v24, v24, 0, s75
	v_lshl_add_u32 v20, v16, 9, v158
	v_lshl_add_u32 v28, v24, 9, v158
	global_load_dwordx4 v[16:19], v20, s[100:101]
	s_nop 0
	global_load_dwordx4 v[20:23], v20, s[100:101] offset:64
	s_nop 0
	global_load_dwordx4 v[24:27], v28, s[100:101]
	s_nop 0
	global_load_dwordx4 v[28:31], v28, s[100:101] offset:64
	ds_read_b64_tr_b16 v[98:99], v169 offset:2304
	ds_read_b64_tr_b16 v[96:97], v169
	ds_read_b64_tr_b16 v[100:101], v169 offset:32
	ds_read_b64_tr_b16 v[102:103], v169 offset:2336
	ds_read_b64_tr_b16 v[116:117], v169 offset:64
	ds_read_b64_tr_b16 v[118:119], v169 offset:2368
	ds_read_b64_tr_b16 v[134:135], v169 offset:96
	ds_read_b64_tr_b16 v[136:137], v169 offset:2400
	s_waitcnt vmcnt(15)
	ds_write_b128 v241, v[76:79] offset:4608
	s_waitcnt vmcnt(14)
	ds_write_b128 v242, v[84:87] offset:4608
	s_waitcnt vmcnt(13)
	ds_write_b128 v243, v[88:91] offset:4608
	s_waitcnt vmcnt(12)
	ds_write_b128 v244, v[92:95] offset:4608
	v_mfma_f32_16x16x32_bf16 v[76:79], v[32:35], v[4:7], 0
	v_mfma_f32_16x16x32_bf16 v[32:35], v[32:35], v[12:15], 0
	v_mfma_f32_16x16x32_bf16 v[76:79], v[36:39], v[8:11], v[76:79]
	v_mfma_f32_16x16x32_bf16 v[84:87], v[48:51], v[4:7], 0
	v_mfma_f32_16x16x32_bf16 v[32:35], v[36:39], v[0:3], v[32:35]
	v_mfma_f32_16x16x32_bf16 v[36:39], v[48:51], v[12:15], 0
	v_add_u32_e32 v48, s22, v251
	v_min3_i32 v48, v48, s0, v245
	v_sub_u32_e32 v49, v154, v147
	v_sub_u32_e32 v146, v48, v147
	v_add_u32_e32 v48, s22, v144
	v_min3_i32 v48, v48, s0, v245
	v_add_u32_e32 v51, 1, v49
	v_sub_u32_e32 v145, v48, v148
	v_cmp_gt_u32_e64 s[0:1], v51, v146
	v_cmp_gt_u32_e32 vcc, v49, v146
	s_nop 0
	v_cndmask_b32_e64 v77, v77, v246, s[0:1]
	s_nop 0
	v_cndmask_b32_e32 v76, v76, v246, vcc
	v_max_f32_e32 v48, 0xf149f2ca, v76
	v_mfma_f32_16x16x32_bf16 v[84:87], v[52:55], v[8:11], v[84:87]
	v_max_f32_e32 v48, v48, v77
	v_add_u32_e32 v51, 2, v49
	v_cmp_gt_u32_e64 s[22:23], v51, v146
	v_mfma_f32_16x16x32_bf16 v[36:39], v[52:55], v[0:3], v[36:39]
	v_add_u32_e32 v52, 3, v49
	v_cmp_gt_u32_e64 s[24:25], v52, v146
	v_cndmask_b32_e64 v78, v78, v246, s[22:23]
	v_sub_u32_e32 v50, v154, v148
	v_cndmask_b32_e64 v79, v79, v246, s[24:25]
	v_max3_f32 v48, v48, v78, v79
	v_add_u32_e32 v51, 16, v49
	v_add_u32_e32 v52, 17, v49
	v_cmp_gt_u32_e64 s[26:27], v51, v146
	v_cmp_gt_u32_e64 s[28:29], v52, v146
	v_cmp_gt_u32_e64 s[38:39], v50, v145
	v_cndmask_b32_e64 v84, v84, v246, s[26:27]
	v_cndmask_b32_e64 v85, v85, v246, s[28:29]
	v_max3_f32 v48, v48, v84, v85
	v_add_u32_e32 v51, 18, v49
	v_add_u32_e32 v49, 19, v49
	v_cmp_gt_u32_e64 s[30:31], v51, v146
	v_cmp_gt_u32_e64 s[34:35], v49, v146
	v_add_u32_e32 v52, 3, v50
	v_cndmask_b32_e64 v86, v86, v246, s[30:31]
	v_cndmask_b32_e64 v87, v87, v246, s[34:35]
	v_max3_f32 v48, v48, v86, v87
	v_add_u32_e32 v51, 1, v50
	v_cmp_gt_u32_e64 s[40:41], v51, v145
	v_cndmask_b32_e64 v32, v32, v246, s[38:39]
	v_max_f32_e32 v49, 0xf149f2ca, v32
	v_cndmask_b32_e64 v33, v33, v246, s[40:41]
	v_max_f32_e32 v49, v49, v33
	v_add_u32_e32 v51, 2, v50
	v_cmp_gt_u32_e64 s[42:43], v51, v145
	v_cmp_gt_u32_e64 s[44:45], v52, v145
	s_nop 0
	v_cndmask_b32_e64 v34, v34, v246, s[42:43]
	v_cndmask_b32_e64 v35, v35, v246, s[44:45]
	v_max3_f32 v49, v49, v34, v35
	v_add_u32_e32 v51, 16, v50
	v_add_u32_e32 v52, 17, v50
	v_cmp_gt_u32_e64 s[46:47], v51, v145
	v_cmp_gt_u32_e64 s[48:49], v52, v145
	s_nop 0
	v_cndmask_b32_e64 v36, v36, v246, s[46:47]
	v_cndmask_b32_e64 v37, v37, v246, s[48:49]
	v_max3_f32 v49, v49, v36, v37
	v_add_u32_e32 v51, 18, v50
	v_add_u32_e32 v50, 19, v50
	v_cmp_gt_u32_e64 s[50:51], v51, v145
	v_cmp_gt_u32_e64 s[52:53], v50, v145
	s_nop 0
	v_cndmask_b32_e64 v38, v38, v246, s[50:51]
	v_cndmask_b32_e64 v39, v39, v246, s[52:53]
	v_max3_f32 v49, v49, v38, v39
	v_mov_b32_e32 v50, v48
	s_nop 1
	v_permlane32_swap_b32_e32 v50, v48
	v_max_f32_e32 v48, v48, v50
	v_mov_b32_e32 v50, v49
	s_nop 1
	v_permlane32_swap_b32_e32 v50, v49
	v_max_f32_e32 v49, v49, v50
	v_mov_b32_e32 v50, v48
	s_nop 1
	v_permlane16_swap_b32_e32 v50, v48
	v_max_f32_e32 v48, v48, v50
	v_mov_b32_e32 v50, v49
	s_nop 1
	v_permlane16_swap_b32_e32 v50, v49
	v_max_f32_e32 v129, s73, v48
	v_sub_f32_e32 v48, 0xf149f2ca, v129
	v_max_f32_e32 v49, v49, v50
	v_exp_f32_e32 v50, v48
	v_sub_f32_e32 v48, v76, v129
	v_exp_f32_e32 v48, v48
	v_sub_f32_e32 v52, v77, v129
	v_max_f32_e32 v131, s73, v49
	v_exp_f32_e32 v52, v52
	v_sub_f32_e32 v36, v36, v131
	v_sub_f32_e32 v53, v78, v129
	v_exp_f32_e32 v36, v36
	v_exp_f32_e32 v53, v53
	v_sub_f32_e32 v54, v79, v129
	v_cndmask_b32_e64 v51, v48, 0, vcc
	v_exp_f32_e32 v54, v54
	v_sub_f32_e32 v55, v84, v129
	v_add_f32_e32 v48, 0, v51
	v_exp_f32_e32 v55, v55
	v_sub_f32_e32 v76, v85, v129
	v_add_f32_e32 v48, v52, v48
	v_exp_f32_e32 v76, v76
	v_sub_f32_e32 v77, v86, v129
	v_cvt_pk_bf16_f32 v52, v51, v52
	v_cndmask_b32_e64 v51, v36, 0, s[46:47]
	v_sub_f32_e32 v36, v37, v131
	v_exp_f32_e32 v77, v77
	v_sub_f32_e32 v78, v87, v129
	v_exp_f32_e32 v36, v36
	v_add_f32_e32 v48, v53, v48
	v_exp_f32_e32 v78, v78
	v_add_f32_e32 v48, v54, v48
	v_sub_f32_e32 v32, v32, v131
	v_add_f32_e32 v48, v55, v48
	v_exp_f32_e32 v32, v32
	v_sub_f32_e32 v33, v33, v131
	v_add_f32_e32 v48, v76, v48
	v_cvt_pk_bf16_f32 v53, v53, v54
	v_cvt_pk_bf16_f32 v54, v55, v76
	v_exp_f32_e32 v33, v33
	v_sub_f32_e32 v34, v34, v131
	v_cndmask_b32_e64 v76, v36, 0, s[48:49]
	v_sub_f32_e32 v36, v38, v131
	v_add_f32_e32 v48, v77, v48
	v_exp_f32_e32 v34, v34
	v_sub_f32_e32 v35, v35, v131
	v_exp_f32_e32 v36, v36
	v_add_f32_e32 v130, v78, v48
	v_exp_f32_e32 v35, v35
	v_mul_f32_e32 v48, 0, v50
	v_fmac_f32_e32 v130, 0, v50
	v_cndmask_b32_e64 v50, v32, 0, s[38:39]
	v_add_f32_e32 v32, 0, v50
	v_cvt_pk_bf16_f32 v55, v77, v78
	v_add_f32_e32 v32, v33, v32
	v_cndmask_b32_e64 v77, v36, 0, s[50:51]
	v_sub_f32_e32 v36, v39, v131
	v_sub_f32_e32 v49, 0xf149f2ca, v131
	v_add_f32_e32 v32, v34, v32
	v_exp_f32_e32 v36, v36
	v_exp_f32_e32 v49, v49
	v_add_f32_e32 v32, v35, v32
	v_add_f32_e32 v32, v51, v32
	v_add_f32_e32 v32, v76, v32
	v_add_f32_e32 v32, v77, v32
	v_cndmask_b32_e64 v39, v36, 0, s[52:53]
	v_add_f32_e32 v132, v39, v32
	v_mul_f32_e32 v32, 0, v49
	v_fmac_f32_e32 v132, 0, v49
	v_cvt_pk_bf16_f32 v36, v50, v33
	v_cvt_pk_bf16_f32 v37, v34, v35
	v_cvt_pk_bf16_f32 v38, v51, v76
	v_cvt_pk_bf16_f32 v39, v77, v39
	v_mov_b32_e32 v49, v48
	v_mov_b32_e32 v50, v48
	v_mov_b32_e32 v51, v48
	v_mov_b32_e32 v33, v32
	v_mov_b32_e32 v34, v32
	v_mov_b32_e32 v35, v32
	s_waitcnt lgkmcnt(6)
	v_mfma_f32_16x16x32_bf16 v[112:115], v[116:119], v[52:55], v[48:51]
	v_mfma_f32_16x16x32_bf16 v[124:127], v[96:99], v[36:39], v[32:35]
	v_mfma_f32_16x16x32_bf16 v[108:111], v[100:103], v[36:39], v[32:35]
	v_mfma_f32_16x16x32_bf16 v[116:119], v[116:119], v[36:39], v[32:35]
	s_waitcnt lgkmcnt(4)
	v_mfma_f32_16x16x32_bf16 v[88:91], v[134:137], v[36:39], v[32:35]
	s_nop 2
	v_add_u32_e32 v32, 32, v155
	v_add_u32_e32 v32, s76, v32
	v_mfma_f32_16x16x32_bf16 v[120:123], v[96:99], v[52:55], v[48:51]
	s_nop 0
	v_med3_i32 v32, v32, 0, s75
	v_lshl_add_u32 v32, v32, 9, v152
	global_load_dwordx4 v[76:79], v32, s[98:99]
	v_add_u32_e32 v32, 32, v172
	v_add_u32_e32 v32, s76, v32
	v_mfma_f32_16x16x32_bf16 v[104:107], v[100:103], v[52:55], v[48:51]
	s_nop 0
	v_med3_i32 v32, v32, 0, s75
	v_lshl_add_u32 v32, v32, 9, v152
	global_load_dwordx4 v[84:87], v32, s[98:99]
	v_add_u32_e32 v32, 32, v173
	v_add_u32_e32 v32, s76, v32
	v_mfma_f32_16x16x32_bf16 v[96:99], v[134:137], v[52:55], v[48:51]
	s_nop 0
	v_med3_i32 v32, v32, 0, s75
	v_lshl_add_u32 v32, v32, 9, v152
	global_load_dwordx4 v[92:95], v32, s[98:99]
	v_add_u32_e32 v32, 32, v182
	v_add_u32_e32 v32, s76, v32
	v_or_b32_e32 v48, 48, v166
	v_add_u32_e32 v48, s76, v48
	v_med3_i32 v32, v32, 0, s75
	v_lshl_add_u32 v32, v32, 9, v152
	global_load_dwordx4 v[100:103], v32, s[98:99]
	v_add_u32_e32 v32, s76, v128
	s_nop 0
	v_med3_i32 v32, v32, 0, s75
	v_med3_i32 v48, v48, 0, s75
	v_lshl_add_u32 v36, v32, 9, v158
	v_lshl_add_u32 v52, v48, 9, v158
	global_load_dwordx4 v[32:35], v36, s[100:101]
	s_nop 0
	global_load_dwordx4 v[36:39], v36, s[100:101] offset:64
	s_nop 0
	global_load_dwordx4 v[48:51], v52, s[100:101]
	s_nop 0
	global_load_dwordx4 v[52:55], v52, s[100:101] offset:64
	ds_read_b64_tr_b16 v[136:137], v169 offset:6912
	ds_read_b64_tr_b16 v[134:135], v169 offset:4608
	ds_read_b64_tr_b16 v[138:139], v169 offset:4640
	ds_read_b64_tr_b16 v[140:141], v169 offset:6944
	ds_read_b64_tr_b16 v[176:177], v169 offset:4672
	ds_read_b64_tr_b16 v[178:179], v169 offset:6976
	ds_read_b64_tr_b16 v[188:189], v169 offset:4704
	ds_read_b64_tr_b16 v[190:191], v169 offset:7008
	s_waitcnt vmcnt(15)
	ds_write_b128 v241, v[64:67]
	s_waitcnt vmcnt(14)
	ds_write_b128 v242, v[68:71]
	s_waitcnt vmcnt(13)
	ds_write_b128 v243, v[72:75]
	s_waitcnt vmcnt(12)
	ds_write_b128 v244, v[80:83]
	v_mfma_f32_16x16x32_bf16 v[64:67], v[40:43], v[4:7], 0
	v_mfma_f32_16x16x32_bf16 v[40:43], v[40:43], v[12:15], 0
	v_mfma_f32_16x16x32_bf16 v[64:67], v[44:47], v[8:11], v[64:67]
	v_mfma_f32_16x16x32_bf16 v[68:71], v[56:59], v[4:7], 0
	v_mfma_f32_16x16x32_bf16 v[40:43], v[44:47], v[0:3], v[40:43]
	v_mfma_f32_16x16x32_bf16 v[44:47], v[56:59], v[12:15], 0
	v_sub_u32_e32 v56, v187, v147
	v_add_u32_e32 v59, 1, v56
	s_nop 2
	v_cmp_gt_u32_e64 s[0:1], v59, v146
	v_cmp_gt_u32_e32 vcc, v56, v146
	s_nop 0
	v_cndmask_b32_e64 v65, v65, v246, s[0:1]
	s_nop 0
	v_cndmask_b32_e32 v64, v64, v246, vcc
	v_max_f32_e32 v58, 0xf149f2ca, v64
	v_mfma_f32_16x16x32_bf16 v[68:71], v[60:63], v[8:11], v[68:71]
	v_max_f32_e32 v58, v58, v65
	v_add_u32_e32 v59, 2, v56
	v_cmp_gt_u32_e64 s[22:23], v59, v146
	v_mfma_f32_16x16x32_bf16 v[44:47], v[60:63], v[0:3], v[44:47]
	v_add_u32_e32 v60, 3, v56
	v_cmp_gt_u32_e64 s[24:25], v60, v146
	v_cndmask_b32_e64 v66, v66, v246, s[22:23]
	v_sub_u32_e32 v57, v187, v148
	v_cndmask_b32_e64 v67, v67, v246, s[24:25]
	v_max3_f32 v58, v58, v66, v67
	v_add_u32_e32 v59, 16, v56
	v_add_u32_e32 v60, 17, v56
	v_cmp_gt_u32_e64 s[26:27], v59, v146
	v_cmp_gt_u32_e64 s[28:29], v60, v146
	v_cmp_gt_u32_e64 s[38:39], v57, v145
	v_cndmask_b32_e64 v68, v68, v246, s[26:27]
	v_cndmask_b32_e64 v69, v69, v246, s[28:29]
	v_max3_f32 v58, v58, v68, v69
	v_add_u32_e32 v59, 18, v56
	v_add_u32_e32 v56, 19, v56
	v_cmp_gt_u32_e64 s[30:31], v59, v146
	v_cmp_gt_u32_e64 s[34:35], v56, v146
	v_add_u32_e32 v60, 3, v57
	v_cndmask_b32_e64 v70, v70, v246, s[30:31]
	v_cndmask_b32_e64 v71, v71, v246, s[34:35]
	v_max3_f32 v56, v58, v70, v71
	v_add_u32_e32 v59, 1, v57
	v_cmp_gt_u32_e64 s[40:41], v59, v145
	v_cndmask_b32_e64 v40, v40, v246, s[38:39]
	v_max_f32_e32 v58, 0xf149f2ca, v40
	v_cndmask_b32_e64 v41, v41, v246, s[40:41]
	v_max_f32_e32 v58, v58, v41
	v_add_u32_e32 v59, 2, v57
	v_cmp_gt_u32_e64 s[42:43], v59, v145
	v_cmp_gt_u32_e64 s[44:45], v60, v145
	s_nop 0
	v_cndmask_b32_e64 v42, v42, v246, s[42:43]
	v_cndmask_b32_e64 v43, v43, v246, s[44:45]
	v_max3_f32 v58, v58, v42, v43
	v_add_u32_e32 v59, 16, v57
	v_add_u32_e32 v60, 17, v57
	v_cmp_gt_u32_e64 s[46:47], v59, v145
	v_cmp_gt_u32_e64 s[48:49], v60, v145
	s_nop 0
	v_cndmask_b32_e64 v44, v44, v246, s[46:47]
	v_cndmask_b32_e64 v45, v45, v246, s[48:49]
	v_max3_f32 v58, v58, v44, v45
	v_add_u32_e32 v59, 18, v57
	v_add_u32_e32 v57, 19, v57
	v_cmp_gt_u32_e64 s[50:51], v59, v145
	v_cmp_gt_u32_e64 s[52:53], v57, v145
	s_nop 0
	v_cndmask_b32_e64 v46, v46, v246, s[50:51]
	v_cndmask_b32_e64 v47, v47, v246, s[52:53]
	v_max3_f32 v57, v58, v46, v47
	v_mov_b32_e32 v58, v56
	s_nop 1
	v_permlane32_swap_b32_e32 v58, v56
	v_max_f32_e32 v56, v56, v58
	v_mov_b32_e32 v58, v57
	s_nop 1
	v_permlane32_swap_b32_e32 v58, v57
	v_max_f32_e32 v57, v57, v58
	v_mov_b32_e32 v58, v56
	s_nop 1
	v_permlane16_swap_b32_e32 v58, v56
	v_max_f32_e32 v56, v56, v58
	v_mov_b32_e32 v58, v57
	v_mov_b32_e32 v61, v57
	v_max_f32_e32 v128, v129, v56
	s_nop 0
	v_permlane16_swap_b32_e32 v58, v61
	v_sub_f32_e32 v56, v129, v128
	v_exp_f32_e32 v60, v56
	v_sub_f32_e32 v56, v64, v128
	v_max_f32_e32 v62, v57, v58
	v_exp_f32_e32 v56, v56
	v_sub_f32_e32 v58, v65, v128
	v_exp_f32_e32 v58, v58
	v_sub_f32_e32 v59, v66, v128
	v_exp_f32_e32 v59, v59
	v_sub_f32_e32 v63, v67, v128
	v_exp_f32_e32 v63, v63
	v_sub_f32_e32 v64, v68, v128
	v_exp_f32_e32 v64, v64
	v_sub_f32_e32 v65, v69, v128
	v_add_f32_e32 v57, 0, v56
	v_exp_f32_e32 v65, v65
	v_sub_f32_e32 v66, v70, v128
	v_add_f32_e32 v57, v58, v57
	v_exp_f32_e32 v66, v66
	v_sub_f32_e32 v67, v71, v128
	v_add_f32_e32 v57, v59, v57
	v_exp_f32_e32 v67, v67
	v_add_f32_e32 v57, v63, v57
	v_add_f32_e32 v57, v64, v57
	v_add_f32_e32 v57, v65, v57
	v_add_f32_e32 v57, v66, v57
	v_add_f32_e32 v129, v67, v57
	v_fmac_f32_e32 v129, v130, v60
	v_max3_f32 v130, v131, v62, v61
	v_sub_f32_e32 v40, v40, v130
	v_exp_f32_e32 v40, v40
	v_sub_f32_e32 v41, v41, v130
	v_exp_f32_e32 v41, v41
	v_sub_f32_e32 v42, v42, v130
	v_exp_f32_e32 v42, v42
	v_sub_f32_e32 v43, v43, v130
	v_exp_f32_e32 v43, v43
	v_sub_f32_e32 v44, v44, v130
	v_sub_f32_e32 v61, v131, v130
	v_exp_f32_e32 v44, v44
	v_sub_f32_e32 v45, v45, v130
	v_exp_f32_e32 v62, v61
	v_add_f32_e32 v61, 0, v40
	v_exp_f32_e32 v45, v45
	v_sub_f32_e32 v46, v46, v130
	v_add_f32_e32 v61, v41, v61
	v_exp_f32_e32 v46, v46
	v_sub_f32_e32 v47, v47, v130
	v_add_f32_e32 v61, v42, v61
	v_exp_f32_e32 v47, v47
	v_add_f32_e32 v61, v43, v61
	v_add_f32_e32 v61, v44, v61
	v_add_f32_e32 v61, v45, v61
	v_add_f32_e32 v61, v46, v61
	v_cvt_pk_bf16_f32 v56, v56, v58
	v_cvt_pk_bf16_f32 v57, v59, v63
	v_cvt_pk_bf16_f32 v58, v64, v65
	v_cvt_pk_bf16_f32 v59, v66, v67
	v_add_f32_e32 v131, v47, v61
	v_cvt_pk_bf16_f32 v40, v40, v41
	v_cvt_pk_bf16_f32 v41, v42, v43
	v_cvt_pk_bf16_f32 v42, v44, v45
	v_cvt_pk_bf16_f32 v43, v46, v47
	v_pk_mul_f32 v[46:47], v[122:123], v[60:61] op_sel_hi:[1,0]
	v_pk_mul_f32 v[44:45], v[120:121], v[60:61] op_sel_hi:[1,0]
	v_fmac_f32_e32 v131, v132, v62
	s_waitcnt lgkmcnt(10)
	v_mfma_f32_16x16x32_bf16 v[64:67], v[134:137], v[56:59], v[44:47]
	s_nop 2
	v_mul_f32_e64 v46, v126, v62
	v_mul_f32_e64 v47, v127, v62
	v_pk_mul_f32 v[44:45], v[124:125], v[62:63] op_sel_hi:[1,0]
	s_nop 1
	v_mfma_f32_16x16x32_bf16 v[68:71], v[134:137], v[40:43], v[44:47]
	s_nop 2
	v_mul_f32_e64 v46, v106, v60
	v_mul_f32_e64 v47, v107, v60
	v_pk_mul_f32 v[44:45], v[104:105], v[60:61] op_sel_hi:[1,0]
	s_waitcnt lgkmcnt(8)
	s_nop 0
	v_mfma_f32_16x16x32_bf16 v[104:107], v[138:141], v[56:59], v[44:47]
	s_nop 2
	v_mul_f32_e64 v46, v110, v62
	v_mul_f32_e64 v47, v111, v62
	v_pk_mul_f32 v[44:45], v[108:109], v[62:63] op_sel_hi:[1,0]
	s_nop 1
	v_mfma_f32_16x16x32_bf16 v[108:111], v[138:141], v[40:43], v[44:47]
	s_nop 2
	v_mul_f32_e64 v46, v114, v60
	v_mul_f32_e64 v47, v115, v60
	v_pk_mul_f32 v[44:45], v[112:113], v[60:61] op_sel_hi:[1,0]
	s_waitcnt lgkmcnt(6)
	s_nop 0
	v_mfma_f32_16x16x32_bf16 v[112:115], v[176:179], v[56:59], v[44:47]
	s_nop 2
	v_mul_f32_e64 v46, v118, v62
	v_mul_f32_e64 v47, v119, v62
	v_pk_mul_f32 v[44:45], v[116:117], v[62:63] op_sel_hi:[1,0]
	s_nop 1
	v_mfma_f32_16x16x32_bf16 v[116:119], v[176:179], v[40:43], v[44:47]
	s_nop 2
	v_mul_f32_e64 v46, v98, v60
	v_mul_f32_e64 v47, v99, v60
	v_pk_mul_f32 v[44:45], v[96:97], v[60:61] op_sel_hi:[1,0]
	s_waitcnt lgkmcnt(4)
	s_nop 0
	v_mfma_f32_16x16x32_bf16 v[120:123], v[188:191], v[56:59], v[44:47]
	v_or_b32_e32 v56, 0x50, v166
	v_add_u32_e32 v56, s76, v56
	s_nop 0
	v_pk_mul_f32 v[46:47], v[90:91], v[62:63] op_sel_hi:[1,0]
	v_pk_mul_f32 v[44:45], v[88:89], v[62:63] op_sel_hi:[1,0]
	s_nop 1
	v_mfma_f32_16x16x32_bf16 v[124:127], v[188:191], v[40:43], v[44:47]
	v_add_u32_e32 v40, 64, v155
	v_add_u32_e32 v40, s76, v40
	v_med3_i32 v40, v40, 0, s75
	v_lshl_add_u32 v40, v40, 9, v152
	global_load_dwordx4 v[72:75], v40, s[98:99]
	v_add_u32_e32 v40, 64, v172
	v_add_u32_e32 v40, s76, v40
	v_med3_i32 v40, v40, 0, s75
	v_lshl_add_u32 v40, v40, 9, v152
	global_load_dwordx4 v[80:83], v40, s[98:99]
	v_add_u32_e32 v40, 64, v173
	v_add_u32_e32 v40, s76, v40
	v_med3_i32 v40, v40, 0, s75
	v_lshl_add_u32 v40, v40, 9, v152
	global_load_dwordx4 v[88:91], v40, s[98:99]
	v_add_u32_e32 v40, 64, v182
	v_add_u32_e32 v40, s76, v40
	v_med3_i32 v40, v40, 0, s75
	v_lshl_add_u32 v40, v40, 9, v152
	global_load_dwordx4 v[96:99], v40, s[98:99]
	v_or_b32_e32 v40, 64, v166
	v_add_u32_e32 v40, s76, v40
	v_med3_i32 v40, v40, 0, s75
	v_med3_i32 v56, v56, 0, s75
	v_lshl_add_u32 v44, v40, 9, v158
	v_lshl_add_u32 v60, v56, 9, v158
	global_load_dwordx4 v[40:43], v44, s[100:101]
	s_nop 0
	global_load_dwordx4 v[44:47], v44, s[100:101] offset:64
	s_nop 0
	global_load_dwordx4 v[56:59], v60, s[100:101]
	s_nop 0
	global_load_dwordx4 v[60:63], v60, s[100:101] offset:64
	ds_read_b64_tr_b16 v[136:137], v169 offset:2304
	ds_read_b64_tr_b16 v[134:135], v169
	ds_read_b64_tr_b16 v[138:139], v169 offset:32
	ds_read_b64_tr_b16 v[140:141], v169 offset:2336
	ds_read_b64_tr_b16 v[176:177], v169 offset:64
	ds_read_b64_tr_b16 v[178:179], v169 offset:2368
	ds_read_b64_tr_b16 v[188:189], v169 offset:96
	ds_read_b64_tr_b16 v[190:191], v169 offset:2400
	s_waitcnt vmcnt(15)
	ds_write_b128 v241, v[76:79] offset:4608
	s_waitcnt vmcnt(14)
	ds_write_b128 v242, v[84:87] offset:4608
	s_waitcnt vmcnt(13)
	ds_write_b128 v243, v[92:95] offset:4608
	s_waitcnt vmcnt(12)
	ds_write_b128 v244, v[100:103] offset:4608
	v_mfma_f32_16x16x32_bf16 v[76:79], v[16:19], v[4:7], 0
	v_mfma_f32_16x16x32_bf16 v[16:19], v[16:19], v[12:15], 0
	v_mfma_f32_16x16x32_bf16 v[76:79], v[20:23], v[8:11], v[76:79]
	v_mfma_f32_16x16x32_bf16 v[84:87], v[24:27], v[4:7], 0
	v_mfma_f32_16x16x32_bf16 v[16:19], v[20:23], v[0:3], v[16:19]
	v_mfma_f32_16x16x32_bf16 v[20:23], v[24:27], v[12:15], 0
	v_sub_u32_e32 v24, v192, v147
	v_add_u32_e32 v27, 1, v24
	s_nop 2
	v_cmp_gt_u32_e64 s[0:1], v27, v146
	v_cmp_gt_u32_e32 vcc, v24, v146
	s_nop 0
	v_cndmask_b32_e64 v77, v77, v246, s[0:1]
	s_nop 0
	v_cndmask_b32_e32 v76, v76, v246, vcc
	v_max_f32_e32 v26, 0xf149f2ca, v76
	v_mfma_f32_16x16x32_bf16 v[84:87], v[28:31], v[8:11], v[84:87]
	v_max_f32_e32 v26, v26, v77
	v_add_u32_e32 v27, 2, v24
	v_cmp_gt_u32_e64 s[22:23], v27, v146
	v_mfma_f32_16x16x32_bf16 v[20:23], v[28:31], v[0:3], v[20:23]
	v_add_u32_e32 v28, 3, v24
	v_cmp_gt_u32_e64 s[24:25], v28, v146
	v_cndmask_b32_e64 v78, v78, v246, s[22:23]
	v_sub_u32_e32 v25, v192, v148
	v_cndmask_b32_e64 v79, v79, v246, s[24:25]
	v_max3_f32 v26, v26, v78, v79
	v_add_u32_e32 v27, 16, v24
	v_add_u32_e32 v28, 17, v24
	v_cmp_gt_u32_e64 s[26:27], v27, v146
	v_cmp_gt_u32_e64 s[28:29], v28, v146
	v_cmp_gt_u32_e64 s[38:39], v25, v145
	v_cndmask_b32_e64 v84, v84, v246, s[26:27]
	v_cndmask_b32_e64 v85, v85, v246, s[28:29]
	v_max3_f32 v26, v26, v84, v85
	v_add_u32_e32 v27, 18, v24
	v_add_u32_e32 v24, 19, v24
	v_cmp_gt_u32_e64 s[30:31], v27, v146
	v_cmp_gt_u32_e64 s[34:35], v24, v146
	v_add_u32_e32 v28, 3, v25
	v_cndmask_b32_e64 v86, v86, v246, s[30:31]
	v_cndmask_b32_e64 v87, v87, v246, s[34:35]
	v_max3_f32 v24, v26, v86, v87
	v_add_u32_e32 v27, 1, v25
	v_cmp_gt_u32_e64 s[40:41], v27, v145
	v_cndmask_b32_e64 v16, v16, v246, s[38:39]
	v_max_f32_e32 v26, 0xf149f2ca, v16
	v_cndmask_b32_e64 v17, v17, v246, s[40:41]
	v_max_f32_e32 v26, v26, v17
	v_add_u32_e32 v27, 2, v25
	v_cmp_gt_u32_e64 s[42:43], v27, v145
	v_cmp_gt_u32_e64 s[44:45], v28, v145
	s_nop 0
	v_cndmask_b32_e64 v18, v18, v246, s[42:43]
	v_cndmask_b32_e64 v19, v19, v246, s[44:45]
	v_max3_f32 v26, v26, v18, v19
	v_add_u32_e32 v27, 16, v25
	v_add_u32_e32 v28, 17, v25
	v_cmp_gt_u32_e64 s[46:47], v27, v145
	v_cmp_gt_u32_e64 s[48:49], v28, v145
	s_nop 0
	v_cndmask_b32_e64 v20, v20, v246, s[46:47]
	v_cndmask_b32_e64 v21, v21, v246, s[48:49]
	v_max3_f32 v26, v26, v20, v21
	v_add_u32_e32 v27, 18, v25
	v_add_u32_e32 v25, 19, v25
	v_cmp_gt_u32_e64 s[50:51], v27, v145
	v_cmp_gt_u32_e64 s[52:53], v25, v145
	s_nop 0
	v_cndmask_b32_e64 v22, v22, v246, s[50:51]
	v_cndmask_b32_e64 v23, v23, v246, s[52:53]
	v_max3_f32 v25, v26, v22, v23
	v_mov_b32_e32 v26, v24
	s_nop 1
	v_permlane32_swap_b32_e32 v26, v24
	v_max_f32_e32 v24, v24, v26
	v_mov_b32_e32 v26, v25
	s_nop 1
	v_permlane32_swap_b32_e32 v26, v25
	v_max_f32_e32 v25, v25, v26
	v_mov_b32_e32 v26, v24
	s_nop 1
	v_permlane16_swap_b32_e32 v26, v24
	v_max_f32_e32 v24, v24, v26
	v_mov_b32_e32 v26, v25
	v_mov_b32_e32 v28, v25
	v_max_f32_e32 v132, v128, v24
	s_nop 0
	v_permlane16_swap_b32_e32 v26, v28
	v_sub_f32_e32 v24, v128, v132
	v_exp_f32_e32 v92, v24
	v_sub_f32_e32 v24, v76, v132
	v_max_f32_e32 v29, v25, v26
	v_exp_f32_e32 v24, v24
	v_sub_f32_e32 v26, v77, v132
	v_exp_f32_e32 v26, v26
	v_sub_f32_e32 v27, v78, v132
	v_exp_f32_e32 v27, v27
	v_sub_f32_e32 v30, v79, v132
	v_exp_f32_e32 v30, v30
	v_sub_f32_e32 v31, v84, v132
	v_exp_f32_e32 v31, v31
	v_sub_f32_e32 v76, v85, v132
	v_add_f32_e32 v25, 0, v24
	v_exp_f32_e32 v76, v76
	v_sub_f32_e32 v77, v86, v132
	v_add_f32_e32 v25, v26, v25
	v_exp_f32_e32 v77, v77
	v_sub_f32_e32 v78, v87, v132
	v_add_f32_e32 v25, v27, v25
	v_exp_f32_e32 v78, v78
	v_add_f32_e32 v25, v30, v25
	v_add_f32_e32 v25, v31, v25
	v_add_f32_e32 v25, v76, v25
	v_add_f32_e32 v25, v77, v25
	v_add_f32_e32 v128, v78, v25
	v_fmac_f32_e32 v128, v129, v92
	v_max3_f32 v129, v130, v29, v28
	v_sub_f32_e32 v16, v16, v129
	v_exp_f32_e32 v16, v16
	v_sub_f32_e32 v17, v17, v129
	v_exp_f32_e32 v17, v17
	v_sub_f32_e32 v18, v18, v129
	v_exp_f32_e32 v18, v18
	v_sub_f32_e32 v19, v19, v129
	v_exp_f32_e32 v19, v19
	v_sub_f32_e32 v20, v20, v129
	v_sub_f32_e32 v28, v130, v129
	v_exp_f32_e32 v20, v20
	v_sub_f32_e32 v21, v21, v129
	v_cvt_pk_bf16_f32 v24, v24, v26
	v_cvt_pk_bf16_f32 v26, v31, v76
	v_exp_f32_e32 v76, v28
	v_add_f32_e32 v28, 0, v16
	v_exp_f32_e32 v21, v21
	v_sub_f32_e32 v22, v22, v129
	v_add_f32_e32 v28, v17, v28
	v_exp_f32_e32 v22, v22
	v_sub_f32_e32 v23, v23, v129
	v_add_f32_e32 v28, v18, v28
	v_exp_f32_e32 v23, v23
	v_add_f32_e32 v28, v19, v28
	v_add_f32_e32 v28, v20, v28
	v_add_f32_e32 v28, v21, v28
	v_add_f32_e32 v28, v22, v28
	v_cvt_pk_bf16_f32 v25, v27, v30
	v_cvt_pk_bf16_f32 v27, v77, v78
	v_add_f32_e32 v130, v23, v28
	v_cvt_pk_bf16_f32 v28, v16, v17
	v_cvt_pk_bf16_f32 v29, v18, v19
	v_pk_mul_f32 v[18:19], v[66:67], v[92:93] op_sel_hi:[1,0]
	v_pk_mul_f32 v[16:17], v[64:65], v[92:93] op_sel_hi:[1,0]
	v_pk_mul_f32 v[66:67], v[106:107], v[92:93] op_sel_hi:[1,0]
	v_pk_mul_f32 v[64:65], v[104:105], v[92:93] op_sel_hi:[1,0]
	v_cvt_pk_bf16_f32 v30, v20, v21
	v_cvt_pk_bf16_f32 v31, v22, v23
	s_waitcnt lgkmcnt(8)
	v_mfma_f32_16x16x32_bf16 v[104:107], v[138:141], v[24:27], v[64:67]
	v_fmac_f32_e32 v130, v131, v76
	v_pk_mul_f32 v[22:23], v[70:71], v[76:77] op_sel_hi:[1,0]
	v_pk_mul_f32 v[20:21], v[68:69], v[76:77] op_sel_hi:[1,0]
	v_pk_mul_f32 v[66:67], v[110:111], v[76:77] op_sel_hi:[1,0]
	v_pk_mul_f32 v[64:65], v[108:109], v[76:77] op_sel_hi:[1,0]
	v_mfma_f32_16x16x32_bf16 v[16:19], v[134:137], v[24:27], v[16:19]
	s_nop 0
	v_mfma_f32_16x16x32_bf16 v[108:111], v[138:141], v[28:31], v[64:67]
	s_nop 2
	v_mul_f32_e64 v66, v114, v92
	v_mul_f32_e64 v67, v115, v92
	v_pk_mul_f32 v[64:65], v[112:113], v[92:93] op_sel_hi:[1,0]
	v_mfma_f32_16x16x32_bf16 v[20:23], v[134:137], v[28:31], v[20:23]
	s_waitcnt lgkmcnt(6)
	v_mfma_f32_16x16x32_bf16 v[112:115], v[176:179], v[24:27], v[64:67]
	s_nop 2
	v_mul_f32_e64 v66, v118, v76
	v_mul_f32_e64 v67, v119, v76
	v_pk_mul_f32 v[64:65], v[116:117], v[76:77] op_sel_hi:[1,0]
	s_nop 1
	v_mfma_f32_16x16x32_bf16 v[116:119], v[176:179], v[28:31], v[64:67]
	s_nop 2
	v_mul_f32_e64 v66, v122, v92
	v_mul_f32_e64 v67, v123, v92
	v_pk_mul_f32 v[64:65], v[120:121], v[92:93] op_sel_hi:[1,0]
	s_waitcnt lgkmcnt(4)
	s_nop 0
	v_mfma_f32_16x16x32_bf16 v[120:123], v[188:191], v[24:27], v[64:67]
	v_mul_f32_e64 v26, v126, v76
	v_mul_f32_e64 v27, v127, v76
	v_pk_mul_f32 v[24:25], v[124:125], v[76:77] op_sel_hi:[1,0]
	v_or_b32_e32 v64, 0x70, v166
	s_nop 0
	v_mfma_f32_16x16x32_bf16 v[124:127], v[188:191], v[28:31], v[24:27]
	v_add_u32_e32 v64, s76, v64
	s_nop 0
	s_nop 0
	v_add_u32_e32 v24, s76, v196
	v_med3_i32 v24, v24, 0, s75
	v_lshl_add_u32 v24, v24, 9, v152
	global_load_dwordx4 v[76:79], v24, s[98:99]
	v_add_u32_e32 v24, s76, v168
	v_med3_i32 v24, v24, 0, s75
	v_lshl_add_u32 v24, v24, 9, v152
	global_load_dwordx4 v[84:87], v24, s[98:99]
	v_add_u32_e32 v24, s76, v193
	v_med3_i32 v24, v24, 0, s75
	v_lshl_add_u32 v24, v24, 9, v152
	global_load_dwordx4 v[92:95], v24, s[98:99]
	v_add_u32_e32 v24, s76, v194
	v_med3_i32 v24, v24, 0, s75
	v_lshl_add_u32 v24, v24, 9, v152
	global_load_dwordx4 v[100:103], v24, s[98:99]
	v_or_b32_e32 v24, 0x60, v166
	v_add_u32_e32 v24, s76, v24
	v_med3_i32 v24, v24, 0, s75
	v_med3_i32 v64, v64, 0, s75
	v_lshl_add_u32 v28, v24, 9, v158
	v_lshl_add_u32 v68, v64, 9, v158
	global_load_dwordx4 v[24:27], v28, s[100:101]
	s_nop 0
	global_load_dwordx4 v[28:31], v28, s[100:101] offset:64
	s_nop 0
	global_load_dwordx4 v[64:67], v68, s[100:101]
	s_nop 0
	global_load_dwordx4 v[68:71], v68, s[100:101] offset:64
	ds_read_b64_tr_b16 v[136:137], v169 offset:6912
	ds_read_b64_tr_b16 v[134:135], v169 offset:4608
	ds_read_b64_tr_b16 v[138:139], v169 offset:4640
	ds_read_b64_tr_b16 v[140:141], v169 offset:6944
	ds_read_b64_tr_b16 v[176:177], v169 offset:4672
	ds_read_b64_tr_b16 v[178:179], v169 offset:6976
	ds_read_b64_tr_b16 v[188:189], v169 offset:4704
	ds_read_b64_tr_b16 v[190:191], v169 offset:7008
	s_waitcnt vmcnt(15)
	ds_write_b128 v241, v[72:75]
	s_waitcnt vmcnt(14)
	ds_write_b128 v242, v[80:83]
	s_waitcnt vmcnt(13)
	ds_write_b128 v243, v[88:91]
	s_waitcnt vmcnt(12)
	ds_write_b128 v244, v[96:99]
	v_mfma_f32_16x16x32_bf16 v[72:75], v[32:35], v[4:7], 0
	v_mfma_f32_16x16x32_bf16 v[32:35], v[32:35], v[12:15], 0
	v_mfma_f32_16x16x32_bf16 v[72:75], v[36:39], v[8:11], v[72:75]
	v_mfma_f32_16x16x32_bf16 v[80:83], v[48:51], v[4:7], 0
	v_mfma_f32_16x16x32_bf16 v[32:35], v[36:39], v[0:3], v[32:35]
	v_mfma_f32_16x16x32_bf16 v[36:39], v[48:51], v[12:15], 0
	v_sub_u32_e32 v48, v197, v147
	v_add_u32_e32 v51, 1, v48
	s_nop 2
	v_cmp_gt_u32_e64 s[0:1], v51, v146
	v_cmp_gt_u32_e32 vcc, v48, v146
	s_nop 0
	v_cndmask_b32_e64 v73, v73, v246, s[0:1]
	s_nop 0
	v_cndmask_b32_e32 v72, v72, v246, vcc
	v_max_f32_e32 v50, 0xf149f2ca, v72
	v_mfma_f32_16x16x32_bf16 v[80:83], v[52:55], v[8:11], v[80:83]
	v_max_f32_e32 v50, v50, v73
	v_add_u32_e32 v51, 2, v48
	v_cmp_gt_u32_e64 s[22:23], v51, v146
	v_mfma_f32_16x16x32_bf16 v[36:39], v[52:55], v[0:3], v[36:39]
	v_add_u32_e32 v52, 3, v48
	v_cmp_gt_u32_e64 s[24:25], v52, v146
	v_cndmask_b32_e64 v74, v74, v246, s[22:23]
	v_sub_u32_e32 v49, v197, v148
	v_cndmask_b32_e64 v75, v75, v246, s[24:25]
	v_max3_f32 v50, v50, v74, v75
	v_add_u32_e32 v51, 16, v48
	v_add_u32_e32 v52, 17, v48
	v_cmp_gt_u32_e64 s[26:27], v51, v146
	v_cmp_gt_u32_e64 s[28:29], v52, v146
	v_cmp_gt_u32_e64 s[38:39], v49, v145
	v_cndmask_b32_e64 v80, v80, v246, s[26:27]
	v_cndmask_b32_e64 v81, v81, v246, s[28:29]
	v_max3_f32 v50, v50, v80, v81
	v_add_u32_e32 v51, 18, v48
	v_add_u32_e32 v48, 19, v48
	v_cmp_gt_u32_e64 s[30:31], v51, v146
	v_cmp_gt_u32_e64 s[34:35], v48, v146
	v_add_u32_e32 v52, 3, v49
	v_cndmask_b32_e64 v82, v82, v246, s[30:31]
	v_cndmask_b32_e64 v83, v83, v246, s[34:35]
	v_max3_f32 v48, v50, v82, v83
	v_add_u32_e32 v51, 1, v49
	v_cmp_gt_u32_e64 s[40:41], v51, v145
	v_cndmask_b32_e64 v32, v32, v246, s[38:39]
	v_max_f32_e32 v50, 0xf149f2ca, v32
	v_cndmask_b32_e64 v33, v33, v246, s[40:41]
	v_max_f32_e32 v50, v50, v33
	v_add_u32_e32 v51, 2, v49
	v_cmp_gt_u32_e64 s[42:43], v51, v145
	v_cmp_gt_u32_e64 s[44:45], v52, v145
	s_nop 0
	v_cndmask_b32_e64 v34, v34, v246, s[42:43]
	v_cndmask_b32_e64 v35, v35, v246, s[44:45]
	v_max3_f32 v50, v50, v34, v35
	v_add_u32_e32 v51, 16, v49
	v_add_u32_e32 v52, 17, v49
	v_cmp_gt_u32_e64 s[46:47], v51, v145
	v_cmp_gt_u32_e64 s[48:49], v52, v145
	s_nop 0
	v_cndmask_b32_e64 v36, v36, v246, s[46:47]
	v_cndmask_b32_e64 v37, v37, v246, s[48:49]
	v_max3_f32 v50, v50, v36, v37
	v_add_u32_e32 v51, 18, v49
	v_add_u32_e32 v49, 19, v49
	v_cmp_gt_u32_e64 s[50:51], v51, v145
	v_cmp_gt_u32_e64 s[52:53], v49, v145
	s_nop 0
	v_cndmask_b32_e64 v38, v38, v246, s[50:51]
	v_cndmask_b32_e64 v39, v39, v246, s[52:53]
	v_max3_f32 v49, v50, v38, v39
	v_mov_b32_e32 v50, v48
	s_nop 1
	v_permlane32_swap_b32_e32 v50, v48
	v_max_f32_e32 v48, v48, v50
	v_mov_b32_e32 v50, v49
	s_nop 1
	v_permlane32_swap_b32_e32 v50, v49
	v_max_f32_e32 v49, v49, v50
	v_mov_b32_e32 v50, v48
	s_nop 1
	v_permlane16_swap_b32_e32 v50, v48
	v_max_f32_e32 v48, v48, v50
	v_mov_b32_e32 v50, v49
	v_mov_b32_e32 v53, v49
	v_max_f32_e32 v131, v132, v48
	s_nop 0
	v_permlane16_swap_b32_e32 v50, v53
	v_sub_f32_e32 v48, v132, v131
	v_exp_f32_e32 v52, v48
	v_sub_f32_e32 v48, v72, v131
	v_max_f32_e32 v54, v49, v50
	v_exp_f32_e32 v48, v48
	v_sub_f32_e32 v50, v73, v131
	v_exp_f32_e32 v50, v50
	v_sub_f32_e32 v51, v74, v131
	v_exp_f32_e32 v51, v51
	v_sub_f32_e32 v55, v75, v131
	v_exp_f32_e32 v55, v55
	v_sub_f32_e32 v72, v80, v131
	v_exp_f32_e32 v72, v72
	v_sub_f32_e32 v73, v81, v131
	v_add_f32_e32 v49, 0, v48
	v_exp_f32_e32 v73, v73
	v_sub_f32_e32 v74, v82, v131
	v_add_f32_e32 v49, v50, v49
	v_exp_f32_e32 v74, v74
	v_sub_f32_e32 v75, v83, v131
	v_add_f32_e32 v49, v51, v49
	v_exp_f32_e32 v75, v75
	v_add_f32_e32 v49, v55, v49
	v_add_f32_e32 v49, v72, v49
	v_add_f32_e32 v49, v73, v49
	v_add_f32_e32 v49, v74, v49
	v_add_f32_e32 v132, v75, v49
	v_fmac_f32_e32 v132, v128, v52
	v_max3_f32 v128, v129, v54, v53
	v_sub_f32_e32 v32, v32, v128
	v_exp_f32_e32 v32, v32
	v_sub_f32_e32 v33, v33, v128
	v_exp_f32_e32 v33, v33
	v_sub_f32_e32 v34, v34, v128
	v_exp_f32_e32 v34, v34
	v_sub_f32_e32 v35, v35, v128
	v_exp_f32_e32 v35, v35
	v_sub_f32_e32 v36, v36, v128
	v_sub_f32_e32 v53, v129, v128
	v_exp_f32_e32 v36, v36
	v_sub_f32_e32 v37, v37, v128
	v_exp_f32_e32 v54, v53
	v_add_f32_e32 v53, 0, v32
	v_exp_f32_e32 v37, v37
	v_add_f32_e32 v53, v33, v53
	v_add_f32_e32 v53, v34, v53
	v_cvt_pk_bf16_f32 v49, v51, v55
	v_add_f32_e32 v53, v35, v53
	v_cndmask_b32_e64 v55, v36, 0, s[46:47]
	v_add_f32_e32 v36, v55, v53
	v_cndmask_b32_e64 v53, v37, 0, s[48:49]
	v_sub_f32_e32 v37, v38, v128
	v_exp_f32_e32 v37, v37
	v_cvt_pk_bf16_f32 v48, v48, v50
	v_cvt_pk_bf16_f32 v50, v72, v73
	v_add_f32_e32 v36, v53, v36
	v_cndmask_b32_e64 v72, v37, 0, s[50:51]
	v_sub_f32_e32 v37, v39, v128
	v_exp_f32_e32 v37, v37
	v_cvt_pk_bf16_f32 v51, v74, v75
	v_add_f32_e32 v36, v72, v36
	v_pk_mul_f32 v[18:19], v[18:19], v[52:53] op_sel_hi:[1,0]
	v_cndmask_b32_e64 v39, v37, 0, s[52:53]
	v_pk_mul_f32 v[16:17], v[16:17], v[52:53] op_sel_hi:[1,0]
	v_add_f32_e32 v129, v39, v36
	v_cvt_pk_bf16_f32 v36, v32, v33
	v_cvt_pk_bf16_f32 v37, v34, v35
	v_cvt_pk_bf16_f32 v38, v55, v53
	v_cvt_pk_bf16_f32 v39, v72, v39
	s_waitcnt lgkmcnt(10)
	v_mfma_f32_16x16x32_bf16 v[32:35], v[134:137], v[48:51], v[16:19]
	v_fmac_f32_e32 v129, v130, v54
	s_nop 1
	v_pk_mul_f32 v[18:19], v[22:23], v[54:55] op_sel_hi:[1,0]
	v_pk_mul_f32 v[16:17], v[20:21], v[54:55] op_sel_hi:[1,0]
	s_nop 1
	v_mfma_f32_16x16x32_bf16 v[96:99], v[134:137], v[36:39], v[16:19]
	s_nop 2
	v_mul_f32_e64 v18, v106, v52
	v_mul_f32_e64 v19, v107, v52
	v_pk_mul_f32 v[16:17], v[104:105], v[52:53] op_sel_hi:[1,0]
	s_waitcnt lgkmcnt(8)
	s_nop 0
	v_mfma_f32_16x16x32_bf16 v[104:107], v[138:141], v[48:51], v[16:19]
	s_nop 2
	v_mul_f32_e64 v18, v110, v54
	v_mul_f32_e64 v19, v111, v54
	v_pk_mul_f32 v[16:17], v[108:109], v[54:55] op_sel_hi:[1,0]
	s_nop 1
	v_mfma_f32_16x16x32_bf16 v[108:111], v[138:141], v[36:39], v[16:19]
	s_nop 2
	v_mul_f32_e64 v18, v114, v52
	v_mul_f32_e64 v19, v115, v52
	v_pk_mul_f32 v[16:17], v[112:113], v[52:53] op_sel_hi:[1,0]
	s_waitcnt lgkmcnt(6)
	s_nop 0
	v_mfma_f32_16x16x32_bf16 v[112:115], v[176:179], v[48:51], v[16:19]
	s_nop 2
	v_mul_f32_e64 v18, v118, v54
	v_mul_f32_e64 v19, v119, v54
	v_pk_mul_f32 v[16:17], v[116:117], v[54:55] op_sel_hi:[1,0]
	s_nop 1
	v_mfma_f32_16x16x32_bf16 v[116:119], v[176:179], v[36:39], v[16:19]
	s_nop 2
	v_mul_f32_e64 v18, v122, v52
	v_mul_f32_e64 v19, v123, v52
	v_pk_mul_f32 v[16:17], v[120:121], v[52:53] op_sel_hi:[1,0]
	s_waitcnt lgkmcnt(4)
	s_nop 0
	v_mfma_f32_16x16x32_bf16 v[120:123], v[188:191], v[48:51], v[16:19]
	v_or_b32_e32 v48, 0x90, v166
	v_add_u32_e32 v48, s76, v48
	s_nop 0
	v_pk_mul_f32 v[18:19], v[126:127], v[54:55] op_sel_hi:[1,0]
	v_pk_mul_f32 v[16:17], v[124:125], v[54:55] op_sel_hi:[1,0]
	s_nop 1
	v_mfma_f32_16x16x32_bf16 v[124:127], v[188:191], v[36:39], v[16:19]
	s_nop 2
	v_add_u32_e32 v16, 0x80, v149
	v_med3_i32 v16, v16, 0, s75
	v_lshl_add_u32 v16, v16, 9, v152
	global_load_dwordx4 v[36:39], v16, s[98:99]
	v_add_u32_e32 v16, 0x80, v150
	v_med3_i32 v16, v16, 0, s75
	v_lshl_add_u32 v16, v16, 9, v152
	global_load_dwordx4 v[72:75], v16, s[98:99]
	v_add_u32_e32 v16, 0x80, v151
	v_med3_i32 v16, v16, 0, s75
	v_lshl_add_u32 v16, v16, 9, v152
	global_load_dwordx4 v[80:83], v16, s[98:99]
	v_add_u32_e32 v16, 0x80, v252
	v_med3_i32 v16, v16, 0, s75
	v_lshl_add_u32 v16, v16, 9, v152
	global_load_dwordx4 v[88:91], v16, s[98:99]
	v_or_b32_e32 v16, 0x80, v166
	v_add_u32_e32 v16, s76, v16
	v_med3_i32 v16, v16, 0, s75
	v_med3_i32 v48, v48, 0, s75
	v_lshl_add_u32 v20, v16, 9, v158
	v_lshl_add_u32 v52, v48, 9, v158
	global_load_dwordx4 v[16:19], v20, s[100:101]
	s_nop 0
	global_load_dwordx4 v[20:23], v20, s[100:101] offset:64
	s_nop 0
	global_load_dwordx4 v[48:51], v52, s[100:101]
	s_nop 0
	global_load_dwordx4 v[52:55], v52, s[100:101] offset:64
	ds_read_b64_tr_b16 v[136:137], v169 offset:2304
	ds_read_b64_tr_b16 v[134:135], v169
	ds_read_b64_tr_b16 v[138:139], v169 offset:32
	ds_read_b64_tr_b16 v[140:141], v169 offset:2336
	ds_read_b64_tr_b16 v[188:189], v169 offset:64
	ds_read_b64_tr_b16 v[190:191], v169 offset:2368
	ds_read_b64_tr_b16 v[200:201], v169 offset:96
	ds_read_b64_tr_b16 v[202:203], v169 offset:2400
	s_waitcnt vmcnt(15)
	ds_write_b128 v241, v[76:79] offset:4608
	s_waitcnt vmcnt(14)
	ds_write_b128 v242, v[84:87] offset:4608
	s_waitcnt vmcnt(13)
	ds_write_b128 v243, v[92:95] offset:4608
	s_waitcnt vmcnt(12)
	ds_write_b128 v244, v[100:103] offset:4608
	v_mfma_f32_16x16x32_bf16 v[76:79], v[40:43], v[4:7], 0
	v_mfma_f32_16x16x32_bf16 v[40:43], v[40:43], v[12:15], 0
	v_mfma_f32_16x16x32_bf16 v[76:79], v[44:47], v[8:11], v[76:79]
	v_mfma_f32_16x16x32_bf16 v[84:87], v[56:59], v[4:7], 0
	v_mfma_f32_16x16x32_bf16 v[40:43], v[44:47], v[0:3], v[40:43]
	v_mfma_f32_16x16x32_bf16 v[44:47], v[56:59], v[12:15], 0
	v_sub_u32_e32 v56, v198, v147
	v_add_u32_e32 v59, 1, v56
	s_nop 2
	v_cmp_gt_u32_e64 s[0:1], v59, v146
	v_cmp_gt_u32_e32 vcc, v56, v146
	s_nop 0
	v_cndmask_b32_e64 v77, v77, v246, s[0:1]
	s_nop 0
	v_cndmask_b32_e32 v76, v76, v246, vcc
	v_max_f32_e32 v58, 0xf149f2ca, v76
	v_mfma_f32_16x16x32_bf16 v[84:87], v[60:63], v[8:11], v[84:87]
	v_max_f32_e32 v58, v58, v77
	v_add_u32_e32 v59, 2, v56
	v_cmp_gt_u32_e64 s[22:23], v59, v146
	v_mfma_f32_16x16x32_bf16 v[44:47], v[60:63], v[0:3], v[44:47]
	v_add_u32_e32 v60, 3, v56
	v_cmp_gt_u32_e64 s[24:25], v60, v146
	v_cndmask_b32_e64 v78, v78, v246, s[22:23]
	v_sub_u32_e32 v57, v198, v148
	v_cndmask_b32_e64 v79, v79, v246, s[24:25]
	v_max3_f32 v58, v58, v78, v79
	v_add_u32_e32 v59, 16, v56
	v_add_u32_e32 v60, 17, v56
	v_cmp_gt_u32_e64 s[26:27], v59, v146
	v_cmp_gt_u32_e64 s[28:29], v60, v146
	v_cmp_gt_u32_e64 s[38:39], v57, v145
	v_cndmask_b32_e64 v84, v84, v246, s[26:27]
	v_cndmask_b32_e64 v85, v85, v246, s[28:29]
	v_max3_f32 v58, v58, v84, v85
	v_add_u32_e32 v59, 18, v56
	v_add_u32_e32 v56, 19, v56
	v_cmp_gt_u32_e64 s[30:31], v59, v146
	v_cmp_gt_u32_e64 s[34:35], v56, v146
	v_add_u32_e32 v60, 3, v57
	v_cndmask_b32_e64 v86, v86, v246, s[30:31]
	v_cndmask_b32_e64 v87, v87, v246, s[34:35]
	v_max3_f32 v56, v58, v86, v87
	v_add_u32_e32 v59, 1, v57
	v_cmp_gt_u32_e64 s[40:41], v59, v145
	v_cndmask_b32_e64 v40, v40, v246, s[38:39]
	v_max_f32_e32 v58, 0xf149f2ca, v40
	v_cndmask_b32_e64 v41, v41, v246, s[40:41]
	v_max_f32_e32 v58, v58, v41
	v_add_u32_e32 v59, 2, v57
	v_cmp_gt_u32_e64 s[42:43], v59, v145
	v_cmp_gt_u32_e64 s[44:45], v60, v145
	s_nop 0
	v_cndmask_b32_e64 v42, v42, v246, s[42:43]
	v_cndmask_b32_e64 v43, v43, v246, s[44:45]
	v_max3_f32 v58, v58, v42, v43
	v_add_u32_e32 v59, 16, v57
	v_add_u32_e32 v60, 17, v57
	v_cmp_gt_u32_e64 s[46:47], v59, v145
	v_cmp_gt_u32_e64 s[48:49], v60, v145
	s_nop 0
	v_cndmask_b32_e64 v44, v44, v246, s[46:47]
	v_cndmask_b32_e64 v45, v45, v246, s[48:49]
	v_max3_f32 v58, v58, v44, v45
	v_add_u32_e32 v59, 18, v57
	v_add_u32_e32 v57, 19, v57
	v_cmp_gt_u32_e64 s[50:51], v59, v145
	v_cmp_gt_u32_e64 s[52:53], v57, v145
	s_nop 0
	v_cndmask_b32_e64 v46, v46, v246, s[50:51]
	v_cndmask_b32_e64 v47, v47, v246, s[52:53]
	v_max3_f32 v57, v58, v46, v47
	v_mov_b32_e32 v58, v56
	s_nop 1
	v_permlane32_swap_b32_e32 v58, v56
	v_max_f32_e32 v56, v56, v58
	v_mov_b32_e32 v58, v57
	s_nop 1
	v_permlane32_swap_b32_e32 v58, v57
	v_max_f32_e32 v57, v57, v58
	v_mov_b32_e32 v58, v56
	s_nop 1
	v_permlane16_swap_b32_e32 v58, v56
	v_max_f32_e32 v56, v56, v58
	v_mov_b32_e32 v58, v57
	s_nop 1
	v_permlane16_swap_b32_e32 v58, v57
	v_max_f32_e32 v175, v131, v56
	v_sub_f32_e32 v56, v131, v175
	v_max3_f32 v177, v128, v57, v58
	v_exp_f32_e32 v60, v56
	v_sub_f32_e32 v56, v76, v175
	v_sub_f32_e32 v40, v40, v177
	v_exp_f32_e32 v56, v56
	v_sub_f32_e32 v58, v77, v175
	v_exp_f32_e32 v40, v40
	v_sub_f32_e32 v41, v41, v177
	v_exp_f32_e32 v58, v58
	v_sub_f32_e32 v59, v78, v175
	v_exp_f32_e32 v41, v41
	v_sub_f32_e32 v42, v42, v177
	v_exp_f32_e32 v59, v59
	v_sub_f32_e32 v63, v79, v175
	v_exp_f32_e32 v42, v42
	v_sub_f32_e32 v43, v43, v177
	v_exp_f32_e32 v63, v63
	v_sub_f32_e32 v76, v84, v175
	v_exp_f32_e32 v43, v43
	v_sub_f32_e32 v44, v44, v177
	v_exp_f32_e32 v76, v76
	v_sub_f32_e32 v77, v85, v175
	v_sub_f32_e32 v61, v128, v177
	v_exp_f32_e32 v44, v44
	v_sub_f32_e32 v45, v45, v177
	v_add_f32_e32 v57, 0, v56
	v_exp_f32_e32 v77, v77
	v_sub_f32_e32 v78, v86, v175
	v_exp_f32_e32 v62, v61
	v_add_f32_e32 v61, 0, v40
	v_exp_f32_e32 v45, v45
	v_sub_f32_e32 v46, v46, v177
	v_add_f32_e32 v57, v58, v57
	v_exp_f32_e32 v78, v78
	v_sub_f32_e32 v79, v87, v175
	v_add_f32_e32 v61, v41, v61
	v_exp_f32_e32 v46, v46
	v_add_f32_e32 v57, v59, v57
	v_exp_f32_e32 v79, v79
	v_add_f32_e32 v61, v42, v61
	v_sub_f32_e32 v47, v47, v177
	v_add_f32_e32 v57, v63, v57
	v_add_f32_e32 v61, v43, v61
	v_exp_f32_e32 v47, v47
	v_add_f32_e32 v57, v76, v57
	v_add_f32_e32 v61, v44, v61
	v_add_f32_e32 v57, v77, v57
	v_add_f32_e32 v61, v45, v61
	v_add_f32_e32 v57, v78, v57
	v_add_f32_e32 v61, v46, v61
	v_add_f32_e32 v176, v79, v57
	v_cvt_pk_bf16_f32 v56, v56, v58
	v_cvt_pk_bf16_f32 v57, v59, v63
	v_cvt_pk_bf16_f32 v58, v76, v77
	v_cvt_pk_bf16_f32 v59, v78, v79
	v_pk_mul_f32 v[34:35], v[34:35], v[60:61] op_sel_hi:[1,0]
	v_pk_mul_f32 v[32:33], v[32:33], v[60:61] op_sel_hi:[1,0]
	v_add_f32_e32 v178, v47, v61
	v_cvt_pk_bf16_f32 v40, v40, v41
	v_cvt_pk_bf16_f32 v41, v42, v43
	v_cvt_pk_bf16_f32 v42, v44, v45
	v_cvt_pk_bf16_f32 v43, v46, v47
	s_waitcnt lgkmcnt(10)
	v_mfma_f32_16x16x32_bf16 v[44:47], v[134:137], v[56:59], v[32:35]
	v_fmac_f32_e32 v176, v132, v60
	v_fmac_f32_e32 v178, v129, v62
	s_nop 0
	v_pk_mul_f32 v[34:35], v[98:99], v[62:63] op_sel_hi:[1,0]
	v_pk_mul_f32 v[32:33], v[96:97], v[62:63] op_sel_hi:[1,0]
	s_nop 1
	v_mfma_f32_16x16x32_bf16 v[100:103], v[134:137], v[40:43], v[32:35]
	s_nop 2
	v_mul_f32_e64 v34, v106, v60
	v_mul_f32_e64 v35, v107, v60
	v_pk_mul_f32 v[32:33], v[104:105], v[60:61] op_sel_hi:[1,0]
	s_waitcnt lgkmcnt(8)
	s_nop 0
	v_mfma_f32_16x16x32_bf16 v[104:107], v[138:141], v[56:59], v[32:35]
	s_nop 2
	v_mul_f32_e64 v34, v110, v62
	v_mul_f32_e64 v35, v111, v62
	v_pk_mul_f32 v[32:33], v[108:109], v[62:63] op_sel_hi:[1,0]
	s_nop 1
	v_mfma_f32_16x16x32_bf16 v[108:111], v[138:141], v[40:43], v[32:35]
	s_nop 2
	v_mul_f32_e64 v34, v114, v60
	v_mul_f32_e64 v35, v115, v60
	v_pk_mul_f32 v[32:33], v[112:113], v[60:61] op_sel_hi:[1,0]
	s_waitcnt lgkmcnt(6)
	s_nop 0
	v_mfma_f32_16x16x32_bf16 v[112:115], v[188:191], v[56:59], v[32:35]
	s_nop 2
	v_mul_f32_e64 v34, v118, v62
	v_mul_f32_e64 v35, v119, v62
	v_pk_mul_f32 v[32:33], v[116:117], v[62:63] op_sel_hi:[1,0]
	s_nop 1
	v_mfma_f32_16x16x32_bf16 v[116:119], v[188:191], v[40:43], v[32:35]
	v_add_u32_e32 v188, s76, v207
	s_nop 1
	v_pk_mul_f32 v[34:35], v[122:123], v[60:61] op_sel_hi:[1,0]
	v_pk_mul_f32 v[32:33], v[120:121], v[60:61] op_sel_hi:[1,0]
	s_waitcnt lgkmcnt(4)
	s_nop 0
	v_mfma_f32_16x16x32_bf16 v[120:123], v[200:203], v[56:59], v[32:35]
	v_or_b32_e32 v56, 0xb0, v166
	v_add_u32_e32 v56, s76, v56
	s_nop 0
	v_pk_mul_f32 v[34:35], v[126:127], v[62:63] op_sel_hi:[1,0]
	v_pk_mul_f32 v[32:33], v[124:125], v[62:63] op_sel_hi:[1,0]
	s_nop 1
	v_mfma_f32_16x16x32_bf16 v[124:127], v[200:203], v[40:43], v[32:35]
	s_nop 2
	v_add_u32_e32 v32, 0xa0, v149
	v_med3_i32 v32, v32, 0, s75
	v_lshl_add_u32 v32, v32, 9, v152
	global_load_dwordx4 v[76:79], v32, s[98:99]
	v_add_u32_e32 v32, 0xa0, v150
	v_med3_i32 v32, v32, 0, s75
	v_lshl_add_u32 v32, v32, 9, v152
	global_load_dwordx4 v[84:87], v32, s[98:99]
	v_add_u32_e32 v32, 0xa0, v151
	v_med3_i32 v32, v32, 0, s75
	v_lshl_add_u32 v32, v32, 9, v152
	global_load_dwordx4 v[92:95], v32, s[98:99]
	v_add_u32_e32 v32, 0xa0, v252
	v_med3_i32 v32, v32, 0, s75
	v_lshl_add_u32 v32, v32, 9, v152
	global_load_dwordx4 v[96:99], v32, s[98:99]
	v_or_b32_e32 v32, 0xa0, v166
	v_add_u32_e32 v32, s76, v32
	v_med3_i32 v32, v32, 0, s75
	v_med3_i32 v56, v56, 0, s75
	v_lshl_add_u32 v40, v32, 9, v158
	v_lshl_add_u32 v60, v56, 9, v158
	global_load_dwordx4 v[32:35], v40, s[100:101]
	s_nop 0
	global_load_dwordx4 v[40:43], v40, s[100:101] offset:64
	s_nop 0
	global_load_dwordx4 v[56:59], v60, s[100:101]
	s_nop 0
	global_load_dwordx4 v[60:63], v60, s[100:101] offset:64
	ds_read_b64_tr_b16 v[142:143], v169 offset:6912
	ds_read_b64_tr_b16 v[140:141], v169 offset:4608
	ds_read_b64_tr_b16 v[136:137], v169 offset:4640
	ds_read_b64_tr_b16 v[138:139], v169 offset:6944
	ds_read_b64_tr_b16 v[132:133], v169 offset:4672
	ds_read_b64_tr_b16 v[134:135], v169 offset:6976
	ds_read_b64_tr_b16 v[128:129], v169 offset:4704
	ds_read_b64_tr_b16 v[130:131], v169 offset:7008
	s_waitcnt vmcnt(15)
	ds_write_b128 v241, v[36:39]
	s_waitcnt vmcnt(14)
	ds_write_b128 v242, v[72:75]
	s_waitcnt vmcnt(13)
	ds_write_b128 v243, v[80:83]
	s_waitcnt vmcnt(12)
	ds_write_b128 v244, v[88:91]
	v_mfma_f32_16x16x32_bf16 v[36:39], v[24:27], v[4:7], 0
	v_mfma_f32_16x16x32_bf16 v[24:27], v[24:27], v[12:15], 0
	v_mfma_f32_16x16x32_bf16 v[36:39], v[28:31], v[8:11], v[36:39]
	v_mfma_f32_16x16x32_bf16 v[72:75], v[64:67], v[4:7], 0
	v_mfma_f32_16x16x32_bf16 v[24:27], v[28:31], v[0:3], v[24:27]
	v_mfma_f32_16x16x32_bf16 v[28:31], v[64:67], v[12:15], 0
	v_sub_u32_e32 v64, v199, v147
	v_add_u32_e32 v67, 1, v64
	s_nop 2
	v_cmp_gt_u32_e64 s[0:1], v67, v146
	v_cmp_gt_u32_e32 vcc, v64, v146
	s_nop 0
	v_cndmask_b32_e64 v37, v37, v246, s[0:1]
	s_nop 0
	v_cndmask_b32_e32 v36, v36, v246, vcc
	v_max_f32_e32 v66, 0xf149f2ca, v36
	v_mfma_f32_16x16x32_bf16 v[72:75], v[68:71], v[8:11], v[72:75]
	v_max_f32_e32 v66, v66, v37
	v_add_u32_e32 v67, 2, v64
	v_cmp_gt_u32_e64 s[22:23], v67, v146
	v_mfma_f32_16x16x32_bf16 v[28:31], v[68:71], v[0:3], v[28:31]
	v_add_u32_e32 v68, 3, v64
	v_cmp_gt_u32_e64 s[24:25], v68, v146
	v_cndmask_b32_e64 v38, v38, v246, s[22:23]
	v_sub_u32_e32 v65, v199, v148
	v_cndmask_b32_e64 v39, v39, v246, s[24:25]
	v_max3_f32 v66, v66, v38, v39
	v_add_u32_e32 v67, 16, v64
	v_add_u32_e32 v68, 17, v64
	v_cmp_gt_u32_e64 s[26:27], v67, v146
	v_cmp_gt_u32_e64 s[28:29], v68, v146
	v_cmp_gt_u32_e64 s[38:39], v65, v145
	v_cndmask_b32_e64 v72, v72, v246, s[26:27]
	v_cndmask_b32_e64 v73, v73, v246, s[28:29]
	v_max3_f32 v66, v66, v72, v73
	v_add_u32_e32 v67, 18, v64
	v_add_u32_e32 v64, 19, v64
	v_cmp_gt_u32_e64 s[30:31], v67, v146
	v_cmp_gt_u32_e64 s[34:35], v64, v146
	v_add_u32_e32 v68, 3, v65
	v_cndmask_b32_e64 v74, v74, v246, s[30:31]
	v_cndmask_b32_e64 v75, v75, v246, s[34:35]
	v_max3_f32 v64, v66, v74, v75
	v_add_u32_e32 v67, 1, v65
	v_cmp_gt_u32_e64 s[40:41], v67, v145
	v_cndmask_b32_e64 v24, v24, v246, s[38:39]
	v_max_f32_e32 v66, 0xf149f2ca, v24
	v_cndmask_b32_e64 v25, v25, v246, s[40:41]
	v_max_f32_e32 v66, v66, v25
	v_add_u32_e32 v67, 2, v65
	v_cmp_gt_u32_e64 s[42:43], v67, v145
	v_cmp_gt_u32_e64 s[44:45], v68, v145
	s_nop 0
	v_cndmask_b32_e64 v26, v26, v246, s[42:43]
	v_cndmask_b32_e64 v27, v27, v246, s[44:45]
	v_max3_f32 v66, v66, v26, v27
	v_add_u32_e32 v67, 16, v65
	v_add_u32_e32 v68, 17, v65
	v_cmp_gt_u32_e64 s[46:47], v67, v145
	v_cmp_gt_u32_e64 s[48:49], v68, v145
	s_nop 0
	v_cndmask_b32_e64 v28, v28, v246, s[46:47]
	v_cndmask_b32_e64 v29, v29, v246, s[48:49]
	v_max3_f32 v66, v66, v28, v29
	v_add_u32_e32 v67, 18, v65
	v_add_u32_e32 v65, 19, v65
	v_cmp_gt_u32_e64 s[50:51], v67, v145
	v_cmp_gt_u32_e64 s[52:53], v65, v145
	s_nop 0
	v_cndmask_b32_e64 v30, v30, v246, s[50:51]
	v_cndmask_b32_e64 v31, v31, v246, s[52:53]
	v_max3_f32 v65, v66, v30, v31
	v_mov_b32_e32 v66, v64
	s_nop 1
	v_permlane32_swap_b32_e32 v66, v64
	v_max_f32_e32 v64, v64, v66
	v_mov_b32_e32 v66, v65
	s_nop 1
	v_permlane32_swap_b32_e32 v66, v65
	v_max_f32_e32 v65, v65, v66
	v_mov_b32_e32 v66, v64
	s_nop 1
	v_permlane16_swap_b32_e32 v66, v64
	v_max3_f32 v179, v175, v64, v66
	v_sub_f32_e32 v36, v36, v179
	v_exp_f32_e32 v36, v36
	v_sub_f32_e32 v37, v37, v179
	v_mov_b32_e32 v66, v65
	v_exp_f32_e32 v37, v37
	v_sub_f32_e32 v38, v38, v179
	v_permlane16_swap_b32_e32 v66, v65
	v_exp_f32_e32 v38, v38
	v_sub_f32_e32 v39, v39, v179
	v_exp_f32_e32 v39, v39
	v_sub_f32_e32 v67, v72, v179
	v_max_f32_e32 v65, v65, v66
	v_exp_f32_e32 v67, v67
	v_sub_f32_e32 v69, v73, v179
	v_add_f32_e32 v66, 0, v36
	v_exp_f32_e32 v69, v69
	v_sub_f32_e32 v70, v74, v179
	v_max_f32_e32 v181, v177, v65
	v_add_f32_e32 v66, v37, v66
	v_exp_f32_e32 v70, v70
	v_sub_f32_e32 v71, v75, v179
	v_sub_f32_e32 v24, v24, v181
	v_add_f32_e32 v66, v38, v66
	v_exp_f32_e32 v71, v71
	v_exp_f32_e32 v24, v24
	v_sub_f32_e32 v25, v25, v181
	v_add_f32_e32 v66, v39, v66
	v_exp_f32_e32 v25, v25
	v_sub_f32_e32 v26, v26, v181
	v_add_f32_e32 v66, v67, v66
	v_exp_f32_e32 v26, v26
	v_sub_f32_e32 v27, v27, v181
	v_add_f32_e32 v66, v69, v66
	v_exp_f32_e32 v27, v27
	v_sub_f32_e32 v28, v28, v181
	v_add_f32_e32 v66, v70, v66
	v_sub_f32_e32 v65, v177, v181
	v_exp_f32_e32 v28, v28
	v_sub_f32_e32 v29, v29, v181
	v_add_f32_e32 v180, v71, v66
	v_exp_f32_e32 v66, v65
	v_add_f32_e32 v65, 0, v24
	v_exp_f32_e32 v29, v29
	v_sub_f32_e32 v30, v30, v181
	v_add_f32_e32 v65, v25, v65
	v_exp_f32_e32 v30, v30
	v_sub_f32_e32 v31, v31, v181
	v_sub_f32_e32 v64, v175, v179
	v_add_f32_e32 v65, v26, v65
	v_exp_f32_e32 v31, v31
	v_exp_f32_e32 v64, v64
	v_add_f32_e32 v65, v27, v65
	v_add_f32_e32 v65, v28, v65
	v_add_f32_e32 v65, v29, v65
	v_add_f32_e32 v65, v30, v65
	v_cvt_pk_bf16_f32 v36, v36, v37
	v_cvt_pk_bf16_f32 v37, v38, v39
	v_cvt_pk_bf16_f32 v38, v67, v69
	v_cvt_pk_bf16_f32 v39, v70, v71
	v_add_f32_e32 v183, v31, v65
	v_cvt_pk_bf16_f32 v24, v24, v25
	v_cvt_pk_bf16_f32 v25, v26, v27
	v_cvt_pk_bf16_f32 v26, v28, v29
	v_cvt_pk_bf16_f32 v27, v30, v31
	v_pk_mul_f32 v[30:31], v[46:47], v[64:65] op_sel_hi:[1,0]
	v_pk_mul_f32 v[28:29], v[44:45], v[64:65] op_sel_hi:[1,0]
	v_fmac_f32_e32 v180, v176, v64
	v_fmac_f32_e32 v183, v178, v66
	s_waitcnt lgkmcnt(10)
	v_mfma_f32_16x16x32_bf16 v[68:71], v[140:143], v[36:39], v[28:31]
	s_nop 2
	v_mul_f32_e64 v30, v102, v66
	v_mul_f32_e64 v31, v103, v66
	v_pk_mul_f32 v[28:29], v[100:101], v[66:67] op_sel_hi:[1,0]
	s_nop 1
	v_mfma_f32_16x16x32_bf16 v[72:75], v[140:143], v[24:27], v[28:31]
	s_nop 2
	v_mul_f32_e64 v30, v106, v64
	v_mul_f32_e64 v31, v107, v64
	v_pk_mul_f32 v[28:29], v[104:105], v[64:65] op_sel_hi:[1,0]
	s_waitcnt lgkmcnt(8)
	s_nop 0
	v_mfma_f32_16x16x32_bf16 v[80:83], v[136:139], v[36:39], v[28:31]
	s_nop 2
	v_mul_f32_e64 v30, v110, v66
	v_mul_f32_e64 v31, v111, v66
	v_pk_mul_f32 v[28:29], v[108:109], v[66:67] op_sel_hi:[1,0]
	s_nop 1
	v_mfma_f32_16x16x32_bf16 v[108:111], v[136:139], v[24:27], v[28:31]
	s_nop 2
	v_mul_f32_e64 v30, v114, v64
	v_mul_f32_e64 v31, v115, v64
	v_pk_mul_f32 v[28:29], v[112:113], v[64:65] op_sel_hi:[1,0]
	s_waitcnt lgkmcnt(6)
	s_nop 0
	v_mfma_f32_16x16x32_bf16 v[112:115], v[132:135], v[36:39], v[28:31]
	s_nop 2
	v_mul_f32_e64 v30, v118, v66
	v_mul_f32_e64 v31, v119, v66
	v_pk_mul_f32 v[28:29], v[116:117], v[66:67] op_sel_hi:[1,0]
	s_nop 1
	v_mfma_f32_16x16x32_bf16 v[116:119], v[132:135], v[24:27], v[28:31]
	s_nop 2
	v_mul_f32_e64 v30, v122, v64
	v_mul_f32_e64 v31, v123, v64
	v_pk_mul_f32 v[28:29], v[120:121], v[64:65] op_sel_hi:[1,0]
	s_waitcnt lgkmcnt(4)
	s_nop 0
	v_mfma_f32_16x16x32_bf16 v[120:123], v[128:131], v[36:39], v[28:31]
	s_nop 2
	v_mul_f32_e64 v30, v126, v66
	v_mul_f32_e64 v31, v127, v66
	v_pk_mul_f32 v[28:29], v[124:125], v[66:67] op_sel_hi:[1,0]
	s_nop 1
	v_mfma_f32_16x16x32_bf16 v[124:127], v[128:131], v[24:27], v[28:31]
	v_add_u32_e32 v24, 0xc0, v149
	v_med3_i32 v24, v24, 0, s75
	v_lshl_add_u32 v24, v24, 9, v152
	global_load_dwordx4 v[64:67], v24, s[98:99]
	v_add_u32_e32 v24, 0xc0, v150
	v_med3_i32 v24, v24, 0, s75
	v_lshl_add_u32 v24, v24, 9, v152
	global_load_dwordx4 v[88:91], v24, s[98:99]
	v_add_u32_e32 v24, 0xc0, v151
	v_med3_i32 v24, v24, 0, s75
	v_lshl_add_u32 v24, v24, 9, v152
	global_load_dwordx4 v[100:103], v24, s[98:99]
	v_add_u32_e32 v24, 0xc0, v252
	v_med3_i32 v24, v24, 0, s75
	v_lshl_add_u32 v24, v24, 9, v152
	global_load_dwordx4 v[104:107], v24, s[98:99]
	v_or_b32_e32 v24, 0xc0, v166
	v_add_u32_e32 v24, s76, v24
	v_med3_i32 v24, v24, 0, s75
	v_lshl_add_u32 v24, v24, 9, v158
	global_load_dwordx4 v[36:39], v24, s[100:101]
	global_load_dwordx4 v[44:47], v24, s[100:101] offset:64
	v_or_b32_e32 v24, 0xd0, v166
	v_add_u32_e32 v24, s76, v24
	v_med3_i32 v24, v24, 0, s75
	v_lshl_add_u32 v28, v24, 9, v158
	global_load_dwordx4 v[24:27], v28, s[100:101]
	s_nop 0
	global_load_dwordx4 v[28:31], v28, s[100:101] offset:64
	ds_read_b64_tr_b16 v[142:143], v169 offset:2304
	ds_read_b64_tr_b16 v[140:141], v169
	ds_read_b64_tr_b16 v[136:137], v169 offset:32
	ds_read_b64_tr_b16 v[138:139], v169 offset:2336
	ds_read_b64_tr_b16 v[132:133], v169 offset:64
	ds_read_b64_tr_b16 v[134:135], v169 offset:2368
	ds_read_b64_tr_b16 v[128:129], v169 offset:96
	ds_read_b64_tr_b16 v[130:131], v169 offset:2400
	s_waitcnt vmcnt(15)
	ds_write_b128 v241, v[76:79] offset:4608
	s_waitcnt vmcnt(14)
	ds_write_b128 v242, v[84:87] offset:4608
	s_waitcnt vmcnt(13)
	ds_write_b128 v243, v[92:95] offset:4608
	s_waitcnt vmcnt(12)
	ds_write_b128 v244, v[96:99] offset:4608
	v_mfma_f32_16x16x32_bf16 v[76:79], v[16:19], v[4:7], 0
	v_mfma_f32_16x16x32_bf16 v[16:19], v[16:19], v[12:15], 0
	v_mfma_f32_16x16x32_bf16 v[76:79], v[20:23], v[8:11], v[76:79]
	v_mfma_f32_16x16x32_bf16 v[84:87], v[48:51], v[4:7], 0
	v_mfma_f32_16x16x32_bf16 v[16:19], v[20:23], v[0:3], v[16:19]
	v_mfma_f32_16x16x32_bf16 v[20:23], v[48:51], v[12:15], 0
	v_add_u32_e32 v49, 0xc0, v154
	v_sub_u32_e32 v48, v49, v147
	v_add_u32_e32 v51, 1, v48
	s_nop 1
	v_cmp_gt_u32_e64 s[0:1], v51, v146
	v_cmp_gt_u32_e32 vcc, v48, v146
	s_nop 0
	v_cndmask_b32_e64 v77, v77, v246, s[0:1]
	s_nop 0
	v_cndmask_b32_e32 v76, v76, v246, vcc
	v_max_f32_e32 v50, 0xf149f2ca, v76
	v_mfma_f32_16x16x32_bf16 v[84:87], v[52:55], v[8:11], v[84:87]
	v_max_f32_e32 v50, v50, v77
	v_add_u32_e32 v51, 2, v48
	v_cmp_gt_u32_e64 s[22:23], v51, v146
	v_mfma_f32_16x16x32_bf16 v[20:23], v[52:55], v[0:3], v[20:23]
	v_add_u32_e32 v52, 3, v48
	v_cmp_gt_u32_e64 s[24:25], v52, v146
	v_cndmask_b32_e64 v78, v78, v246, s[22:23]
	v_sub_u32_e32 v49, v49, v148
	v_cndmask_b32_e64 v79, v79, v246, s[24:25]
	v_max3_f32 v50, v50, v78, v79
	v_add_u32_e32 v51, 16, v48
	v_add_u32_e32 v52, 17, v48
	v_cmp_gt_u32_e64 s[26:27], v51, v146
	v_cmp_gt_u32_e64 s[28:29], v52, v146
	v_cmp_gt_u32_e64 s[38:39], v49, v145
	v_cndmask_b32_e64 v84, v84, v246, s[26:27]
	v_cndmask_b32_e64 v85, v85, v246, s[28:29]
	v_max3_f32 v50, v50, v84, v85
	v_add_u32_e32 v51, 18, v48
	v_add_u32_e32 v48, 19, v48
	v_cmp_gt_u32_e64 s[30:31], v51, v146
	v_cmp_gt_u32_e64 s[34:35], v48, v146
	v_add_u32_e32 v52, 3, v49
	v_cndmask_b32_e64 v86, v86, v246, s[30:31]
	v_cndmask_b32_e64 v87, v87, v246, s[34:35]
	v_max3_f32 v48, v50, v86, v87
	v_add_u32_e32 v51, 1, v49
	v_cmp_gt_u32_e64 s[40:41], v51, v145
	v_cndmask_b32_e64 v16, v16, v246, s[38:39]
	v_max_f32_e32 v50, 0xf149f2ca, v16
	v_cndmask_b32_e64 v17, v17, v246, s[40:41]
	v_max_f32_e32 v50, v50, v17
	v_add_u32_e32 v51, 2, v49
	v_cmp_gt_u32_e64 s[42:43], v51, v145
	v_cmp_gt_u32_e64 s[44:45], v52, v145
	s_nop 0
	v_cndmask_b32_e64 v18, v18, v246, s[42:43]
	v_cndmask_b32_e64 v19, v19, v246, s[44:45]
	v_max3_f32 v50, v50, v18, v19
	v_add_u32_e32 v51, 16, v49
	v_add_u32_e32 v52, 17, v49
	v_cmp_gt_u32_e64 s[46:47], v51, v145
	v_cmp_gt_u32_e64 s[48:49], v52, v145
	s_nop 0
	v_cndmask_b32_e64 v20, v20, v246, s[46:47]
	v_cndmask_b32_e64 v21, v21, v246, s[48:49]
	v_max3_f32 v50, v50, v20, v21
	v_add_u32_e32 v51, 18, v49
	v_add_u32_e32 v49, 19, v49
	v_cmp_gt_u32_e64 s[50:51], v51, v145
	v_cmp_gt_u32_e64 s[52:53], v49, v145
	s_nop 0
	v_cndmask_b32_e64 v22, v22, v246, s[50:51]
	v_cndmask_b32_e64 v23, v23, v246, s[52:53]
	v_max3_f32 v49, v50, v22, v23
	v_mov_b32_e32 v50, v48
	s_nop 1
	v_permlane32_swap_b32_e32 v50, v48
	v_max_f32_e32 v48, v48, v50
	v_mov_b32_e32 v50, v49
	s_nop 1
	v_permlane32_swap_b32_e32 v50, v49
	v_max_f32_e32 v49, v49, v50
	v_mov_b32_e32 v50, v48
	s_nop 1
	v_permlane16_swap_b32_e32 v50, v48
	v_max_f32_e32 v48, v48, v50
	v_mov_b32_e32 v50, v49
	s_nop 1
	v_permlane16_swap_b32_e32 v50, v49
	v_max_f32_e32 v175, v179, v48
	v_sub_f32_e32 v48, v179, v175
	v_max3_f32 v177, v181, v49, v50
	v_exp_f32_e32 v52, v48
	v_sub_f32_e32 v48, v76, v175
	v_sub_f32_e32 v16, v16, v177
	v_exp_f32_e32 v48, v48
	v_sub_f32_e32 v50, v77, v175
	v_exp_f32_e32 v16, v16
	v_sub_f32_e32 v17, v17, v177
	v_exp_f32_e32 v50, v50
	v_sub_f32_e32 v51, v78, v175
	v_exp_f32_e32 v17, v17
	v_sub_f32_e32 v18, v18, v177
	v_exp_f32_e32 v51, v51
	v_sub_f32_e32 v55, v79, v175
	v_exp_f32_e32 v18, v18
	v_sub_f32_e32 v19, v19, v177
	v_exp_f32_e32 v55, v55
	v_sub_f32_e32 v76, v84, v175
	v_exp_f32_e32 v19, v19
	v_sub_f32_e32 v20, v20, v177
	v_exp_f32_e32 v76, v76
	v_sub_f32_e32 v77, v85, v175
	v_sub_f32_e32 v53, v181, v177
	v_exp_f32_e32 v20, v20
	v_sub_f32_e32 v21, v21, v177
	v_add_f32_e32 v49, 0, v48
	v_exp_f32_e32 v77, v77
	v_sub_f32_e32 v78, v86, v175
	v_exp_f32_e32 v54, v53
	v_add_f32_e32 v53, 0, v16
	v_exp_f32_e32 v21, v21
	v_sub_f32_e32 v22, v22, v177
	v_add_f32_e32 v49, v50, v49
	v_exp_f32_e32 v78, v78
	v_sub_f32_e32 v79, v87, v175
	v_add_f32_e32 v53, v17, v53
	v_exp_f32_e32 v22, v22
	v_sub_f32_e32 v23, v23, v177
	v_add_f32_e32 v49, v51, v49
	v_exp_f32_e32 v79, v79
	v_add_f32_e32 v53, v18, v53
	v_exp_f32_e32 v23, v23
	v_add_f32_e32 v49, v55, v49
	v_add_f32_e32 v53, v19, v53
	v_add_f32_e32 v49, v76, v49
	v_add_f32_e32 v53, v20, v53
	v_add_f32_e32 v49, v77, v49
	v_add_f32_e32 v53, v21, v53
	v_add_f32_e32 v49, v78, v49
	v_add_f32_e32 v53, v22, v53
	v_add_f32_e32 v176, v79, v49
	v_cvt_pk_bf16_f32 v48, v48, v50
	v_cvt_pk_bf16_f32 v49, v51, v55
	v_cvt_pk_bf16_f32 v50, v76, v77
	v_cvt_pk_bf16_f32 v51, v78, v79
	v_add_f32_e32 v178, v23, v53
	v_cvt_pk_bf16_f32 v16, v16, v17
	v_cvt_pk_bf16_f32 v17, v18, v19
	v_cvt_pk_bf16_f32 v18, v20, v21
	v_cvt_pk_bf16_f32 v19, v22, v23
	v_pk_mul_f32 v[22:23], v[70:71], v[52:53] op_sel_hi:[1,0]
	v_pk_mul_f32 v[20:21], v[68:69], v[52:53] op_sel_hi:[1,0]
	v_fmac_f32_e32 v176, v180, v52
	v_fmac_f32_e32 v178, v183, v54
	s_waitcnt lgkmcnt(10)
	v_mfma_f32_16x16x32_bf16 v[76:79], v[140:143], v[48:51], v[20:23]
	v_add_u32_e32 v180, 0x100, v149
	v_add_u32_e32 v179, 0x100, v150
	s_nop 0
	v_pk_mul_f32 v[22:23], v[74:75], v[54:55] op_sel_hi:[1,0]
	v_pk_mul_f32 v[20:21], v[72:73], v[54:55] op_sel_hi:[1,0]
	s_nop 1
	v_mfma_f32_16x16x32_bf16 v[92:95], v[140:143], v[16:19], v[20:23]
	s_nop 2
	v_mul_f32_e64 v22, v82, v52
	v_mul_f32_e64 v23, v83, v52
	v_pk_mul_f32 v[20:21], v[80:81], v[52:53] op_sel_hi:[1,0]
	s_waitcnt lgkmcnt(8)
	s_nop 0
	v_mfma_f32_16x16x32_bf16 v[96:99], v[136:139], v[48:51], v[20:23]
	s_nop 2
	v_mul_f32_e64 v22, v110, v54
	v_mul_f32_e64 v23, v111, v54
	v_pk_mul_f32 v[20:21], v[108:109], v[54:55] op_sel_hi:[1,0]
	s_nop 1
	v_mfma_f32_16x16x32_bf16 v[108:111], v[136:139], v[16:19], v[20:23]
	s_nop 2
	v_mul_f32_e64 v22, v114, v52
	v_mul_f32_e64 v23, v115, v52
	v_pk_mul_f32 v[20:21], v[112:113], v[52:53] op_sel_hi:[1,0]
	s_waitcnt lgkmcnt(6)
	s_nop 0
	v_mfma_f32_16x16x32_bf16 v[112:115], v[132:135], v[48:51], v[20:23]
	s_nop 2
	v_mul_f32_e64 v22, v118, v54
	v_mul_f32_e64 v23, v119, v54
	v_pk_mul_f32 v[20:21], v[116:117], v[54:55] op_sel_hi:[1,0]
	s_nop 1
	v_mfma_f32_16x16x32_bf16 v[116:119], v[132:135], v[16:19], v[20:23]
	s_nop 2
	v_mul_f32_e64 v22, v122, v52
	v_mul_f32_e64 v23, v123, v52
	v_pk_mul_f32 v[20:21], v[120:121], v[52:53] op_sel_hi:[1,0]
	s_waitcnt lgkmcnt(4)
	s_nop 0
	v_mfma_f32_16x16x32_bf16 v[120:123], v[128:131], v[48:51], v[20:23]
	s_nop 2
	v_mul_f32_e64 v22, v126, v54
	v_mul_f32_e64 v23, v127, v54
	v_pk_mul_f32 v[20:21], v[124:125], v[54:55] op_sel_hi:[1,0]
	s_nop 1
	v_mfma_f32_16x16x32_bf16 v[124:127], v[128:131], v[16:19], v[20:23]
	v_add_u32_e32 v16, 0xe0, v149
	v_med3_i32 v16, v16, 0, s75
	v_lshl_add_u32 v16, v16, 9, v152
	global_load_dwordx4 v[68:71], v16, s[98:99]
	v_add_u32_e32 v16, 0xe0, v150
	v_med3_i32 v16, v16, 0, s75
	v_lshl_add_u32 v16, v16, 9, v152
	global_load_dwordx4 v[72:75], v16, s[98:99]
	v_add_u32_e32 v16, 0xe0, v151
	v_med3_i32 v16, v16, 0, s75
	v_lshl_add_u32 v16, v16, 9, v152
	global_load_dwordx4 v[80:83], v16, s[98:99]
	v_add_u32_e32 v16, 0xe0, v252
	v_med3_i32 v16, v16, 0, s75
	v_lshl_add_u32 v16, v16, 9, v152
	global_load_dwordx4 v[84:87], v16, s[98:99]
	v_or_b32_e32 v16, 0xe0, v166
	v_add_u32_e32 v16, s76, v16
	v_med3_i32 v16, v16, 0, s75
	v_lshl_add_u32 v16, v16, 9, v158
	global_load_dwordx4 v[48:51], v16, s[100:101]
	global_load_dwordx4 v[52:55], v16, s[100:101] offset:64
	v_or_b32_e32 v16, 0xf0, v166
	v_add_u32_e32 v16, s76, v16
	v_med3_i32 v16, v16, 0, s75
	v_lshl_add_u32 v20, v16, 9, v158
	global_load_dwordx4 v[16:19], v20, s[100:101]
	s_nop 0
	global_load_dwordx4 v[20:23], v20, s[100:101] offset:64
	ds_read_b64_tr_b16 v[142:143], v169 offset:6912
	ds_read_b64_tr_b16 v[140:141], v169 offset:4608
	ds_read_b64_tr_b16 v[136:137], v169 offset:4640
	ds_read_b64_tr_b16 v[138:139], v169 offset:6944
	ds_read_b64_tr_b16 v[132:133], v169 offset:4672
	ds_read_b64_tr_b16 v[134:135], v169 offset:6976
	ds_read_b64_tr_b16 v[128:129], v169 offset:4704
	ds_read_b64_tr_b16 v[130:131], v169 offset:7008
	s_waitcnt vmcnt(15)
	ds_write_b128 v241, v[64:67]
	s_waitcnt vmcnt(14)
	ds_write_b128 v242, v[88:91]
	s_waitcnt vmcnt(13)
	ds_write_b128 v243, v[100:103]
	s_waitcnt vmcnt(12)
	ds_write_b128 v244, v[104:107]
	v_mfma_f32_16x16x32_bf16 v[64:67], v[32:35], v[4:7], 0
	v_mfma_f32_16x16x32_bf16 v[32:35], v[32:35], v[12:15], 0
	v_mfma_f32_16x16x32_bf16 v[64:67], v[40:43], v[8:11], v[64:67]
	v_mfma_f32_16x16x32_bf16 v[88:91], v[56:59], v[4:7], 0
	v_mfma_f32_16x16x32_bf16 v[32:35], v[40:43], v[0:3], v[32:35]
	v_mfma_f32_16x16x32_bf16 v[40:43], v[56:59], v[12:15], 0
	v_add_u32_e32 v57, 0xe0, v154
	v_sub_u32_e32 v56, v57, v147
	v_add_u32_e32 v59, 1, v56
	s_nop 1
	v_cmp_gt_u32_e64 s[0:1], v59, v146
	v_cmp_gt_u32_e32 vcc, v56, v146
	s_nop 0
	v_cndmask_b32_e64 v65, v65, v246, s[0:1]
	s_nop 0
	v_cndmask_b32_e32 v64, v64, v246, vcc
	v_max_f32_e32 v58, 0xf149f2ca, v64
	v_mfma_f32_16x16x32_bf16 v[88:91], v[60:63], v[8:11], v[88:91]
	v_max_f32_e32 v58, v58, v65
	v_add_u32_e32 v59, 2, v56
	v_cmp_gt_u32_e64 s[22:23], v59, v146
	v_mfma_f32_16x16x32_bf16 v[40:43], v[60:63], v[0:3], v[40:43]
	v_add_u32_e32 v60, 3, v56
	v_cmp_gt_u32_e64 s[24:25], v60, v146
	v_cndmask_b32_e64 v66, v66, v246, s[22:23]
	v_sub_u32_e32 v57, v57, v148
	v_cndmask_b32_e64 v67, v67, v246, s[24:25]
	v_max3_f32 v58, v58, v66, v67
	v_add_u32_e32 v59, 16, v56
	v_add_u32_e32 v60, 17, v56
	v_cmp_gt_u32_e64 s[26:27], v59, v146
	v_cmp_gt_u32_e64 s[28:29], v60, v146
	v_cmp_gt_u32_e64 s[38:39], v57, v145
	v_cndmask_b32_e64 v88, v88, v246, s[26:27]
	v_cndmask_b32_e64 v89, v89, v246, s[28:29]
	v_max3_f32 v58, v58, v88, v89
	v_add_u32_e32 v59, 18, v56
	v_add_u32_e32 v56, 19, v56
	v_cmp_gt_u32_e64 s[30:31], v59, v146
	v_cmp_gt_u32_e64 s[34:35], v56, v146
	v_add_u32_e32 v60, 3, v57
	v_cndmask_b32_e64 v90, v90, v246, s[30:31]
	v_cndmask_b32_e64 v91, v91, v246, s[34:35]
	v_max3_f32 v56, v58, v90, v91
	v_add_u32_e32 v59, 1, v57
	v_cmp_gt_u32_e64 s[40:41], v59, v145
	v_cndmask_b32_e64 v32, v32, v246, s[38:39]
	v_max_f32_e32 v58, 0xf149f2ca, v32
	v_cndmask_b32_e64 v33, v33, v246, s[40:41]
	v_max_f32_e32 v58, v58, v33
	v_add_u32_e32 v59, 2, v57
	v_cmp_gt_u32_e64 s[42:43], v59, v145
	v_cmp_gt_u32_e64 s[44:45], v60, v145
	s_nop 0
	v_cndmask_b32_e64 v34, v34, v246, s[42:43]
	v_cndmask_b32_e64 v35, v35, v246, s[44:45]
	v_max3_f32 v58, v58, v34, v35
	v_add_u32_e32 v59, 16, v57
	v_add_u32_e32 v60, 17, v57
	v_cmp_gt_u32_e64 s[46:47], v59, v145
	v_cmp_gt_u32_e64 s[48:49], v60, v145
	s_nop 0
	v_cndmask_b32_e64 v40, v40, v246, s[46:47]
	v_cndmask_b32_e64 v41, v41, v246, s[48:49]
	v_max3_f32 v58, v58, v40, v41
	v_add_u32_e32 v59, 18, v57
	v_add_u32_e32 v57, 19, v57
	v_cmp_gt_u32_e64 s[50:51], v59, v145
	v_cmp_gt_u32_e64 s[52:53], v57, v145
	s_nop 0
	v_cndmask_b32_e64 v42, v42, v246, s[50:51]
	v_cndmask_b32_e64 v43, v43, v246, s[52:53]
	v_max3_f32 v57, v58, v42, v43
	v_mov_b32_e32 v58, v56
	s_nop 1
	v_permlane32_swap_b32_e32 v58, v56
	v_max_f32_e32 v56, v56, v58
	v_mov_b32_e32 v58, v57
	s_nop 1
	v_permlane32_swap_b32_e32 v58, v57
	v_max_f32_e32 v57, v57, v58
	v_mov_b32_e32 v58, v56
	s_nop 1
	v_permlane16_swap_b32_e32 v58, v56
	v_max_f32_e32 v56, v56, v58
	v_mov_b32_e32 v58, v57
	s_nop 1
	v_permlane16_swap_b32_e32 v58, v57
	v_max_f32_e32 v181, v175, v56
	v_sub_f32_e32 v56, v175, v181
	v_max3_f32 v184, v177, v57, v58
	v_exp_f32_e32 v60, v56
	v_sub_f32_e32 v56, v64, v181
	v_sub_f32_e32 v32, v32, v184
	v_exp_f32_e32 v56, v56
	v_sub_f32_e32 v58, v65, v181
	v_exp_f32_e32 v32, v32
	v_sub_f32_e32 v33, v33, v184
	v_exp_f32_e32 v58, v58
	v_sub_f32_e32 v59, v66, v181
	v_exp_f32_e32 v33, v33
	v_sub_f32_e32 v34, v34, v184
	v_exp_f32_e32 v59, v59
	v_sub_f32_e32 v63, v67, v181
	v_exp_f32_e32 v34, v34
	v_sub_f32_e32 v35, v35, v184
	v_exp_f32_e32 v63, v63
	v_sub_f32_e32 v64, v88, v181
	v_exp_f32_e32 v35, v35
	v_sub_f32_e32 v40, v40, v184
	v_exp_f32_e32 v64, v64
	v_sub_f32_e32 v65, v89, v181
	v_sub_f32_e32 v61, v177, v184
	v_exp_f32_e32 v40, v40
	v_sub_f32_e32 v41, v41, v184
	v_add_f32_e32 v57, 0, v56
	v_exp_f32_e32 v65, v65
	v_sub_f32_e32 v66, v90, v181
	v_exp_f32_e32 v62, v61
	v_add_f32_e32 v61, 0, v32
	v_exp_f32_e32 v41, v41
	v_sub_f32_e32 v42, v42, v184
	v_add_f32_e32 v57, v58, v57
	v_exp_f32_e32 v66, v66
	v_sub_f32_e32 v67, v91, v181
	v_add_f32_e32 v61, v33, v61
	v_exp_f32_e32 v42, v42
	v_sub_f32_e32 v43, v43, v184
	v_add_f32_e32 v57, v59, v57
	v_exp_f32_e32 v67, v67
	v_add_f32_e32 v61, v34, v61
	v_exp_f32_e32 v43, v43
	v_add_f32_e32 v57, v63, v57
	v_add_f32_e32 v61, v35, v61
	v_add_f32_e32 v57, v64, v57
	v_add_f32_e32 v61, v40, v61
	v_add_f32_e32 v57, v65, v57
	v_add_f32_e32 v61, v41, v61
	v_add_f32_e32 v57, v66, v57
	v_add_f32_e32 v61, v42, v61
	v_add_f32_e32 v183, v67, v57
	v_cvt_pk_bf16_f32 v56, v56, v58
	v_cvt_pk_bf16_f32 v57, v59, v63
	v_cvt_pk_bf16_f32 v58, v64, v65
	v_cvt_pk_bf16_f32 v59, v66, v67
	v_add_f32_e32 v185, v43, v61
	v_cvt_pk_bf16_f32 v32, v32, v33
	v_cvt_pk_bf16_f32 v33, v34, v35
	v_cvt_pk_bf16_f32 v34, v40, v41
	v_cvt_pk_bf16_f32 v35, v42, v43
	v_pk_mul_f32 v[42:43], v[78:79], v[60:61] op_sel_hi:[1,0]
	v_pk_mul_f32 v[40:41], v[76:77], v[60:61] op_sel_hi:[1,0]
	v_fmac_f32_e32 v185, v178, v62
	s_waitcnt lgkmcnt(10)
	v_mfma_f32_16x16x32_bf16 v[100:103], v[140:143], v[56:59], v[40:43]
	v_add_u32_e32 v178, 0x100, v151
	v_fmac_f32_e32 v183, v176, v60
	v_add_u32_e32 v177, 0x100, v252
	v_pk_mul_f32 v[42:43], v[94:95], v[62:63] op_sel_hi:[1,0]
	v_pk_mul_f32 v[40:41], v[92:93], v[62:63] op_sel_hi:[1,0]
	s_nop 1
	v_mfma_f32_16x16x32_bf16 v[92:95], v[140:143], v[32:35], v[40:43]
	s_nop 2
	v_mul_f32_e64 v42, v98, v60
	v_mul_f32_e64 v43, v99, v60
	v_pk_mul_f32 v[40:41], v[96:97], v[60:61] op_sel_hi:[1,0]
	s_waitcnt lgkmcnt(8)
	s_nop 0
	v_mfma_f32_16x16x32_bf16 v[104:107], v[136:139], v[56:59], v[40:43]
	s_nop 2
	v_mul_f32_e64 v42, v110, v62
	v_mul_f32_e64 v43, v111, v62
	v_pk_mul_f32 v[40:41], v[108:109], v[62:63] op_sel_hi:[1,0]
	s_nop 1
	v_mfma_f32_16x16x32_bf16 v[108:111], v[136:139], v[32:35], v[40:43]
	s_nop 2
	v_mul_f32_e64 v42, v114, v60
	v_mul_f32_e64 v43, v115, v60
	v_pk_mul_f32 v[40:41], v[112:113], v[60:61] op_sel_hi:[1,0]
	s_waitcnt lgkmcnt(6)
	s_nop 0
	v_mfma_f32_16x16x32_bf16 v[112:115], v[132:135], v[56:59], v[40:43]
	s_nop 2
	v_mul_f32_e64 v42, v118, v62
	v_mul_f32_e64 v43, v119, v62
	v_pk_mul_f32 v[40:41], v[116:117], v[62:63] op_sel_hi:[1,0]
	s_nop 1
	v_mfma_f32_16x16x32_bf16 v[116:119], v[132:135], v[32:35], v[40:43]
	s_nop 2
	v_mul_f32_e64 v42, v122, v60
	v_mul_f32_e64 v43, v123, v60
	v_pk_mul_f32 v[40:41], v[120:121], v[60:61] op_sel_hi:[1,0]
	s_waitcnt lgkmcnt(4)
	s_nop 0
	v_mfma_f32_16x16x32_bf16 v[120:123], v[128:131], v[56:59], v[40:43]
	s_nop 2
	v_mul_f32_e64 v42, v126, v62
	v_mul_f32_e64 v43, v127, v62
	v_pk_mul_f32 v[40:41], v[124:125], v[62:63] op_sel_hi:[1,0]
	s_nop 1
	v_mfma_f32_16x16x32_bf16 v[124:127], v[128:131], v[32:35], v[40:43]
	v_med3_i32 v32, v180, 0, s75
	v_lshl_add_u32 v32, v32, 9, v152
	global_load_dwordx4 v[56:59], v32, s[98:99]
	v_med3_i32 v32, v179, 0, s75
	v_lshl_add_u32 v32, v32, 9, v152
	global_load_dwordx4 v[60:63], v32, s[98:99]
	v_med3_i32 v32, v178, 0, s75
	v_lshl_add_u32 v32, v32, 9, v152
	global_load_dwordx4 v[88:91], v32, s[98:99]
	v_med3_i32 v32, v177, 0, s75
	v_lshl_add_u32 v32, v32, 9, v152
	global_load_dwordx4 v[96:99], v32, s[98:99]
	v_or_b32_e32 v32, 0x100, v166
	v_add_u32_e32 v32, s76, v32
	v_med3_i32 v32, v32, 0, s75
	v_lshl_add_u32 v32, v32, 9, v158
	global_load_dwordx4 v[76:79], v32, s[100:101]
	global_load_dwordx4 v[64:67], v32, s[100:101] offset:64
	v_or_b32_e32 v32, 0x110, v166
	v_add_u32_e32 v32, s76, v32
	v_med3_i32 v32, v32, 0, s75
	v_lshl_add_u32 v32, v32, 9, v158
	global_load_dwordx4 v[40:43], v32, s[100:101]
	s_nop 0
	global_load_dwordx4 v[32:35], v32, s[100:101] offset:64
	ds_read_b64_tr_b16 v[142:143], v169 offset:2304
	ds_read_b64_tr_b16 v[140:141], v169
	ds_read_b64_tr_b16 v[136:137], v169 offset:32
	ds_read_b64_tr_b16 v[138:139], v169 offset:2336
	ds_read_b64_tr_b16 v[132:133], v169 offset:64
	ds_read_b64_tr_b16 v[134:135], v169 offset:2368
	ds_read_b64_tr_b16 v[128:129], v169 offset:96
	ds_read_b64_tr_b16 v[130:131], v169 offset:2400
	s_waitcnt vmcnt(15)
	ds_write_b128 v241, v[68:71] offset:4608
	s_waitcnt vmcnt(14)
	ds_write_b128 v242, v[72:75] offset:4608
	s_waitcnt vmcnt(13)
	ds_write_b128 v243, v[80:83] offset:4608
	s_waitcnt vmcnt(12)
	ds_write_b128 v244, v[84:87] offset:4608
	v_mfma_f32_16x16x32_bf16 v[68:71], v[36:39], v[4:7], 0
	v_mfma_f32_16x16x32_bf16 v[72:75], v[24:27], v[4:7], 0
	v_mfma_f32_16x16x32_bf16 v[24:27], v[24:27], v[12:15], 0
	v_mfma_f32_16x16x32_bf16 v[68:71], v[44:47], v[8:11], v[68:71]
	v_mfma_f32_16x16x32_bf16 v[72:75], v[28:31], v[8:11], v[72:75]
	v_mfma_f32_16x16x32_bf16 v[24:27], v[28:31], v[0:3], v[24:27]
	v_add_u32_e32 v29, 0x100, v154
	v_sub_u32_e32 v28, v29, v147
	v_add_u32_e32 v31, 1, v28
	v_mfma_f32_16x16x32_bf16 v[36:39], v[36:39], v[12:15], 0
	s_nop 1
	v_cmp_gt_u32_e64 s[0:1], v31, v146
	v_cmp_gt_u32_e32 vcc, v28, v146
	s_nop 0
	v_cndmask_b32_e64 v69, v69, v246, s[0:1]
	s_nop 0
	v_cndmask_b32_e32 v68, v68, v246, vcc
	v_max_f32_e32 v30, 0xf149f2ca, v68
	v_mfma_f32_16x16x32_bf16 v[36:39], v[44:47], v[0:3], v[36:39]
	v_max_f32_e32 v30, v30, v69
	v_add_u32_e32 v31, 2, v28
	v_add_u32_e32 v44, 3, v28
	v_cmp_gt_u32_e64 s[22:23], v31, v146
	v_cmp_gt_u32_e64 s[24:25], v44, v146
	v_sub_u32_e32 v29, v29, v148
	v_cndmask_b32_e64 v70, v70, v246, s[22:23]
	v_cndmask_b32_e64 v71, v71, v246, s[24:25]
	v_max3_f32 v30, v30, v70, v71
	v_add_u32_e32 v31, 16, v28
	v_add_u32_e32 v44, 17, v28
	v_cmp_gt_u32_e64 s[26:27], v31, v146
	v_cmp_gt_u32_e64 s[28:29], v44, v146
	v_cmp_gt_u32_e64 s[38:39], v29, v145
	v_cndmask_b32_e64 v72, v72, v246, s[26:27]
	v_cndmask_b32_e64 v73, v73, v246, s[28:29]
	v_max3_f32 v30, v30, v72, v73
	v_add_u32_e32 v31, 18, v28
	v_add_u32_e32 v28, 19, v28
	v_cmp_gt_u32_e64 s[30:31], v31, v146
	v_cmp_gt_u32_e64 s[34:35], v28, v146
	v_add_u32_e32 v44, 3, v29
	v_cndmask_b32_e64 v74, v74, v246, s[30:31]
	v_cndmask_b32_e64 v75, v75, v246, s[34:35]
	v_max3_f32 v28, v30, v74, v75
	v_add_u32_e32 v31, 1, v29
	v_cmp_gt_u32_e64 s[40:41], v31, v145
	v_cndmask_b32_e64 v36, v36, v246, s[38:39]
	v_max_f32_e32 v30, 0xf149f2ca, v36
	v_cndmask_b32_e64 v37, v37, v246, s[40:41]
	v_max_f32_e32 v30, v30, v37
	v_add_u32_e32 v31, 2, v29
	v_cmp_gt_u32_e64 s[42:43], v31, v145
	v_cmp_gt_u32_e64 s[44:45], v44, v145
	s_nop 0
	v_cndmask_b32_e64 v38, v38, v246, s[42:43]
	v_cndmask_b32_e64 v39, v39, v246, s[44:45]
	v_max3_f32 v30, v30, v38, v39
	v_add_u32_e32 v31, 16, v29
	v_add_u32_e32 v44, 17, v29
	v_cmp_gt_u32_e64 s[46:47], v31, v145
	v_cmp_gt_u32_e64 s[48:49], v44, v145
	s_nop 0
	v_cndmask_b32_e64 v24, v24, v246, s[46:47]
	v_cndmask_b32_e64 v25, v25, v246, s[48:49]
	v_max3_f32 v30, v30, v24, v25
	v_add_u32_e32 v31, 18, v29
	v_add_u32_e32 v29, 19, v29
	v_cmp_gt_u32_e64 s[50:51], v31, v145
	v_cmp_gt_u32_e64 s[52:53], v29, v145
	s_nop 0
	v_cndmask_b32_e64 v26, v26, v246, s[50:51]
	v_cndmask_b32_e64 v27, v27, v246, s[52:53]
	v_max3_f32 v29, v30, v26, v27
	v_mov_b32_e32 v30, v28
	s_nop 1
	v_permlane32_swap_b32_e32 v30, v28
	v_max_f32_e32 v28, v28, v30
	v_mov_b32_e32 v30, v29
	s_nop 1
	v_permlane32_swap_b32_e32 v30, v29
	v_max_f32_e32 v29, v29, v30
	v_mov_b32_e32 v30, v28
	s_nop 1
	v_permlane16_swap_b32_e32 v30, v28
	v_max_f32_e32 v28, v28, v30
	v_mov_b32_e32 v30, v29
	v_max_f32_e32 v175, v181, v28
	s_nop 0
	v_permlane16_swap_b32_e32 v30, v29
	v_sub_f32_e32 v28, v181, v175
	v_exp_f32_e32 v44, v28
	v_sub_f32_e32 v28, v68, v175
	v_max_f32_e32 v46, v29, v30
	v_exp_f32_e32 v28, v28
	v_sub_f32_e32 v30, v69, v175
	v_exp_f32_e32 v30, v30
	v_sub_f32_e32 v31, v70, v175
	v_exp_f32_e32 v31, v31
	v_sub_f32_e32 v47, v71, v175
	v_max_f32_e32 v181, v184, v46
	v_exp_f32_e32 v47, v47
	v_sub_f32_e32 v68, v72, v175
	v_sub_f32_e32 v36, v36, v181
	v_exp_f32_e32 v68, v68
	v_sub_f32_e32 v69, v73, v175
	v_exp_f32_e32 v36, v36
	v_sub_f32_e32 v37, v37, v181
	v_add_f32_e32 v29, 0, v28
	v_exp_f32_e32 v69, v69
	v_sub_f32_e32 v70, v74, v175
	v_exp_f32_e32 v37, v37
	v_sub_f32_e32 v38, v38, v181
	v_add_f32_e32 v29, v30, v29
	v_exp_f32_e32 v70, v70
	v_sub_f32_e32 v71, v75, v175
	v_exp_f32_e32 v38, v38
	v_sub_f32_e32 v39, v39, v181
	v_add_f32_e32 v29, v31, v29
	v_exp_f32_e32 v71, v71
	v_exp_f32_e32 v39, v39
	v_sub_f32_e32 v24, v24, v181
	v_add_f32_e32 v29, v47, v29
	v_sub_f32_e32 v45, v184, v181
	v_exp_f32_e32 v24, v24
	v_sub_f32_e32 v25, v25, v181
	v_add_f32_e32 v29, v68, v29
	v_exp_f32_e32 v46, v45
	v_add_f32_e32 v45, 0, v36
	v_exp_f32_e32 v25, v25
	v_add_f32_e32 v29, v69, v29
	v_add_f32_e32 v45, v37, v45
	v_add_f32_e32 v29, v70, v29
	v_add_f32_e32 v45, v38, v45
	v_add_f32_e32 v176, v71, v29
	v_cvt_pk_bf16_f32 v29, v31, v47
	v_add_f32_e32 v45, v39, v45
	v_cndmask_b32_e64 v47, v24, 0, s[46:47]
	v_add_f32_e32 v24, v47, v45
	v_cndmask_b32_e64 v45, v25, 0, s[48:49]
	v_sub_f32_e32 v25, v26, v181
	v_exp_f32_e32 v25, v25
	v_cvt_pk_bf16_f32 v28, v28, v30
	v_cvt_pk_bf16_f32 v30, v68, v69
	v_add_f32_e32 v24, v45, v24
	v_cndmask_b32_e64 v68, v25, 0, s[50:51]
	v_sub_f32_e32 v25, v27, v181
	v_exp_f32_e32 v25, v25
	v_add_f32_e32 v24, v68, v24
	v_fmac_f32_e32 v176, v183, v44
	v_cvt_pk_bf16_f32 v31, v70, v71
	v_cndmask_b32_e64 v27, v25, 0, s[52:53]
	v_add_f32_e32 v183, v27, v24
	v_cvt_pk_bf16_f32 v24, v36, v37
	v_cvt_pk_bf16_f32 v25, v38, v39
	v_pk_mul_f32 v[38:39], v[102:103], v[44:45] op_sel_hi:[1,0]
	v_pk_mul_f32 v[36:37], v[100:101], v[44:45] op_sel_hi:[1,0]
	v_cvt_pk_bf16_f32 v26, v47, v45
	v_cvt_pk_bf16_f32 v27, v68, v27
	s_waitcnt lgkmcnt(10)
	v_mfma_f32_16x16x32_bf16 v[80:83], v[140:143], v[28:31], v[36:39]
	v_fmac_f32_e32 v183, v185, v46
	v_add_u32_e32 v184, s76, v204
	v_add_u32_e32 v185, s76, v205
	v_pk_mul_f32 v[38:39], v[94:95], v[46:47] op_sel_hi:[1,0]
	v_pk_mul_f32 v[36:37], v[92:93], v[46:47] op_sel_hi:[1,0]
	s_nop 1
	v_mfma_f32_16x16x32_bf16 v[84:87], v[140:143], v[24:27], v[36:39]
	s_nop 2
	v_mul_f32_e64 v38, v106, v44
	v_mul_f32_e64 v39, v107, v44
	v_pk_mul_f32 v[36:37], v[104:105], v[44:45] op_sel_hi:[1,0]
	s_waitcnt lgkmcnt(8)
	s_nop 0
	v_mfma_f32_16x16x32_bf16 v[104:107], v[136:139], v[28:31], v[36:39]
	s_nop 2
	v_mul_f32_e64 v38, v110, v46
	v_mul_f32_e64 v39, v111, v46
	v_pk_mul_f32 v[36:37], v[108:109], v[46:47] op_sel_hi:[1,0]
	s_nop 1
	v_mfma_f32_16x16x32_bf16 v[108:111], v[136:139], v[24:27], v[36:39]
	s_nop 2
	v_mul_f32_e64 v38, v114, v44
	v_mul_f32_e64 v39, v115, v44
	v_pk_mul_f32 v[36:37], v[112:113], v[44:45] op_sel_hi:[1,0]
	s_waitcnt lgkmcnt(6)
	s_nop 0
	v_mfma_f32_16x16x32_bf16 v[112:115], v[132:135], v[28:31], v[36:39]
	s_nop 2
	v_mul_f32_e64 v38, v118, v46
	v_mul_f32_e64 v39, v119, v46
	v_pk_mul_f32 v[36:37], v[116:117], v[46:47] op_sel_hi:[1,0]
	s_nop 1
	v_mfma_f32_16x16x32_bf16 v[116:119], v[132:135], v[24:27], v[36:39]
	s_nop 2
	v_mul_f32_e64 v38, v122, v44
	v_mul_f32_e64 v39, v123, v44
	v_pk_mul_f32 v[36:37], v[120:121], v[44:45] op_sel_hi:[1,0]
	s_waitcnt lgkmcnt(4)
	s_nop 0
	v_mfma_f32_16x16x32_bf16 v[120:123], v[128:131], v[28:31], v[36:39]
	v_mul_f32_e64 v30, v126, v46
	v_mul_f32_e64 v31, v127, v46
	v_pk_mul_f32 v[28:29], v[124:125], v[46:47] op_sel_hi:[1,0]
	s_nop 1
	v_mfma_f32_16x16x32_bf16 v[124:127], v[128:131], v[24:27], v[28:31]
	v_add_u32_e32 v24, 0x120, v149
	v_med3_i32 v24, v24, 0, s75
	v_lshl_add_u32 v24, v24, 9, v152
	global_load_dwordx4 v[28:31], v24, s[98:99]
	v_add_u32_e32 v24, 0x120, v150
	v_med3_i32 v24, v24, 0, s75
	v_lshl_add_u32 v24, v24, 9, v152
	global_load_dwordx4 v[44:47], v24, s[98:99]
	v_add_u32_e32 v24, 0x120, v151
	v_med3_i32 v24, v24, 0, s75
	v_lshl_add_u32 v24, v24, 9, v152
	global_load_dwordx4 v[92:95], v24, s[98:99]
	v_add_u32_e32 v24, 0x120, v252
	v_med3_i32 v24, v24, 0, s75
	v_lshl_add_u32 v24, v24, 9, v152
	global_load_dwordx4 v[100:103], v24, s[98:99]
	v_or_b32_e32 v24, 0x120, v166
	v_add_u32_e32 v24, s76, v24
	v_med3_i32 v24, v24, 0, s75
	v_lshl_add_u32 v24, v24, 9, v158
	global_load_dwordx4 v[72:75], v24, s[100:101]
	global_load_dwordx4 v[68:71], v24, s[100:101] offset:64
	v_or_b32_e32 v24, 0x130, v166
	v_add_u32_e32 v24, s76, v24
	v_med3_i32 v24, v24, 0, s75
	v_lshl_add_u32 v24, v24, 9, v158
	global_load_dwordx4 v[36:39], v24, s[100:101]
	s_nop 0
	global_load_dwordx4 v[24:27], v24, s[100:101] offset:64
	ds_read_b64_tr_b16 v[142:143], v169 offset:6912
	ds_read_b64_tr_b16 v[140:141], v169 offset:4608
	ds_read_b64_tr_b16 v[136:137], v169 offset:4640
	ds_read_b64_tr_b16 v[138:139], v169 offset:6944
	ds_read_b64_tr_b16 v[132:133], v169 offset:4672
	ds_read_b64_tr_b16 v[134:135], v169 offset:6976
	ds_read_b64_tr_b16 v[128:129], v169 offset:4704
	ds_read_b64_tr_b16 v[130:131], v169 offset:7008
	s_waitcnt vmcnt(15)
	ds_write_b128 v241, v[56:59]
	s_waitcnt vmcnt(14)
	ds_write_b128 v242, v[60:63]
	s_waitcnt vmcnt(13)
	ds_write_b128 v243, v[88:91]
	s_waitcnt vmcnt(12)
	ds_write_b128 v244, v[96:99]
	v_mfma_f32_16x16x32_bf16 v[56:59], v[48:51], v[4:7], 0
	v_mfma_f32_16x16x32_bf16 v[60:63], v[16:19], v[4:7], 0
	v_mfma_f32_16x16x32_bf16 v[16:19], v[16:19], v[12:15], 0
	v_mfma_f32_16x16x32_bf16 v[56:59], v[52:55], v[8:11], v[56:59]
	v_mfma_f32_16x16x32_bf16 v[60:63], v[20:23], v[8:11], v[60:63]
	v_mfma_f32_16x16x32_bf16 v[16:19], v[20:23], v[0:3], v[16:19]
	v_sub_u32_e32 v20, v195, v147
	v_add_u32_e32 v23, 1, v20
	s_nop 3
	v_mfma_f32_16x16x32_bf16 v[48:51], v[48:51], v[12:15], 0
	v_cmp_gt_u32_e64 s[0:1], v23, v146
	v_cmp_gt_u32_e32 vcc, v20, v146
	s_nop 0
	v_cndmask_b32_e64 v57, v57, v246, s[0:1]
	s_nop 0
	v_cndmask_b32_e32 v56, v56, v246, vcc
	v_max_f32_e32 v22, 0xf149f2ca, v56
	v_mfma_f32_16x16x32_bf16 v[48:51], v[52:55], v[0:3], v[48:51]
	v_max_f32_e32 v22, v22, v57
	v_add_u32_e32 v23, 2, v20
	v_add_u32_e32 v52, 3, v20
	v_cmp_gt_u32_e64 s[22:23], v23, v146
	v_cmp_gt_u32_e64 s[24:25], v52, v146
	v_sub_u32_e32 v21, v195, v148
	v_cndmask_b32_e64 v58, v58, v246, s[22:23]
	v_cndmask_b32_e64 v59, v59, v246, s[24:25]
	v_max3_f32 v22, v22, v58, v59
	v_add_u32_e32 v23, 16, v20
	v_add_u32_e32 v52, 17, v20
	v_cmp_gt_u32_e64 s[26:27], v23, v146
	v_cmp_gt_u32_e64 s[28:29], v52, v146
	v_cmp_gt_u32_e64 s[38:39], v21, v145
	v_cndmask_b32_e64 v60, v60, v246, s[26:27]
	v_cndmask_b32_e64 v61, v61, v246, s[28:29]
	v_max3_f32 v22, v22, v60, v61
	v_add_u32_e32 v23, 18, v20
	v_add_u32_e32 v20, 19, v20
	v_cmp_gt_u32_e64 s[30:31], v23, v146
	v_cmp_gt_u32_e64 s[34:35], v20, v146
	v_add_u32_e32 v52, 3, v21
	v_cndmask_b32_e64 v62, v62, v246, s[30:31]
	v_cndmask_b32_e64 v63, v63, v246, s[34:35]
	v_max3_f32 v20, v22, v62, v63
	v_add_u32_e32 v23, 1, v21
	v_cmp_gt_u32_e64 s[40:41], v23, v145
	v_cndmask_b32_e64 v48, v48, v246, s[38:39]
	v_max_f32_e32 v22, 0xf149f2ca, v48
	v_cndmask_b32_e64 v49, v49, v246, s[40:41]
	v_max_f32_e32 v22, v22, v49
	v_add_u32_e32 v23, 2, v21
	v_cmp_gt_u32_e64 s[42:43], v23, v145
	v_cmp_gt_u32_e64 s[44:45], v52, v145
	s_nop 0
	v_cndmask_b32_e64 v50, v50, v246, s[42:43]
	v_cndmask_b32_e64 v51, v51, v246, s[44:45]
	v_max3_f32 v22, v22, v50, v51
	v_add_u32_e32 v23, 16, v21
	v_add_u32_e32 v52, 17, v21
	v_cmp_gt_u32_e64 s[46:47], v23, v145
	v_cmp_gt_u32_e64 s[48:49], v52, v145
	s_nop 0
	v_cndmask_b32_e64 v16, v16, v246, s[46:47]
	v_cndmask_b32_e64 v17, v17, v246, s[48:49]
	v_max3_f32 v22, v22, v16, v17
	v_add_u32_e32 v23, 18, v21
	v_add_u32_e32 v21, 19, v21
	v_cmp_gt_u32_e64 s[50:51], v23, v145
	v_cmp_gt_u32_e64 s[52:53], v21, v145
	s_nop 0
	v_cndmask_b32_e64 v18, v18, v246, s[50:51]
	v_cndmask_b32_e64 v19, v19, v246, s[52:53]
	v_max3_f32 v21, v22, v18, v19
	v_mov_b32_e32 v22, v20
	s_nop 1
	v_permlane32_swap_b32_e32 v22, v20
	v_max_f32_e32 v20, v20, v22
	v_mov_b32_e32 v22, v21
	s_nop 1
	v_permlane32_swap_b32_e32 v22, v21
	v_max_f32_e32 v21, v21, v22
	v_mov_b32_e32 v22, v20
	s_nop 1
	v_permlane16_swap_b32_e32 v22, v20
	v_max3_f32 v149, v175, v20, v22
	v_sub_f32_e32 v20, v175, v149
	v_exp_f32_e32 v88, v20
	v_sub_f32_e32 v20, v56, v149
	v_sub_f32_e32 v56, v61, v149
	v_exp_f32_e32 v56, v56
	v_exp_f32_e32 v20, v20
	v_sub_f32_e32 v23, v57, v149
	v_exp_f32_e32 v23, v23
	v_sub_f32_e32 v53, v58, v149
	v_cndmask_b32_e64 v58, v56, 0, s[28:29]
	v_sub_f32_e32 v56, v62, v149
	v_mov_b32_e32 v22, v21
	v_exp_f32_e32 v53, v53
	v_sub_f32_e32 v54, v59, v149
	v_exp_f32_e32 v56, v56
	v_permlane16_swap_b32_e32 v22, v21
	v_exp_f32_e32 v54, v54
	v_sub_f32_e32 v55, v60, v149
	v_exp_f32_e32 v55, v55
	v_max_f32_e32 v21, v21, v22
	v_add_f32_e32 v22, 0, v20
	v_add_f32_e32 v22, v23, v22
	v_cndmask_b32_e64 v59, v56, 0, s[30:31]
	v_sub_f32_e32 v56, v63, v149
	v_add_f32_e32 v22, v53, v22
	v_exp_f32_e32 v56, v56
	v_add_f32_e32 v22, v54, v22
	v_add_f32_e32 v22, v55, v22
	v_add_f32_e32 v22, v58, v22
	v_max_f32_e32 v151, v181, v21
	v_add_f32_e32 v22, v59, v22
	v_cndmask_b32_e64 v60, v56, 0, s[34:35]
	v_cvt_pk_bf16_f32 v56, v20, v23
	v_sub_f32_e32 v20, v181, v151
	v_add_f32_e32 v150, v60, v22
	v_cvt_pk_bf16_f32 v59, v59, v60
	v_exp_f32_e32 v60, v20
	v_sub_f32_e32 v20, v48, v151
	v_exp_f32_e32 v20, v20
	v_sub_f32_e32 v22, v49, v151
	v_exp_f32_e32 v22, v22
	v_sub_f32_e32 v23, v50, v151
	v_exp_f32_e32 v23, v23
	v_sub_f32_e32 v48, v51, v151
	v_exp_f32_e32 v48, v48
	v_sub_f32_e32 v16, v16, v151
	v_exp_f32_e32 v16, v16
	v_sub_f32_e32 v17, v17, v151
	v_add_f32_e32 v21, 0, v20
	v_exp_f32_e32 v17, v17
	v_add_f32_e32 v21, v22, v21
	v_add_f32_e32 v21, v23, v21
	v_add_f32_e32 v21, v48, v21
	v_cndmask_b32_e64 v49, v16, 0, s[46:47]
	v_add_f32_e32 v16, v49, v21
	v_cndmask_b32_e64 v21, v17, 0, s[48:49]
	v_sub_f32_e32 v17, v18, v151
	v_exp_f32_e32 v17, v17
	v_add_f32_e32 v16, v21, v16
	v_cvt_pk_bf16_f32 v18, v49, v21
	v_cvt_pk_bf16_f32 v57, v53, v54
	v_cndmask_b32_e64 v50, v17, 0, s[50:51]
	v_sub_f32_e32 v17, v19, v151
	v_exp_f32_e32 v17, v17
	v_add_f32_e32 v16, v50, v16
	v_cvt_pk_bf16_f32 v58, v55, v58
	v_fmac_f32_e32 v150, v176, v88
	v_cndmask_b32_e64 v19, v17, 0, s[52:53]
	v_add_f32_e32 v175, v19, v16
	v_cvt_pk_bf16_f32 v16, v20, v22
	v_cvt_pk_bf16_f32 v17, v23, v48
	v_cvt_pk_bf16_f32 v19, v50, v19
	v_pk_mul_f32 v[50:51], v[86:87], v[60:61] op_sel_hi:[1,0]
	v_pk_mul_f32 v[48:49], v[84:85], v[60:61] op_sel_hi:[1,0]
	v_pk_mul_f32 v[22:23], v[82:83], v[88:89] op_sel_hi:[1,0]
	v_pk_mul_f32 v[20:21], v[80:81], v[88:89] op_sel_hi:[1,0]
	s_waitcnt lgkmcnt(10)
	v_mfma_f32_16x16x32_bf16 v[52:55], v[140:143], v[16:19], v[48:51]
	v_fmac_f32_e32 v175, v183, v60
	s_nop 1
	v_pk_mul_f32 v[50:51], v[106:107], v[88:89] op_sel_hi:[1,0]
	v_pk_mul_f32 v[48:49], v[104:105], v[88:89] op_sel_hi:[1,0]
	v_mfma_f32_16x16x32_bf16 v[20:23], v[140:143], v[56:59], v[20:23]
	s_waitcnt lgkmcnt(8)
	v_mfma_f32_16x16x32_bf16 v[104:107], v[136:139], v[56:59], v[48:51]
	s_nop 2
	v_mul_f32_e64 v50, v110, v60
	v_mul_f32_e64 v51, v111, v60
	v_pk_mul_f32 v[48:49], v[108:109], v[60:61] op_sel_hi:[1,0]
	s_nop 1
	v_mfma_f32_16x16x32_bf16 v[108:111], v[136:139], v[16:19], v[48:51]
	s_nop 2
	v_mul_f32_e64 v50, v114, v88
	v_mul_f32_e64 v51, v115, v88
	v_pk_mul_f32 v[48:49], v[112:113], v[88:89] op_sel_hi:[1,0]
	s_waitcnt lgkmcnt(6)
	s_nop 0
	v_mfma_f32_16x16x32_bf16 v[112:115], v[132:135], v[56:59], v[48:51]
	s_nop 2
	v_mul_f32_e64 v50, v118, v60
	v_mul_f32_e64 v51, v119, v60
	v_pk_mul_f32 v[48:49], v[116:117], v[60:61] op_sel_hi:[1,0]
	s_nop 1
	v_mfma_f32_16x16x32_bf16 v[116:119], v[132:135], v[16:19], v[48:51]
	s_nop 2
	v_mul_f32_e64 v50, v122, v88
	v_mul_f32_e64 v51, v123, v88
	v_pk_mul_f32 v[48:49], v[120:121], v[88:89] op_sel_hi:[1,0]
	s_waitcnt lgkmcnt(4)
	s_nop 0
	v_mfma_f32_16x16x32_bf16 v[120:123], v[128:131], v[56:59], v[48:51]
	v_add_u32_e32 v56, 0xffffff00, v206
	v_add_u32_e32 v56, s76, v56
	s_nop 0
	v_pk_mul_f32 v[50:51], v[126:127], v[60:61] op_sel_hi:[1,0]
	v_pk_mul_f32 v[48:49], v[124:125], v[60:61] op_sel_hi:[1,0]
	s_nop 1
	v_mfma_f32_16x16x32_bf16 v[124:127], v[128:131], v[16:19], v[48:51]
	v_add_u32_e32 v16, 0xffffff00, v204
	v_add_u32_e32 v16, s76, v16
	s_nop 0
	v_add_u32_e32 v48, 0xffffff00, v205
	v_add_u32_e32 v48, s76, v48
	v_med3_i32 v16, v16, 0, s75
	v_med3_i32 v48, v48, 0, s75
	v_med3_i32 v56, v56, 0, s75
	v_lshl_add_u32 v56, v56, 9, v152
	global_load_dwordx4 v[88:91], v56, s[98:99]
	v_add_u32_e32 v56, 0xffffff00, v207
	v_add_u32_e32 v56, s76, v56
	v_med3_i32 v56, v56, 0, s75
	v_lshl_add_u32 v56, v56, 9, v152
	global_load_dwordx4 v[96:99], v56, s[98:99]
	v_add_u32_e32 v56, s76, v208
	v_lshl_add_u32 v16, v16, 9, v152
	v_lshl_add_u32 v48, v48, 9, v152
	v_med3_i32 v56, v56, 0, s75
	v_lshl_add_u32 v56, v56, 9, v158
	global_load_dwordx4 v[16:19], v16, s[98:99]
	s_nop 0
	global_load_dwordx4 v[48:51], v48, s[98:99]
	s_nop 0
	global_load_dwordx4 v[84:87], v56, s[100:101]
	global_load_dwordx4 v[80:83], v56, s[100:101] offset:64
	v_or_b32_e32 v56, 0xffffff40, v209
	v_add_u32_e32 v56, s76, v56
	v_med3_i32 v56, v56, 0, s75
	v_lshl_add_u32 v56, v56, 9, v158
	global_load_dwordx4 v[60:63], v56, s[100:101]
	s_nop 0
	global_load_dwordx4 v[56:59], v56, s[100:101] offset:64
	ds_read_b64_tr_b16 v[142:143], v169 offset:2304
	ds_read_b64_tr_b16 v[140:141], v169
	ds_read_b64_tr_b16 v[136:137], v169 offset:32
	ds_read_b64_tr_b16 v[138:139], v169 offset:2336
	ds_read_b64_tr_b16 v[132:133], v169 offset:64
	ds_read_b64_tr_b16 v[134:135], v169 offset:2368
	ds_read_b64_tr_b16 v[128:129], v169 offset:96
	ds_read_b64_tr_b16 v[130:131], v169 offset:2400
	s_waitcnt vmcnt(15)
	ds_write_b128 v241, v[28:31] offset:4608
	s_waitcnt vmcnt(14)
	ds_write_b128 v242, v[44:47] offset:4608
	s_waitcnt vmcnt(13)
	ds_write_b128 v243, v[92:95] offset:4608
	s_waitcnt vmcnt(12)
	ds_write_b128 v244, v[100:103] offset:4608
	v_mfma_f32_16x16x32_bf16 v[28:31], v[76:79], v[4:7], 0
	v_mfma_f32_16x16x32_bf16 v[44:47], v[40:43], v[4:7], 0
	v_mfma_f32_16x16x32_bf16 v[40:43], v[40:43], v[12:15], 0
	v_mfma_f32_16x16x32_bf16 v[28:31], v[64:67], v[8:11], v[28:31]
	v_mfma_f32_16x16x32_bf16 v[44:47], v[32:35], v[8:11], v[44:47]
	v_mfma_f32_16x16x32_bf16 v[32:35], v[32:35], v[0:3], v[40:43]
	s_nop 4
	v_sub_u32_e32 v40, v210, v147
	v_mfma_f32_16x16x32_bf16 v[76:79], v[76:79], v[12:15], 0
	v_add_u32_e32 v43, 1, v40
	v_cmp_gt_u32_e64 s[0:1], v43, v146
	v_cmp_gt_u32_e32 vcc, v40, v146
	s_nop 0
	v_cndmask_b32_e64 v29, v29, v246, s[0:1]
	s_nop 0
	v_cndmask_b32_e32 v28, v28, v246, vcc
	v_max_f32_e32 v42, 0xf149f2ca, v28
	v_mfma_f32_16x16x32_bf16 v[64:67], v[64:67], v[0:3], v[76:79]
	v_max_f32_e32 v42, v42, v29
	v_add_u32_e32 v43, 2, v40
	v_cmp_gt_u32_e64 s[22:23], v43, v146
	v_add_u32_e32 v76, 3, v40
	v_cmp_gt_u32_e64 s[24:25], v76, v146
	v_cndmask_b32_e64 v30, v30, v246, s[22:23]
	v_sub_u32_e32 v41, v210, v148
	v_cndmask_b32_e64 v31, v31, v246, s[24:25]
	v_max3_f32 v42, v42, v30, v31
	v_add_u32_e32 v43, 16, v40
	v_add_u32_e32 v76, 17, v40
	v_cmp_gt_u32_e64 s[26:27], v43, v146
	v_cmp_gt_u32_e64 s[28:29], v76, v146
	v_cmp_gt_u32_e64 s[38:39], v41, v145
	v_cndmask_b32_e64 v44, v44, v246, s[26:27]
	v_cndmask_b32_e64 v45, v45, v246, s[28:29]
	v_max3_f32 v42, v42, v44, v45
	v_add_u32_e32 v43, 18, v40
	v_add_u32_e32 v40, 19, v40
	v_cmp_gt_u32_e64 s[30:31], v43, v146
	v_cmp_gt_u32_e64 s[34:35], v40, v146
	v_add_u32_e32 v76, 3, v41
	v_cndmask_b32_e64 v46, v46, v246, s[30:31]
	v_cndmask_b32_e64 v47, v47, v246, s[34:35]
	v_max3_f32 v40, v42, v46, v47
	v_add_u32_e32 v43, 1, v41
	v_cmp_gt_u32_e64 s[40:41], v43, v145
	v_cndmask_b32_e64 v64, v64, v246, s[38:39]
	v_max_f32_e32 v42, 0xf149f2ca, v64
	v_cndmask_b32_e64 v65, v65, v246, s[40:41]
	v_max_f32_e32 v42, v42, v65
	v_add_u32_e32 v43, 2, v41
	v_cmp_gt_u32_e64 s[42:43], v43, v145
	v_cmp_gt_u32_e64 s[44:45], v76, v145
	s_nop 0
	v_cndmask_b32_e64 v66, v66, v246, s[42:43]
	v_cndmask_b32_e64 v67, v67, v246, s[44:45]
	v_max3_f32 v42, v42, v66, v67
	v_add_u32_e32 v43, 16, v41
	v_add_u32_e32 v76, 17, v41
	v_cmp_gt_u32_e64 s[46:47], v43, v145
	v_cmp_gt_u32_e64 s[48:49], v76, v145
	s_nop 0
	v_cndmask_b32_e64 v32, v32, v246, s[46:47]
	v_cndmask_b32_e64 v33, v33, v246, s[48:49]
	v_max3_f32 v42, v42, v32, v33
	v_add_u32_e32 v43, 18, v41
	v_add_u32_e32 v41, 19, v41
	v_cmp_gt_u32_e64 s[50:51], v43, v145
	v_cmp_gt_u32_e64 s[52:53], v41, v145
	s_nop 0
	v_cndmask_b32_e64 v34, v34, v246, s[50:51]
	v_cndmask_b32_e64 v35, v35, v246, s[52:53]
	v_max3_f32 v41, v42, v34, v35
	v_mov_b32_e32 v42, v40
	s_nop 1
	v_permlane32_swap_b32_e32 v42, v40
	v_max_f32_e32 v40, v40, v42
	v_mov_b32_e32 v42, v41
	s_nop 1
	v_permlane32_swap_b32_e32 v42, v41
	v_max_f32_e32 v41, v41, v42
	v_mov_b32_e32 v42, v40
	s_nop 1
	v_permlane16_swap_b32_e32 v42, v40
	v_max3_f32 v176, v149, v40, v42
	v_sub_f32_e32 v28, v28, v176
	v_mov_b32_e32 v42, v41
	v_exp_f32_e32 v28, v28
	v_sub_f32_e32 v29, v29, v176
	v_permlane16_swap_b32_e32 v42, v41
	v_exp_f32_e32 v29, v29
	v_sub_f32_e32 v30, v30, v176
	v_exp_f32_e32 v30, v30
	v_sub_f32_e32 v31, v31, v176
	v_max_f32_e32 v41, v41, v42
	v_exp_f32_e32 v31, v31
	v_sub_f32_e32 v42, v44, v176
	v_sub_f32_e32 v40, v149, v176
	v_exp_f32_e32 v42, v42
	v_sub_f32_e32 v43, v45, v176
	v_exp_f32_e32 v76, v40
	v_add_f32_e32 v40, 0, v28
	v_exp_f32_e32 v43, v43
	v_sub_f32_e32 v44, v46, v176
	v_add_f32_e32 v40, v29, v40
	v_exp_f32_e32 v44, v44
	v_sub_f32_e32 v45, v47, v176
	v_add_f32_e32 v40, v30, v40
	v_exp_f32_e32 v45, v45
	v_add_f32_e32 v40, v31, v40
	v_add_f32_e32 v40, v42, v40
	v_add_f32_e32 v40, v43, v40
	v_add_f32_e32 v40, v44, v40
	v_add_f32_e32 v149, v45, v40
	v_fmac_f32_e32 v149, v150, v76
	v_max_f32_e32 v150, v151, v41
	v_sub_f32_e32 v40, v151, v150
	v_cvt_pk_bf16_f32 v28, v28, v29
	v_cvt_pk_bf16_f32 v29, v30, v31
	v_cvt_pk_bf16_f32 v31, v44, v45
	v_exp_f32_e32 v44, v40
	v_sub_f32_e32 v40, v64, v150
	v_cvt_pk_bf16_f32 v30, v42, v43
	v_exp_f32_e32 v40, v40
	v_sub_f32_e32 v42, v65, v150
	v_exp_f32_e32 v42, v42
	v_sub_f32_e32 v43, v66, v150
	v_exp_f32_e32 v43, v43
	v_sub_f32_e32 v45, v67, v150
	v_exp_f32_e32 v45, v45
	v_sub_f32_e32 v32, v32, v150
	v_exp_f32_e32 v32, v32
	v_sub_f32_e32 v33, v33, v150
	v_add_f32_e32 v41, 0, v40
	v_exp_f32_e32 v33, v33
	v_add_f32_e32 v41, v42, v41
	v_add_f32_e32 v41, v43, v41
	v_add_f32_e32 v41, v45, v41
	v_cndmask_b32_e64 v46, v32, 0, s[46:47]
	v_add_f32_e32 v32, v46, v41
	v_cndmask_b32_e64 v41, v33, 0, s[48:49]
	v_sub_f32_e32 v33, v34, v150
	v_exp_f32_e32 v33, v33
	v_add_f32_e32 v32, v41, v32
	v_pk_mul_f32 v[22:23], v[22:23], v[76:77] op_sel_hi:[1,0]
	v_pk_mul_f32 v[20:21], v[20:21], v[76:77] op_sel_hi:[1,0]
	v_cndmask_b32_e64 v47, v33, 0, s[50:51]
	v_sub_f32_e32 v33, v35, v150
	v_exp_f32_e32 v33, v33
	v_add_f32_e32 v32, v47, v32
	v_cvt_pk_bf16_f32 v34, v46, v41
	v_cndmask_b32_e64 v35, v33, 0, s[52:53]
	v_add_f32_e32 v151, v35, v32
	v_cvt_pk_bf16_f32 v32, v40, v42
	v_cvt_pk_bf16_f32 v33, v43, v45
	v_cvt_pk_bf16_f32 v35, v47, v35
	s_waitcnt lgkmcnt(10)
	v_mfma_f32_16x16x32_bf16 v[40:43], v[140:143], v[28:31], v[20:23]
	v_fmac_f32_e32 v151, v175, v44
	s_nop 1
	v_pk_mul_f32 v[22:23], v[54:55], v[44:45] op_sel_hi:[1,0]
	v_pk_mul_f32 v[20:21], v[52:53], v[44:45] op_sel_hi:[1,0]
	s_nop 1
	v_mfma_f32_16x16x32_bf16 v[92:95], v[140:143], v[32:35], v[20:23]
	s_nop 2
	v_mul_f32_e64 v22, v106, v76
	v_mul_f32_e64 v23, v107, v76
	v_pk_mul_f32 v[20:21], v[104:105], v[76:77] op_sel_hi:[1,0]
	s_waitcnt lgkmcnt(8)
	s_nop 0
	v_mfma_f32_16x16x32_bf16 v[104:107], v[136:139], v[28:31], v[20:23]
	s_nop 2
	v_mul_f32_e64 v22, v110, v44
	v_mul_f32_e64 v23, v111, v44
	v_pk_mul_f32 v[20:21], v[108:109], v[44:45] op_sel_hi:[1,0]
	s_nop 1
	v_mfma_f32_16x16x32_bf16 v[108:111], v[136:139], v[32:35], v[20:23]
	s_nop 2
	v_mul_f32_e64 v22, v114, v76
	v_mul_f32_e64 v23, v115, v76
	v_pk_mul_f32 v[20:21], v[112:113], v[76:77] op_sel_hi:[1,0]
	s_waitcnt lgkmcnt(6)
	s_nop 0
	v_mfma_f32_16x16x32_bf16 v[112:115], v[132:135], v[28:31], v[20:23]
	s_nop 2
	v_mul_f32_e64 v22, v118, v44
	v_mul_f32_e64 v23, v119, v44
	v_pk_mul_f32 v[20:21], v[116:117], v[44:45] op_sel_hi:[1,0]
	s_nop 1
	v_mfma_f32_16x16x32_bf16 v[116:119], v[132:135], v[32:35], v[20:23]
	s_nop 2
	v_mul_f32_e64 v22, v122, v76
	v_mul_f32_e64 v23, v123, v76
	v_pk_mul_f32 v[20:21], v[120:121], v[76:77] op_sel_hi:[1,0]
	s_waitcnt lgkmcnt(4)
	s_nop 0
	v_mfma_f32_16x16x32_bf16 v[120:123], v[128:131], v[28:31], v[20:23]
	s_nop 2
	v_mul_f32_e64 v22, v126, v44
	v_mul_f32_e64 v23, v127, v44
	v_pk_mul_f32 v[20:21], v[124:125], v[44:45] op_sel_hi:[1,0]
	s_nop 1
	v_mfma_f32_16x16x32_bf16 v[124:127], v[128:131], v[32:35], v[20:23]
	s_nop 2
	v_add_u32_e32 v20, 0xffffff80, v204
	v_add_u32_e32 v20, s76, v20
	v_med3_i32 v20, v20, 0, s75
	v_lshl_add_u32 v20, v20, 9, v152
	global_load_dwordx4 v[32:35], v20, s[98:99]
	v_add_u32_e32 v20, 0xffffff80, v205
	v_add_u32_e32 v20, s76, v20
	v_med3_i32 v20, v20, 0, s75
	v_lshl_add_u32 v20, v20, 9, v152
	global_load_dwordx4 v[64:67], v20, s[98:99]
	v_add_u32_e32 v20, 0xffffff80, v206
	v_add_u32_e32 v20, s76, v20
	v_med3_i32 v20, v20, 0, s75
	v_lshl_add_u32 v20, v20, 9, v152
	global_load_dwordx4 v[76:79], v20, s[98:99]
	v_add_u32_e32 v20, 0xffffff80, v207
	v_add_u32_e32 v20, s76, v20
	v_med3_i32 v20, v20, 0, s75
	v_lshl_add_u32 v20, v20, 9, v152
	global_load_dwordx4 v[100:103], v20, s[98:99]
	v_or_b32_e32 v20, 0xffffff80, v209
	v_add_u32_e32 v20, s76, v20
	v_med3_i32 v20, v20, 0, s75
	v_lshl_add_u32 v20, v20, 9, v158
	global_load_dwordx4 v[52:55], v20, s[100:101]
	global_load_dwordx4 v[44:47], v20, s[100:101] offset:64
	v_add_u32_e32 v20, s76, v211
	v_med3_i32 v20, v20, 0, s75
	v_lshl_add_u32 v20, v20, 9, v158
	global_load_dwordx4 v[28:31], v20, s[100:101]
	s_nop 0
	global_load_dwordx4 v[20:23], v20, s[100:101] offset:64
	ds_read_b64_tr_b16 v[142:143], v169 offset:6912
	ds_read_b64_tr_b16 v[140:141], v169 offset:4608
	ds_read_b64_tr_b16 v[136:137], v169 offset:4640
	ds_read_b64_tr_b16 v[138:139], v169 offset:6944
	ds_read_b64_tr_b16 v[132:133], v169 offset:4672
	ds_read_b64_tr_b16 v[134:135], v169 offset:6976
	ds_read_b64_tr_b16 v[128:129], v169 offset:4704
	ds_read_b64_tr_b16 v[130:131], v169 offset:7008
	s_waitcnt vmcnt(13)
	ds_write_b128 v241, v[16:19]
	s_waitcnt vmcnt(12)
	ds_write_b128 v242, v[48:51]
	ds_write_b128 v243, v[88:91]
	ds_write_b128 v244, v[96:99]
	v_mfma_f32_16x16x32_bf16 v[16:19], v[72:75], v[4:7], 0
	v_mfma_f32_16x16x32_bf16 v[48:51], v[36:39], v[4:7], 0
	v_mfma_f32_16x16x32_bf16 v[36:39], v[36:39], v[12:15], 0
	v_mfma_f32_16x16x32_bf16 v[16:19], v[68:71], v[8:11], v[16:19]
	v_mfma_f32_16x16x32_bf16 v[48:51], v[24:27], v[8:11], v[48:51]
	v_mfma_f32_16x16x32_bf16 v[24:27], v[24:27], v[0:3], v[36:39]
	s_nop 4
	v_sub_u32_e32 v36, v212, v147
	v_mfma_f32_16x16x32_bf16 v[72:75], v[72:75], v[12:15], 0
	v_add_u32_e32 v39, 1, v36
	v_cmp_gt_u32_e64 s[0:1], v39, v146
	v_cmp_gt_u32_e32 vcc, v36, v146
	s_nop 0
	v_cndmask_b32_e64 v17, v17, v246, s[0:1]
	s_nop 0
	v_cndmask_b32_e32 v16, v16, v246, vcc
	v_max_f32_e32 v38, 0xf149f2ca, v16
	v_mfma_f32_16x16x32_bf16 v[68:71], v[68:71], v[0:3], v[72:75]
	v_max_f32_e32 v38, v38, v17
	v_add_u32_e32 v39, 2, v36
	v_cmp_gt_u32_e64 s[22:23], v39, v146
	v_add_u32_e32 v72, 3, v36
	v_cmp_gt_u32_e64 s[24:25], v72, v146
	v_cndmask_b32_e64 v18, v18, v246, s[22:23]
	v_sub_u32_e32 v37, v212, v148
	v_cndmask_b32_e64 v19, v19, v246, s[24:25]
	v_max3_f32 v38, v38, v18, v19
	v_add_u32_e32 v39, 16, v36
	v_add_u32_e32 v72, 17, v36
	v_cmp_gt_u32_e64 s[26:27], v39, v146
	v_cmp_gt_u32_e64 s[28:29], v72, v146
	v_cmp_gt_u32_e64 s[38:39], v37, v145
	v_cndmask_b32_e64 v48, v48, v246, s[26:27]
	v_cndmask_b32_e64 v49, v49, v246, s[28:29]
	v_max3_f32 v38, v38, v48, v49
	v_add_u32_e32 v39, 18, v36
	v_add_u32_e32 v36, 19, v36
	v_cmp_gt_u32_e64 s[30:31], v39, v146
	v_cmp_gt_u32_e64 s[34:35], v36, v146
	v_add_u32_e32 v72, 3, v37
	v_cndmask_b32_e64 v50, v50, v246, s[30:31]
	v_cndmask_b32_e64 v51, v51, v246, s[34:35]
	v_max3_f32 v36, v38, v50, v51
	v_add_u32_e32 v39, 1, v37
	v_cmp_gt_u32_e64 s[40:41], v39, v145
	v_cndmask_b32_e64 v68, v68, v246, s[38:39]
	v_max_f32_e32 v38, 0xf149f2ca, v68
	v_cndmask_b32_e64 v69, v69, v246, s[40:41]
	v_max_f32_e32 v38, v38, v69
	v_add_u32_e32 v39, 2, v37
	v_cmp_gt_u32_e64 s[42:43], v39, v145
	v_cmp_gt_u32_e64 s[44:45], v72, v145
	s_nop 0
	v_cndmask_b32_e64 v70, v70, v246, s[42:43]
	v_cndmask_b32_e64 v71, v71, v246, s[44:45]
	v_max3_f32 v38, v38, v70, v71
	v_add_u32_e32 v39, 16, v37
	v_add_u32_e32 v72, 17, v37
	v_cmp_gt_u32_e64 s[46:47], v39, v145
	v_cmp_gt_u32_e64 s[48:49], v72, v145
	s_nop 0
	v_cndmask_b32_e64 v24, v24, v246, s[46:47]
	v_cndmask_b32_e64 v25, v25, v246, s[48:49]
	v_max3_f32 v38, v38, v24, v25
	v_add_u32_e32 v39, 18, v37
	v_add_u32_e32 v37, 19, v37
	v_cmp_gt_u32_e64 s[50:51], v39, v145
	v_cmp_gt_u32_e64 s[52:53], v37, v145
	s_nop 0
	v_cndmask_b32_e64 v26, v26, v246, s[50:51]
	v_cndmask_b32_e64 v27, v27, v246, s[52:53]
	v_max3_f32 v37, v38, v26, v27
	v_mov_b32_e32 v38, v36
	s_nop 1
	v_permlane32_swap_b32_e32 v38, v36
	v_max_f32_e32 v36, v36, v38
	v_mov_b32_e32 v38, v37
	s_nop 1
	v_permlane32_swap_b32_e32 v38, v37
	v_max_f32_e32 v37, v37, v38
	v_mov_b32_e32 v38, v36
	s_nop 1
	v_permlane16_swap_b32_e32 v38, v36
	v_max3_f32 v145, v176, v36, v38
	v_sub_f32_e32 v16, v16, v145
	v_mov_b32_e32 v38, v37
	v_exp_f32_e32 v16, v16
	v_sub_f32_e32 v17, v17, v145
	v_permlane16_swap_b32_e32 v38, v37
	v_exp_f32_e32 v17, v17
	v_sub_f32_e32 v18, v18, v145
	v_exp_f32_e32 v18, v18
	v_sub_f32_e32 v19, v19, v145
	v_max_f32_e32 v37, v37, v38
	v_exp_f32_e32 v19, v19
	v_sub_f32_e32 v38, v48, v145
	v_sub_f32_e32 v36, v176, v145
	v_exp_f32_e32 v38, v38
	v_sub_f32_e32 v39, v49, v145
	v_exp_f32_e32 v88, v36
	v_add_f32_e32 v36, 0, v16
	v_exp_f32_e32 v39, v39
	v_sub_f32_e32 v48, v50, v145
	v_add_f32_e32 v36, v17, v36
	v_exp_f32_e32 v48, v48
	v_sub_f32_e32 v49, v51, v145
	v_add_f32_e32 v36, v18, v36
	v_exp_f32_e32 v49, v49
	v_add_f32_e32 v36, v19, v36
	v_add_f32_e32 v36, v38, v36
	v_add_f32_e32 v36, v39, v36
	v_add_f32_e32 v36, v48, v36
	v_max_f32_e32 v147, v150, v37
	v_add_f32_e32 v146, v49, v36
	v_sub_f32_e32 v36, v150, v147
	v_cvt_pk_bf16_f32 v16, v16, v17
	v_cvt_pk_bf16_f32 v17, v18, v19
	v_cvt_pk_bf16_f32 v19, v48, v49
	v_exp_f32_e32 v48, v36
	v_sub_f32_e32 v36, v68, v147
	v_cvt_pk_bf16_f32 v18, v38, v39
	v_exp_f32_e32 v36, v36
	v_sub_f32_e32 v38, v69, v147
	v_exp_f32_e32 v38, v38
	v_sub_f32_e32 v39, v70, v147
	v_exp_f32_e32 v39, v39
	v_sub_f32_e32 v49, v71, v147
	v_exp_f32_e32 v49, v49
	v_sub_f32_e32 v24, v24, v147
	v_exp_f32_e32 v24, v24
	v_sub_f32_e32 v25, v25, v147
	v_add_f32_e32 v37, 0, v36
	v_exp_f32_e32 v25, v25
	v_add_f32_e32 v37, v38, v37
	v_add_f32_e32 v37, v39, v37
	v_add_f32_e32 v37, v49, v37
	v_cndmask_b32_e64 v50, v24, 0, s[46:47]
	v_add_f32_e32 v24, v50, v37
	v_cndmask_b32_e64 v37, v25, 0, s[48:49]
	v_sub_f32_e32 v25, v26, v147
	v_exp_f32_e32 v25, v25
	v_add_f32_e32 v24, v37, v24
	v_cvt_pk_bf16_f32 v26, v50, v37
	v_cmp_lt_i32_e32 vcc, -1, v184
	v_cndmask_b32_e64 v51, v25, 0, s[50:51]
	v_sub_f32_e32 v25, v27, v147
	v_exp_f32_e32 v25, v25
	v_add_f32_e32 v24, v51, v24
	v_fmac_f32_e32 v146, v149, v88
	s_add_i32 s0, s76, 0xffffff00
	v_cndmask_b32_e64 v27, v25, 0, s[52:53]
	v_add_f32_e32 v183, v27, v24
	v_cvt_pk_bf16_f32 v24, v36, v38
	v_cvt_pk_bf16_f32 v25, v39, v49
	v_cvt_pk_bf16_f32 v27, v51, v27
	v_pk_mul_f32 v[38:39], v[42:43], v[88:89] op_sel_hi:[1,0]
	v_pk_mul_f32 v[36:37], v[40:41], v[88:89] op_sel_hi:[1,0]
	v_pk_mul_f32 v[42:43], v[94:95], v[48:49] op_sel_hi:[1,0]
	v_pk_mul_f32 v[40:41], v[92:93], v[48:49] op_sel_hi:[1,0]
	s_waitcnt lgkmcnt(10)
	v_mfma_f32_16x16x32_bf16 v[36:39], v[140:143], v[16:19], v[36:39]
	v_fmac_f32_e32 v183, v151, v48
	s_min_i32 s1, s0, 0
	s_sub_i32 s1, 3, s1
	v_mfma_f32_16x16x32_bf16 v[68:71], v[140:143], v[24:27], v[40:43]
	s_ashr_i32 s1, s1, 2
	s_sub_i32 s22, 0x200, s76
	s_sub_i32 s0, s75, s0
	v_pk_mul_f32 v[42:43], v[106:107], v[88:89] op_sel_hi:[1,0]
	v_pk_mul_f32 v[40:41], v[104:105], v[88:89] op_sel_hi:[1,0]
	s_ashr_i32 s0, s0, 2
	s_cmp_lt_i32 s76, 0
	s_waitcnt lgkmcnt(8)
	v_mfma_f32_16x16x32_bf16 v[72:75], v[136:139], v[16:19], v[40:43]
	s_nop 2
	v_mul_f32_e64 v42, v110, v48
	v_mul_f32_e64 v43, v111, v48
	v_pk_mul_f32 v[40:41], v[108:109], v[48:49] op_sel_hi:[1,0]
	s_nop 1
	v_mfma_f32_16x16x32_bf16 v[104:107], v[136:139], v[24:27], v[40:43]
	s_nop 2
	v_mul_f32_e64 v42, v114, v88
	v_mul_f32_e64 v43, v115, v88
	v_pk_mul_f32 v[40:41], v[112:113], v[88:89] op_sel_hi:[1,0]
	s_waitcnt lgkmcnt(6)
	s_nop 0
	v_mfma_f32_16x16x32_bf16 v[108:111], v[132:135], v[16:19], v[40:43]
	s_nop 2
	v_mul_f32_e64 v42, v118, v48
	v_mul_f32_e64 v43, v119, v48
	v_pk_mul_f32 v[40:41], v[116:117], v[48:49] op_sel_hi:[1,0]
	s_nop 1
	v_mfma_f32_16x16x32_bf16 v[112:115], v[132:135], v[24:27], v[40:43]
	s_nop 2
	v_mul_f32_e64 v42, v122, v88
	v_mul_f32_e64 v43, v123, v88
	v_pk_mul_f32 v[40:41], v[120:121], v[88:89] op_sel_hi:[1,0]
	s_waitcnt lgkmcnt(4)
	s_nop 0
	v_mfma_f32_16x16x32_bf16 v[116:119], v[128:131], v[16:19], v[40:43]
	v_mul_f32_e64 v18, v126, v48
	v_mul_f32_e64 v19, v127, v48
	v_pk_mul_f32 v[16:17], v[124:125], v[48:49] op_sel_hi:[1,0]
	s_nop 1
	v_mfma_f32_16x16x32_bf16 v[128:131], v[128:131], v[24:27], v[16:19]
	s_nop 2
	v_min_i32_e32 v16, s75, v184
	v_cndmask_b32_e32 v16, 0, v16, vcc
	v_lshl_add_u32 v16, v16, 9, v152
	global_load_dwordx4 v[88:91], v16, s[98:99]
	v_med3_i32 v16, v185, 0, s75
	v_lshl_add_u32 v16, v16, 9, v152
	global_load_dwordx4 v[92:95], v16, s[98:99]
	v_med3_i32 v16, v186, 0, s75
	v_lshl_add_u32 v16, v16, 9, v152
	global_load_dwordx4 v[120:123], v16, s[98:99]
	v_med3_i32 v16, v188, 0, s75
	v_lshl_add_u32 v16, v16, 9, v152
	global_load_dwordx4 v[124:127], v16, s[98:99]
	v_add_u32_e32 v16, s76, v209
	v_med3_i32 v16, v16, 0, s75
	v_lshl_add_u32 v16, v16, 9, v158
	global_load_dwordx4 v[48:51], v16, s[100:101]
	global_load_dwordx4 v[40:43], v16, s[100:101] offset:64
	v_or_b32_e32 v16, 64, v209
	v_add_u32_e32 v16, s76, v16
	v_med3_i32 v16, v16, 0, s75
	v_lshl_add_u32 v16, v16, 9, v158
	global_load_dwordx4 v[24:27], v16, s[100:101]
	s_nop 0
	global_load_dwordx4 v[16:19], v16, s[100:101] offset:64
	ds_read_b64_tr_b16 v[98:99], v169 offset:2304
	ds_read_b64_tr_b16 v[96:97], v169
	ds_read_b64_tr_b16 v[140:141], v169 offset:32
	ds_read_b64_tr_b16 v[142:143], v169 offset:2336
	ds_read_b64_tr_b16 v[136:137], v169 offset:64
	ds_read_b64_tr_b16 v[138:139], v169 offset:2368
	ds_read_b64_tr_b16 v[132:133], v169 offset:96
	ds_read_b64_tr_b16 v[134:135], v169 offset:2400
	s_waitcnt vmcnt(15)
	ds_write_b128 v241, v[32:35] offset:4608
	s_waitcnt vmcnt(14)
	ds_write_b128 v242, v[64:67] offset:4608
	s_waitcnt vmcnt(13)
	ds_write_b128 v243, v[76:79] offset:4608
	s_waitcnt vmcnt(12)
	ds_write_b128 v244, v[100:103] offset:4608
	v_mfma_f32_16x16x32_bf16 v[64:67], v[60:63], v[4:7], 0
	v_mfma_f32_16x16x32_bf16 v[60:63], v[60:63], v[12:15], 0
	v_mfma_f32_16x16x32_bf16 v[32:35], v[84:87], v[4:7], 0
	v_mfma_f32_16x16x32_bf16 v[64:67], v[56:59], v[8:11], v[64:67]
	v_mfma_f32_16x16x32_bf16 v[56:59], v[56:59], v[0:3], v[60:63]
	s_nop 4
	v_ashrrev_i32_e32 v60, 2, v250
	v_max_i32_e32 v176, s1, v60
	v_add_u32_e32 v60, s22, v251
	v_ashrrev_i32_e32 v60, 2, v60
	v_min3_i32 v60, v60, s0, v247
	v_mfma_f32_16x16x32_bf16 v[32:35], v[80:83], v[8:11], v[32:35]
	v_sub_u32_e32 v175, v60, v176
	v_ashrrev_i32_e32 v60, 2, v249
	v_max_i32_e32 v181, s1, v60
	v_add_u32_e32 v60, s22, v144
	v_sub_u32_e32 v61, v154, v176
	v_ashrrev_i32_e32 v60, 2, v60
	v_mfma_f32_16x16x32_bf16 v[76:79], v[84:87], v[12:15], 0
	v_min3_i32 v60, v60, s0, v247
	v_add_u32_e32 v63, 1, v61
	v_sub_u32_e32 v252, v60, v181
	v_cmp_gt_u32_e64 s[0:1], v63, v175
	v_cmp_gt_u32_e32 vcc, v61, v175
	s_nop 0
	v_cndmask_b32_e64 v33, v33, v246, s[0:1]
	s_nop 0
	v_cndmask_b32_e32 v32, v32, v246, vcc
	v_max_f32_e32 v60, 0xf149f2ca, v32
	v_mfma_f32_16x16x32_bf16 v[76:79], v[80:83], v[0:3], v[76:79]
	v_max_f32_e32 v60, v60, v33
	v_add_u32_e32 v63, 2, v61
	v_add_u32_e32 v80, 3, v61
	v_cmp_gt_u32_e64 s[22:23], v63, v175
	v_cmp_gt_u32_e64 s[24:25], v80, v175
	v_sub_u32_e32 v62, v154, v181
	v_cndmask_b32_e64 v34, v34, v246, s[22:23]
	v_cndmask_b32_e64 v35, v35, v246, s[24:25]
	v_max3_f32 v60, v60, v34, v35
	v_add_u32_e32 v63, 16, v61
	v_add_u32_e32 v80, 17, v61
	v_cmp_gt_u32_e64 s[26:27], v63, v175
	v_cmp_gt_u32_e64 s[28:29], v80, v175
	v_cmp_gt_u32_e64 s[38:39], v62, v252
	v_cndmask_b32_e64 v64, v64, v246, s[26:27]
	v_cndmask_b32_e64 v65, v65, v246, s[28:29]
	v_max3_f32 v60, v60, v64, v65
	v_add_u32_e32 v63, 18, v61
	v_add_u32_e32 v61, 19, v61
	v_cmp_gt_u32_e64 s[30:31], v63, v175
	v_cmp_gt_u32_e64 s[34:35], v61, v175
	v_add_u32_e32 v80, 3, v62
	v_cndmask_b32_e64 v66, v66, v246, s[30:31]
	v_cndmask_b32_e64 v67, v67, v246, s[34:35]
	v_max3_f32 v60, v60, v66, v67
	v_add_u32_e32 v63, 1, v62
	v_cmp_gt_u32_e64 s[40:41], v63, v252
	v_cndmask_b32_e64 v76, v76, v246, s[38:39]
	v_max_f32_e32 v61, 0xf149f2ca, v76
	v_cndmask_b32_e64 v77, v77, v246, s[40:41]
	v_max_f32_e32 v61, v61, v77
	v_add_u32_e32 v63, 2, v62
	v_cmp_gt_u32_e64 s[42:43], v63, v252
	v_cmp_gt_u32_e64 s[44:45], v80, v252
	s_nop 0
	v_cndmask_b32_e64 v78, v78, v246, s[42:43]
	v_cndmask_b32_e64 v79, v79, v246, s[44:45]
	v_max3_f32 v61, v61, v78, v79
	v_add_u32_e32 v63, 16, v62
	v_add_u32_e32 v80, 17, v62
	v_cmp_gt_u32_e64 s[46:47], v63, v252
	v_cmp_gt_u32_e64 s[48:49], v80, v252
	s_nop 0
	v_cndmask_b32_e64 v56, v56, v246, s[46:47]
	v_cndmask_b32_e64 v57, v57, v246, s[48:49]
	v_max3_f32 v61, v61, v56, v57
	v_add_u32_e32 v63, 18, v62
	v_add_u32_e32 v62, 19, v62
	v_cmp_gt_u32_e64 s[50:51], v63, v252
	v_cmp_gt_u32_e64 s[52:53], v62, v252
	s_nop 0
	v_cndmask_b32_e64 v58, v58, v246, s[50:51]
	v_cndmask_b32_e64 v59, v59, v246, s[52:53]
	v_max3_f32 v61, v61, v58, v59
	v_mov_b32_e32 v62, v60
	s_nop 1
	v_permlane32_swap_b32_e32 v62, v60
	v_max_f32_e32 v60, v60, v62
	v_mov_b32_e32 v62, v61
	s_nop 1
	v_permlane32_swap_b32_e32 v62, v61
	v_max_f32_e32 v61, v61, v62
	v_mov_b32_e32 v62, v60
	s_nop 1
	v_permlane16_swap_b32_e32 v62, v60
	v_max3_f32 v148, v145, v60, v62
	v_sub_f32_e32 v32, v32, v148
	v_exp_f32_e32 v32, v32
	v_sub_f32_e32 v33, v33, v148
	v_exp_f32_e32 v33, v33
	v_sub_f32_e32 v34, v34, v148
	v_mov_b32_e32 v62, v61
	v_exp_f32_e32 v34, v34
	v_sub_f32_e32 v35, v35, v148
	v_permlane16_swap_b32_e32 v62, v61
	v_exp_f32_e32 v35, v35
	v_sub_f32_e32 v63, v64, v148
	v_exp_f32_e32 v63, v63
	v_sub_f32_e32 v64, v65, v148
	v_max_f32_e32 v61, v61, v62
	v_add_f32_e32 v62, 0, v32
	v_exp_f32_e32 v64, v64
	v_sub_f32_e32 v65, v66, v148
	v_add_f32_e32 v62, v33, v62
	v_exp_f32_e32 v65, v65
	v_sub_f32_e32 v66, v67, v148
	v_add_f32_e32 v62, v34, v62
	v_exp_f32_e32 v66, v66
	v_add_f32_e32 v62, v35, v62
	v_add_f32_e32 v62, v63, v62
	v_add_f32_e32 v62, v64, v62
	v_max_f32_e32 v150, v147, v61
	v_add_f32_e32 v62, v65, v62
	v_sub_f32_e32 v61, v147, v150
	v_add_f32_e32 v149, v66, v62
	v_exp_f32_e32 v62, v61
	v_sub_f32_e32 v61, v76, v150
	v_cvt_pk_bf16_f32 v32, v32, v33
	v_cvt_pk_bf16_f32 v33, v34, v35
	v_cvt_pk_bf16_f32 v34, v63, v64
	v_exp_f32_e32 v61, v61
	v_sub_f32_e32 v64, v77, v150
	v_cvt_pk_bf16_f32 v35, v65, v66
	v_exp_f32_e32 v64, v64
	v_sub_f32_e32 v65, v78, v150
	v_exp_f32_e32 v65, v65
	v_sub_f32_e32 v66, v79, v150
	v_exp_f32_e32 v66, v66
	v_sub_f32_e32 v56, v56, v150
	v_exp_f32_e32 v56, v56
	v_sub_f32_e32 v57, v57, v150
	v_add_f32_e32 v63, 0, v61
	v_exp_f32_e32 v57, v57
	v_add_f32_e32 v63, v64, v63
	v_add_f32_e32 v63, v65, v63
	v_add_f32_e32 v63, v66, v63
	v_cndmask_b32_e64 v67, v56, 0, s[46:47]
	v_add_f32_e32 v56, v67, v63
	v_cndmask_b32_e64 v63, v57, 0, s[48:49]
	v_sub_f32_e32 v57, v58, v150
	v_exp_f32_e32 v57, v57
	v_sub_f32_e32 v60, v145, v148
	v_exp_f32_e32 v60, v60
	v_add_f32_e32 v56, v63, v56
	v_cndmask_b32_e64 v76, v57, 0, s[50:51]
	v_sub_f32_e32 v57, v59, v150
	v_exp_f32_e32 v57, v57
	v_add_f32_e32 v56, v76, v56
	v_pk_mul_f32 v[38:39], v[38:39], v[60:61] op_sel_hi:[1,0]
	v_pk_mul_f32 v[36:37], v[36:37], v[60:61] op_sel_hi:[1,0]
	v_cndmask_b32_e64 v59, v57, 0, s[52:53]
	v_add_f32_e32 v151, v59, v56
	v_cvt_pk_bf16_f32 v56, v61, v64
	v_cvt_pk_bf16_f32 v57, v65, v66
	v_cvt_pk_bf16_f32 v58, v67, v63
	v_cvt_pk_bf16_f32 v59, v76, v59
	s_waitcnt lgkmcnt(10)
	v_mfma_f32_16x16x32_bf16 v[80:83], v[96:99], v[32:35], v[36:39]
	v_fmac_f32_e32 v149, v146, v60
	v_fmac_f32_e32 v151, v183, v62
	s_nop 0
	v_pk_mul_f32 v[38:39], v[70:71], v[62:63] op_sel_hi:[1,0]
	v_pk_mul_f32 v[36:37], v[68:69], v[62:63] op_sel_hi:[1,0]
	s_nop 1
	v_mfma_f32_16x16x32_bf16 v[84:87], v[96:99], v[56:59], v[36:39]
	s_nop 2
	v_mul_f32_e64 v38, v74, v60
	v_mul_f32_e64 v39, v75, v60
	v_pk_mul_f32 v[36:37], v[72:73], v[60:61] op_sel_hi:[1,0]
	s_waitcnt lgkmcnt(8)
	s_nop 0
	v_mfma_f32_16x16x32_bf16 v[96:99], v[140:143], v[32:35], v[36:39]
	s_nop 2
	v_mul_f32_e64 v38, v106, v62
	v_mul_f32_e64 v39, v107, v62
	v_pk_mul_f32 v[36:37], v[104:105], v[62:63] op_sel_hi:[1,0]
	s_nop 1
	v_mfma_f32_16x16x32_bf16 v[100:103], v[140:143], v[56:59], v[36:39]
	s_nop 2
	v_mul_f32_e64 v38, v110, v60
	v_mul_f32_e64 v39, v111, v60
	v_pk_mul_f32 v[36:37], v[108:109], v[60:61] op_sel_hi:[1,0]
	s_waitcnt lgkmcnt(6)
	s_nop 0
	v_mfma_f32_16x16x32_bf16 v[104:107], v[136:139], v[32:35], v[36:39]
	s_nop 2
	v_mul_f32_e64 v38, v114, v62
	v_mul_f32_e64 v39, v115, v62
	v_pk_mul_f32 v[36:37], v[112:113], v[62:63] op_sel_hi:[1,0]
	s_nop 1
	v_mfma_f32_16x16x32_bf16 v[108:111], v[136:139], v[56:59], v[36:39]
	s_nop 2
	v_mul_f32_e64 v38, v118, v60
	v_mul_f32_e64 v39, v119, v60
	v_pk_mul_f32 v[36:37], v[116:117], v[60:61] op_sel_hi:[1,0]
	s_waitcnt lgkmcnt(4)
	s_nop 0
	v_mfma_f32_16x16x32_bf16 v[112:115], v[132:135], v[32:35], v[36:39]
	v_mul_f32_e64 v34, v130, v62
	v_mul_f32_e64 v35, v131, v62
	v_pk_mul_f32 v[32:33], v[128:129], v[62:63] op_sel_hi:[1,0]
	s_nop 1
	v_mfma_f32_16x16x32_bf16 v[116:119], v[132:135], v[56:59], v[32:35]
	s_nop 2
	v_add_u32_e32 v32, 0x80, v184
	v_med3_i32 v32, v32, 0, s75
	v_lshl_add_u32 v32, v32, 9, v152
	global_load_dwordx4 v[64:67], v32, s[98:99]
	v_add_u32_e32 v32, 0x80, v185
	v_med3_i32 v32, v32, 0, s75
	v_lshl_add_u32 v32, v32, 9, v152
	global_load_dwordx4 v[68:71], v32, s[98:99]
	v_add_u32_e32 v32, 0x80, v186
	v_med3_i32 v32, v32, 0, s75
	v_lshl_add_u32 v32, v32, 9, v152
	global_load_dwordx4 v[72:75], v32, s[98:99]
	v_add_u32_e32 v32, 0x80, v188
	v_med3_i32 v32, v32, 0, s75
	v_lshl_add_u32 v32, v32, 9, v152
	global_load_dwordx4 v[76:79], v32, s[98:99]
	v_or_b32_e32 v32, 0x80, v209
	v_add_u32_e32 v32, s76, v32
	v_med3_i32 v32, v32, 0, s75
	v_lshl_add_u32 v32, v32, 9, v158
	global_load_dwordx4 v[60:63], v32, s[100:101]
	global_load_dwordx4 v[56:59], v32, s[100:101] offset:64
	v_or_b32_e32 v32, 0xc0, v209
	v_add_u32_e32 v32, s76, v32
	v_med3_i32 v32, v32, 0, s75
	v_lshl_add_u32 v32, v32, 9, v158
	global_load_dwordx4 v[36:39], v32, s[100:101]
	s_nop 0
	global_load_dwordx4 v[32:35], v32, s[100:101] offset:64
	ds_read_b64_tr_b16 v[134:135], v169 offset:6912
	ds_read_b64_tr_b16 v[132:133], v169 offset:4608
	ds_read_b64_tr_b16 v[128:129], v169 offset:4640
	ds_read_b64_tr_b16 v[130:131], v169 offset:6944
	ds_read_b64_tr_b16 v[136:137], v169 offset:4672
	ds_read_b64_tr_b16 v[138:139], v169 offset:6976
	ds_read_b64_tr_b16 v[144:145], v169 offset:4704
	ds_read_b64_tr_b16 v[146:147], v169 offset:7008
	s_waitcnt vmcnt(15)
	ds_write_b128 v241, v[88:91]
	s_waitcnt vmcnt(14)
	ds_write_b128 v242, v[92:95]
	s_waitcnt vmcnt(13)
	ds_write_b128 v243, v[120:123]
	s_waitcnt vmcnt(12)
	ds_write_b128 v244, v[124:127]
	v_mfma_f32_16x16x32_bf16 v[88:91], v[52:55], v[4:7], 0
	v_mfma_f32_16x16x32_bf16 v[92:95], v[28:31], v[4:7], 0
	v_mfma_f32_16x16x32_bf16 v[28:31], v[28:31], v[12:15], 0
	v_mfma_f32_16x16x32_bf16 v[88:91], v[44:47], v[8:11], v[88:91]
	v_mfma_f32_16x16x32_bf16 v[92:95], v[20:23], v[8:11], v[92:95]
	v_mfma_f32_16x16x32_bf16 v[20:23], v[20:23], v[0:3], v[28:31]
	s_nop 4
	v_sub_u32_e32 v28, v187, v176
	v_mfma_f32_16x16x32_bf16 v[52:55], v[52:55], v[12:15], 0
	v_add_u32_e32 v31, 1, v28
	v_cmp_gt_u32_e64 s[0:1], v31, v175
	v_cmp_gt_u32_e32 vcc, v28, v175
	s_nop 0
	v_cndmask_b32_e64 v89, v89, v246, s[0:1]
	s_nop 0
	v_cndmask_b32_e32 v88, v88, v246, vcc
	v_max_f32_e32 v30, 0xf149f2ca, v88
	v_mfma_f32_16x16x32_bf16 v[44:47], v[44:47], v[0:3], v[52:55]
	v_max_f32_e32 v30, v30, v89
	v_add_u32_e32 v31, 2, v28
	v_cmp_gt_u32_e64 s[22:23], v31, v175
	v_add_u32_e32 v52, 3, v28
	v_cmp_gt_u32_e64 s[24:25], v52, v175
	v_cndmask_b32_e64 v90, v90, v246, s[22:23]
	v_sub_u32_e32 v29, v187, v181
	v_cndmask_b32_e64 v91, v91, v246, s[24:25]
	v_max3_f32 v30, v30, v90, v91
	v_add_u32_e32 v31, 16, v28
	v_add_u32_e32 v52, 17, v28
	v_cmp_gt_u32_e64 s[26:27], v31, v175
	v_cmp_gt_u32_e64 s[28:29], v52, v175
	v_cmp_gt_u32_e64 s[38:39], v29, v252
	v_cndmask_b32_e64 v92, v92, v246, s[26:27]
	v_cndmask_b32_e64 v93, v93, v246, s[28:29]
	v_max3_f32 v30, v30, v92, v93
	v_add_u32_e32 v31, 18, v28
	v_add_u32_e32 v28, 19, v28
	v_cmp_gt_u32_e64 s[30:31], v31, v175
	v_cmp_gt_u32_e64 s[34:35], v28, v175
	v_add_u32_e32 v52, 3, v29
	v_cndmask_b32_e64 v94, v94, v246, s[30:31]
	v_cndmask_b32_e64 v95, v95, v246, s[34:35]
	v_max3_f32 v28, v30, v94, v95
	v_add_u32_e32 v31, 1, v29
	v_cmp_gt_u32_e64 s[40:41], v31, v252
	v_cndmask_b32_e64 v44, v44, v246, s[38:39]
	v_max_f32_e32 v30, 0xf149f2ca, v44
	v_cndmask_b32_e64 v45, v45, v246, s[40:41]
	v_max_f32_e32 v30, v30, v45
	v_add_u32_e32 v31, 2, v29
	v_cmp_gt_u32_e64 s[42:43], v31, v252
	v_cmp_gt_u32_e64 s[44:45], v52, v252
	s_nop 0
	v_cndmask_b32_e64 v46, v46, v246, s[42:43]
	v_cndmask_b32_e64 v47, v47, v246, s[44:45]
	v_max3_f32 v30, v30, v46, v47
	v_add_u32_e32 v31, 16, v29
	v_add_u32_e32 v52, 17, v29
	v_cmp_gt_u32_e64 s[46:47], v31, v252
	v_cmp_gt_u32_e64 s[48:49], v52, v252
	s_nop 0
	v_cndmask_b32_e64 v20, v20, v246, s[46:47]
	v_cndmask_b32_e64 v21, v21, v246, s[48:49]
	v_max3_f32 v30, v30, v20, v21
	v_add_u32_e32 v31, 18, v29
	v_add_u32_e32 v29, 19, v29
	v_cmp_gt_u32_e64 s[50:51], v31, v252
	v_cmp_gt_u32_e64 s[52:53], v29, v252
	s_nop 0
	v_cndmask_b32_e64 v22, v22, v246, s[50:51]
	v_cndmask_b32_e64 v23, v23, v246, s[52:53]
	v_max3_f32 v29, v30, v22, v23
	v_mov_b32_e32 v30, v28
	s_nop 1
	v_permlane32_swap_b32_e32 v30, v28
	v_max_f32_e32 v28, v28, v30
	v_mov_b32_e32 v30, v29
	s_nop 1
	v_permlane32_swap_b32_e32 v30, v29
	v_max_f32_e32 v29, v29, v30
	v_mov_b32_e32 v30, v28
	s_nop 1
	v_permlane16_swap_b32_e32 v30, v28
	v_max_f32_e32 v28, v28, v30
	v_mov_b32_e32 v30, v29
	v_max_f32_e32 v183, v148, v28
	s_nop 0
	v_permlane16_swap_b32_e32 v30, v29
	v_sub_f32_e32 v28, v148, v183
	v_exp_f32_e32 v52, v28
	v_sub_f32_e32 v28, v88, v183
	v_max_f32_e32 v54, v29, v30
	v_exp_f32_e32 v28, v28
	v_sub_f32_e32 v30, v89, v183
	v_exp_f32_e32 v30, v30
	v_sub_f32_e32 v31, v90, v183
	v_exp_f32_e32 v31, v31
	v_sub_f32_e32 v55, v91, v183
	v_max_f32_e32 v185, v150, v54
	v_exp_f32_e32 v55, v55
	v_sub_f32_e32 v88, v92, v183
	v_sub_f32_e32 v44, v44, v185
	v_exp_f32_e32 v88, v88
	v_sub_f32_e32 v89, v93, v183
	v_exp_f32_e32 v44, v44
	v_sub_f32_e32 v45, v45, v185
	v_add_f32_e32 v29, 0, v28
	v_exp_f32_e32 v89, v89
	v_sub_f32_e32 v90, v94, v183
	v_exp_f32_e32 v45, v45
	v_sub_f32_e32 v46, v46, v185
	v_add_f32_e32 v29, v30, v29
	v_exp_f32_e32 v90, v90
	v_sub_f32_e32 v91, v95, v183
	v_exp_f32_e32 v46, v46
	v_sub_f32_e32 v47, v47, v185
	v_add_f32_e32 v29, v31, v29
	v_exp_f32_e32 v91, v91
	v_exp_f32_e32 v47, v47
	v_sub_f32_e32 v20, v20, v185
	v_add_f32_e32 v29, v55, v29
	v_sub_f32_e32 v53, v150, v185
	v_exp_f32_e32 v20, v20
	v_sub_f32_e32 v21, v21, v185
	v_add_f32_e32 v29, v88, v29
	v_exp_f32_e32 v54, v53
	v_add_f32_e32 v53, 0, v44
	v_exp_f32_e32 v21, v21
	v_add_f32_e32 v29, v89, v29
	v_add_f32_e32 v53, v45, v53
	v_add_f32_e32 v29, v90, v29
	v_add_f32_e32 v53, v46, v53
	v_add_f32_e32 v184, v91, v29
	v_cvt_pk_bf16_f32 v29, v31, v55
	v_add_f32_e32 v53, v47, v53
	v_cndmask_b32_e64 v55, v20, 0, s[46:47]
	v_add_f32_e32 v20, v55, v53
	v_cndmask_b32_e64 v53, v21, 0, s[48:49]
	v_sub_f32_e32 v21, v22, v185
	v_exp_f32_e32 v21, v21
	v_cvt_pk_bf16_f32 v28, v28, v30
	v_cvt_pk_bf16_f32 v30, v88, v89
	v_add_f32_e32 v20, v53, v20
	v_cndmask_b32_e64 v88, v21, 0, s[50:51]
	v_sub_f32_e32 v21, v23, v185
	v_exp_f32_e32 v21, v21
	v_add_f32_e32 v20, v88, v20
	v_cvt_pk_bf16_f32 v31, v90, v91
	v_cvt_pk_bf16_f32 v22, v55, v53
	v_cndmask_b32_e64 v23, v21, 0, s[52:53]
	v_add_f32_e32 v186, v23, v20
	v_cvt_pk_bf16_f32 v20, v44, v45
	v_cvt_pk_bf16_f32 v21, v46, v47
	v_pk_mul_f32 v[46:47], v[82:83], v[52:53] op_sel_hi:[1,0]
	v_pk_mul_f32 v[44:45], v[80:81], v[52:53] op_sel_hi:[1,0]
	v_cvt_pk_bf16_f32 v23, v88, v23
	v_fmac_f32_e32 v184, v149, v52
	s_waitcnt lgkmcnt(10)
	v_mfma_f32_16x16x32_bf16 v[120:123], v[132:135], v[28:31], v[44:47]
	v_fmac_f32_e32 v186, v151, v54
	s_nop 1
	v_pk_mul_f32 v[46:47], v[86:87], v[54:55] op_sel_hi:[1,0]
	v_pk_mul_f32 v[44:45], v[84:85], v[54:55] op_sel_hi:[1,0]
	s_nop 1
	v_mfma_f32_16x16x32_bf16 v[124:127], v[132:135], v[20:23], v[44:47]
	s_nop 2
	v_mul_f32_e64 v46, v98, v52
	v_mul_f32_e64 v47, v99, v52
	v_pk_mul_f32 v[44:45], v[96:97], v[52:53] op_sel_hi:[1,0]
	s_waitcnt lgkmcnt(8)
	s_nop 0
	v_mfma_f32_16x16x32_bf16 v[96:99], v[128:131], v[28:31], v[44:47]
	s_nop 2
	v_mul_f32_e64 v46, v102, v54
	v_mul_f32_e64 v47, v103, v54
	v_pk_mul_f32 v[44:45], v[100:101], v[54:55] op_sel_hi:[1,0]
	s_nop 1
	v_mfma_f32_16x16x32_bf16 v[128:131], v[128:131], v[20:23], v[44:47]
	s_nop 2
	v_mul_f32_e64 v46, v106, v52
	v_mul_f32_e64 v47, v107, v52
	v_pk_mul_f32 v[44:45], v[104:105], v[52:53] op_sel_hi:[1,0]
	s_waitcnt lgkmcnt(6)
	s_nop 0
	v_mfma_f32_16x16x32_bf16 v[132:135], v[136:139], v[28:31], v[44:47]
	s_nop 2
	v_mul_f32_e64 v46, v110, v54
	v_mul_f32_e64 v47, v111, v54
	v_pk_mul_f32 v[44:45], v[108:109], v[54:55] op_sel_hi:[1,0]
	s_nop 1
	v_mfma_f32_16x16x32_bf16 v[136:139], v[136:139], v[20:23], v[44:47]
	s_nop 2
	v_mul_f32_e64 v46, v114, v52
	v_mul_f32_e64 v47, v115, v52
	v_pk_mul_f32 v[44:45], v[112:113], v[52:53] op_sel_hi:[1,0]
	s_waitcnt lgkmcnt(4)
	s_nop 0
	v_mfma_f32_16x16x32_bf16 v[140:143], v[144:147], v[28:31], v[44:47]
	v_mul_f32_e64 v30, v118, v54
	v_mul_f32_e64 v31, v119, v54
	v_pk_mul_f32 v[28:29], v[116:117], v[54:55] op_sel_hi:[1,0]
	s_nop 1
	v_mfma_f32_16x16x32_bf16 v[144:147], v[144:147], v[20:23], v[28:31]
	v_lshl_add_u32 v20, v155, 1, v155
	v_add_u32_e32 v20, v180, v20
	v_med3_i32 v20, v20, 0, s75
	v_lshl_add_u32 v20, v20, 9, v152
	global_load_dwordx4 v[80:83], v20, s[98:99]
	v_lshl_add_u32 v20, v172, 1, v172
	v_add_u32_e32 v20, v179, v20
	v_med3_i32 v20, v20, 0, s75
	v_lshl_add_u32 v20, v20, 9, v152
	global_load_dwordx4 v[84:87], v20, s[98:99]
	v_lshl_add_u32 v20, v173, 1, v173
	v_add_u32_e32 v20, v178, v20
	v_med3_i32 v20, v20, 0, s75
	v_lshl_add_u32 v20, v20, 9, v152
	global_load_dwordx4 v[88:91], v20, s[98:99]
	v_lshl_add_u32 v20, v182, 1, v182
	v_add_u32_e32 v20, v177, v20
	v_med3_i32 v20, v20, 0, s75
	v_lshl_add_u32 v20, v20, 9, v152
	global_load_dwordx4 v[92:95], v20, s[98:99]
	v_or_b32_e32 v20, 0x100, v209
	v_add_u32_e32 v20, s76, v20
	v_med3_i32 v20, v20, 0, s75
	v_lshl_add_u32 v20, v20, 9, v158
	global_load_dwordx4 v[52:55], v20, s[100:101]
	global_load_dwordx4 v[44:47], v20, s[100:101] offset:64
	v_or_b32_e32 v20, 0x140, v209
	v_add_u32_e32 v20, s76, v20
	v_med3_i32 v20, v20, 0, s75
	v_lshl_add_u32 v20, v20, 9, v158
	global_load_dwordx4 v[28:31], v20, s[100:101]
	s_nop 0
	global_load_dwordx4 v[20:23], v20, s[100:101] offset:64
	ds_read_b64_tr_b16 v[102:103], v169 offset:2304
	ds_read_b64_tr_b16 v[100:101], v169
	ds_read_b64_tr_b16 v[108:109], v169 offset:32
	ds_read_b64_tr_b16 v[110:111], v169 offset:2336
	ds_read_b64_tr_b16 v[116:117], v169 offset:64
	ds_read_b64_tr_b16 v[118:119], v169 offset:2368
	ds_read_b64_tr_b16 v[148:149], v169 offset:96
	ds_read_b64_tr_b16 v[150:151], v169 offset:2400
	s_waitcnt vmcnt(15)
	ds_write_b128 v241, v[64:67] offset:4608
	s_waitcnt vmcnt(14)
	ds_write_b128 v242, v[68:71] offset:4608
	s_waitcnt vmcnt(13)
	ds_write_b128 v243, v[72:75] offset:4608
	s_waitcnt vmcnt(12)
	ds_write_b128 v244, v[76:79] offset:4608
	v_mfma_f32_16x16x32_bf16 v[64:67], v[48:51], v[4:7], 0
	v_mfma_f32_16x16x32_bf16 v[68:71], v[24:27], v[4:7], 0
	v_mfma_f32_16x16x32_bf16 v[24:27], v[24:27], v[12:15], 0
	v_mfma_f32_16x16x32_bf16 v[64:67], v[40:43], v[8:11], v[64:67]
	v_mfma_f32_16x16x32_bf16 v[68:71], v[16:19], v[8:11], v[68:71]
	v_mfma_f32_16x16x32_bf16 v[16:19], v[16:19], v[0:3], v[24:27]
	s_nop 4
	v_sub_u32_e32 v24, v192, v176
	v_mfma_f32_16x16x32_bf16 v[48:51], v[48:51], v[12:15], 0
	v_add_u32_e32 v27, 1, v24
	v_cmp_gt_u32_e64 s[0:1], v27, v175
	v_cmp_gt_u32_e32 vcc, v24, v175
	s_nop 0
	v_cndmask_b32_e64 v65, v65, v246, s[0:1]
	s_nop 0
	v_cndmask_b32_e32 v64, v64, v246, vcc
	v_max_f32_e32 v26, 0xf149f2ca, v64
	v_mfma_f32_16x16x32_bf16 v[40:43], v[40:43], v[0:3], v[48:51]
	v_max_f32_e32 v26, v26, v65
	v_add_u32_e32 v27, 2, v24
	v_cmp_gt_u32_e64 s[22:23], v27, v175
	v_add_u32_e32 v48, 3, v24
	v_cmp_gt_u32_e64 s[24:25], v48, v175
	v_cndmask_b32_e64 v66, v66, v246, s[22:23]
	v_sub_u32_e32 v25, v192, v181
	v_cndmask_b32_e64 v67, v67, v246, s[24:25]
	v_max3_f32 v26, v26, v66, v67
	v_add_u32_e32 v27, 16, v24
	v_add_u32_e32 v48, 17, v24
	v_cmp_gt_u32_e64 s[26:27], v27, v175
	v_cmp_gt_u32_e64 s[28:29], v48, v175
	v_cmp_gt_u32_e64 s[38:39], v25, v252
	v_cndmask_b32_e64 v68, v68, v246, s[26:27]
	v_cndmask_b32_e64 v69, v69, v246, s[28:29]
	v_max3_f32 v26, v26, v68, v69
	v_add_u32_e32 v27, 18, v24
	v_add_u32_e32 v24, 19, v24
	v_cmp_gt_u32_e64 s[30:31], v27, v175
	v_cmp_gt_u32_e64 s[34:35], v24, v175
	v_add_u32_e32 v48, 3, v25
	v_cndmask_b32_e64 v70, v70, v246, s[30:31]
	v_cndmask_b32_e64 v71, v71, v246, s[34:35]
	v_max3_f32 v24, v26, v70, v71
	v_add_u32_e32 v27, 1, v25
	v_cmp_gt_u32_e64 s[40:41], v27, v252
	v_cndmask_b32_e64 v40, v40, v246, s[38:39]
	v_max_f32_e32 v26, 0xf149f2ca, v40
	v_cndmask_b32_e64 v41, v41, v246, s[40:41]
	v_max_f32_e32 v26, v26, v41
	v_add_u32_e32 v27, 2, v25
	v_cmp_gt_u32_e64 s[42:43], v27, v252
	v_cmp_gt_u32_e64 s[44:45], v48, v252
	s_nop 0
	v_cndmask_b32_e64 v42, v42, v246, s[42:43]
	v_cndmask_b32_e64 v43, v43, v246, s[44:45]
	v_max3_f32 v26, v26, v42, v43
	v_add_u32_e32 v27, 16, v25
	v_add_u32_e32 v48, 17, v25
	v_cmp_gt_u32_e64 s[46:47], v27, v252
	v_cmp_gt_u32_e64 s[48:49], v48, v252
	s_nop 0
	v_cndmask_b32_e64 v16, v16, v246, s[46:47]
	v_cndmask_b32_e64 v17, v17, v246, s[48:49]
	v_max3_f32 v26, v26, v16, v17
	v_add_u32_e32 v27, 18, v25
	v_add_u32_e32 v25, 19, v25
	v_cmp_gt_u32_e64 s[50:51], v27, v252
	v_cmp_gt_u32_e64 s[52:53], v25, v252
	s_nop 0
	v_cndmask_b32_e64 v18, v18, v246, s[50:51]
	v_cndmask_b32_e64 v19, v19, v246, s[52:53]
	v_max3_f32 v25, v26, v18, v19
	v_mov_b32_e32 v26, v24
	s_nop 1
	v_permlane32_swap_b32_e32 v26, v24
	v_max_f32_e32 v24, v24, v26
	v_mov_b32_e32 v26, v25
	s_nop 1
	v_permlane32_swap_b32_e32 v26, v25
	v_max_f32_e32 v25, v25, v26
	v_mov_b32_e32 v26, v24
	s_nop 1
	v_permlane16_swap_b32_e32 v26, v24
	v_max3_f32 v177, v183, v24, v26
	v_sub_f32_e32 v48, v66, v177
	v_exp_f32_e32 v48, v48
	v_sub_f32_e32 v24, v183, v177
	v_exp_f32_e32 v72, v24
	v_sub_f32_e32 v24, v64, v177
	v_cndmask_b32_e64 v49, v48, 0, s[22:23]
	v_sub_f32_e32 v48, v67, v177
	v_exp_f32_e32 v48, v48
	v_exp_f32_e32 v24, v24
	v_sub_f32_e32 v27, v65, v177
	v_exp_f32_e32 v27, v27
	v_cndmask_b32_e64 v50, v48, 0, s[24:25]
	v_sub_f32_e32 v48, v68, v177
	v_exp_f32_e32 v48, v48
	v_mov_b32_e32 v26, v25
	s_nop 1
	v_permlane16_swap_b32_e32 v26, v25
	v_cndmask_b32_e64 v51, v48, 0, s[26:27]
	v_sub_f32_e32 v48, v69, v177
	v_exp_f32_e32 v48, v48
	v_max_f32_e32 v25, v25, v26
	v_cndmask_b32_e64 v64, v48, 0, s[28:29]
	v_sub_f32_e32 v48, v70, v177
	v_exp_f32_e32 v48, v48
	v_add_f32_e32 v26, 0, v24
	v_add_f32_e32 v26, v27, v26
	v_cndmask_b32_e64 v65, v48, 0, s[30:31]
	v_sub_f32_e32 v48, v71, v177
	v_exp_f32_e32 v48, v48
	v_add_f32_e32 v26, v49, v26
	v_add_f32_e32 v26, v50, v26
	v_add_f32_e32 v26, v51, v26
	v_max_f32_e32 v179, v185, v25
	v_add_f32_e32 v26, v64, v26
	v_cndmask_b32_e64 v66, v48, 0, s[34:35]
	v_cvt_pk_bf16_f32 v48, v24, v27
	v_sub_f32_e32 v24, v185, v179
	v_add_f32_e32 v26, v65, v26
	v_cvt_pk_bf16_f32 v49, v49, v50
	v_cvt_pk_bf16_f32 v50, v51, v64
	v_exp_f32_e32 v64, v24
	v_sub_f32_e32 v24, v40, v179
	v_add_f32_e32 v178, v66, v26
	v_exp_f32_e32 v24, v24
	v_sub_f32_e32 v26, v41, v179
	v_exp_f32_e32 v26, v26
	v_sub_f32_e32 v27, v42, v179
	v_exp_f32_e32 v27, v27
	v_sub_f32_e32 v40, v43, v179
	v_exp_f32_e32 v40, v40
	v_sub_f32_e32 v16, v16, v179
	v_exp_f32_e32 v16, v16
	v_sub_f32_e32 v17, v17, v179
	v_add_f32_e32 v25, 0, v24
	v_exp_f32_e32 v17, v17
	v_add_f32_e32 v25, v26, v25
	v_add_f32_e32 v25, v27, v25
	v_add_f32_e32 v25, v40, v25
	v_cndmask_b32_e64 v41, v16, 0, s[46:47]
	v_add_f32_e32 v16, v41, v25
	v_cndmask_b32_e64 v25, v17, 0, s[48:49]
	v_sub_f32_e32 v17, v18, v179
	v_exp_f32_e32 v17, v17
	v_add_f32_e32 v16, v25, v16
	v_cvt_pk_bf16_f32 v51, v65, v66
	v_cvt_pk_bf16_f32 v18, v41, v25
	v_cndmask_b32_e64 v42, v17, 0, s[50:51]
	v_sub_f32_e32 v17, v19, v179
	v_exp_f32_e32 v17, v17
	v_add_f32_e32 v16, v42, v16
	v_fmac_f32_e32 v178, v184, v72
	v_cndmask_b32_e64 v19, v17, 0, s[52:53]
	v_add_f32_e32 v180, v19, v16
	v_cvt_pk_bf16_f32 v16, v24, v26
	v_cvt_pk_bf16_f32 v17, v27, v40
	v_cvt_pk_bf16_f32 v19, v42, v19
	v_pk_mul_f32 v[26:27], v[122:123], v[72:73] op_sel_hi:[1,0]
	v_pk_mul_f32 v[24:25], v[120:121], v[72:73] op_sel_hi:[1,0]
	v_pk_mul_f32 v[42:43], v[126:127], v[64:65] op_sel_hi:[1,0]
	v_pk_mul_f32 v[40:41], v[124:125], v[64:65] op_sel_hi:[1,0]
	s_waitcnt lgkmcnt(10)
	v_mfma_f32_16x16x32_bf16 v[24:27], v[100:103], v[48:51], v[24:27]
	v_fmac_f32_e32 v180, v186, v64
	v_mfma_f32_16x16x32_bf16 v[100:103], v[100:103], v[16:19], v[40:43]
	s_nop 2
	v_mul_f32_e64 v42, v98, v72
	v_mul_f32_e64 v43, v99, v72
	v_pk_mul_f32 v[40:41], v[96:97], v[72:73] op_sel_hi:[1,0]
	s_waitcnt lgkmcnt(8)
	s_nop 0
	v_mfma_f32_16x16x32_bf16 v[104:107], v[108:111], v[48:51], v[40:43]
	s_nop 2
	v_mul_f32_e64 v42, v130, v64
	v_mul_f32_e64 v43, v131, v64
	v_pk_mul_f32 v[40:41], v[128:129], v[64:65] op_sel_hi:[1,0]
	s_nop 1
	v_mfma_f32_16x16x32_bf16 v[108:111], v[108:111], v[16:19], v[40:43]
	s_nop 2
	v_mul_f32_e64 v42, v134, v72
	v_mul_f32_e64 v43, v135, v72
	v_pk_mul_f32 v[40:41], v[132:133], v[72:73] op_sel_hi:[1,0]
	s_waitcnt lgkmcnt(6)
	s_nop 0
	v_mfma_f32_16x16x32_bf16 v[112:115], v[116:119], v[48:51], v[40:43]
	s_nop 2
	v_mul_f32_e64 v42, v138, v64
	v_mul_f32_e64 v43, v139, v64
	v_pk_mul_f32 v[40:41], v[136:137], v[64:65] op_sel_hi:[1,0]
	s_nop 1
	v_mfma_f32_16x16x32_bf16 v[116:119], v[116:119], v[16:19], v[40:43]
	s_nop 2
	v_mul_f32_e64 v42, v142, v72
	v_mul_f32_e64 v43, v143, v72
	v_pk_mul_f32 v[40:41], v[140:141], v[72:73] op_sel_hi:[1,0]
	s_waitcnt lgkmcnt(4)
	s_nop 0
	v_mfma_f32_16x16x32_bf16 v[120:123], v[148:151], v[48:51], v[40:43]
	s_nop 2
	v_mul_f32_e64 v42, v146, v64
	v_mul_f32_e64 v43, v147, v64
	v_pk_mul_f32 v[40:41], v[144:145], v[64:65] op_sel_hi:[1,0]
	s_nop 1
	v_mfma_f32_16x16x32_bf16 v[124:127], v[148:151], v[16:19], v[40:43]
	v_lshlrev_b32_e32 v16, 2, v196
	v_add_u32_e32 v16, s76, v16
	v_med3_i32 v16, v16, 0, s75
	v_lshl_add_u32 v16, v16, 9, v152
	global_load_dwordx4 v[68:71], v16, s[98:99]
	v_lshlrev_b32_e32 v16, 2, v168
	v_add_u32_e32 v16, s76, v16
	v_med3_i32 v16, v16, 0, s75
	v_lshl_add_u32 v16, v16, 9, v152
	global_load_dwordx4 v[72:75], v16, s[98:99]
	v_lshlrev_b32_e32 v16, 2, v193
	v_add_u32_e32 v16, s76, v16
	v_med3_i32 v16, v16, 0, s75
	v_lshl_add_u32 v16, v16, 9, v152
	global_load_dwordx4 v[76:79], v16, s[98:99]
	v_lshlrev_b32_e32 v16, 2, v194
	v_add_u32_e32 v16, s76, v16
	v_med3_i32 v16, v16, 0, s75
	v_lshl_add_u32 v16, v16, 9, v152
	global_load_dwordx4 v[96:99], v16, s[98:99]
	v_or_b32_e32 v16, 0x180, v209
	v_add_u32_e32 v16, s76, v16
	v_med3_i32 v16, v16, 0, s75
	v_lshl_add_u32 v16, v16, 9, v158
	global_load_dwordx4 v[64:67], v16, s[100:101]
	global_load_dwordx4 v[48:51], v16, s[100:101] offset:64
	v_or_b32_e32 v16, 0x1c0, v209
	v_add_u32_e32 v16, s76, v16
	v_med3_i32 v16, v16, 0, s75
	v_lshl_add_u32 v16, v16, 9, v158
	global_load_dwordx4 v[40:43], v16, s[100:101]
	s_nop 0
	global_load_dwordx4 v[16:19], v16, s[100:101] offset:64
	ds_read_b64_tr_b16 v[142:143], v169 offset:6912
	ds_read_b64_tr_b16 v[140:141], v169 offset:4608
	ds_read_b64_tr_b16 v[136:137], v169 offset:4640
	ds_read_b64_tr_b16 v[138:139], v169 offset:6944
	ds_read_b64_tr_b16 v[132:133], v169 offset:4672
	ds_read_b64_tr_b16 v[134:135], v169 offset:6976
	ds_read_b64_tr_b16 v[128:129], v169 offset:4704
	ds_read_b64_tr_b16 v[130:131], v169 offset:7008
	s_waitcnt vmcnt(15)
	ds_write_b128 v241, v[80:83]
	s_waitcnt vmcnt(14)
	ds_write_b128 v242, v[84:87]
	s_waitcnt vmcnt(13)
	ds_write_b128 v243, v[88:91]
	s_waitcnt vmcnt(12)
	ds_write_b128 v244, v[92:95]
	v_mfma_f32_16x16x32_bf16 v[80:83], v[60:63], v[4:7], 0
	v_mfma_f32_16x16x32_bf16 v[84:87], v[36:39], v[4:7], 0
	v_mfma_f32_16x16x32_bf16 v[36:39], v[36:39], v[12:15], 0
	v_mfma_f32_16x16x32_bf16 v[80:83], v[56:59], v[8:11], v[80:83]
	v_mfma_f32_16x16x32_bf16 v[84:87], v[32:35], v[8:11], v[84:87]
	v_mfma_f32_16x16x32_bf16 v[32:35], v[32:35], v[0:3], v[36:39]
	s_nop 4
	v_sub_u32_e32 v36, v197, v176
	v_mfma_f32_16x16x32_bf16 v[60:63], v[60:63], v[12:15], 0
	v_add_u32_e32 v39, 1, v36
	v_cmp_gt_u32_e64 s[0:1], v39, v175
	v_cmp_gt_u32_e32 vcc, v36, v175
	s_nop 0
	v_cndmask_b32_e64 v81, v81, v246, s[0:1]
	s_nop 0
	v_cndmask_b32_e32 v80, v80, v246, vcc
	v_max_f32_e32 v38, 0xf149f2ca, v80
	v_mfma_f32_16x16x32_bf16 v[56:59], v[56:59], v[0:3], v[60:63]
	v_max_f32_e32 v38, v38, v81
	v_add_u32_e32 v39, 2, v36
	v_cmp_gt_u32_e64 s[22:23], v39, v175
	v_add_u32_e32 v60, 3, v36
	v_cmp_gt_u32_e64 s[24:25], v60, v175
	v_cndmask_b32_e64 v82, v82, v246, s[22:23]
	v_sub_u32_e32 v37, v197, v181
	v_cndmask_b32_e64 v83, v83, v246, s[24:25]
	v_max3_f32 v38, v38, v82, v83
	v_add_u32_e32 v39, 16, v36
	v_add_u32_e32 v60, 17, v36
	v_cmp_gt_u32_e64 s[26:27], v39, v175
	v_cmp_gt_u32_e64 s[28:29], v60, v175
	v_cmp_gt_u32_e64 s[38:39], v37, v252
	v_cndmask_b32_e64 v84, v84, v246, s[26:27]
	v_cndmask_b32_e64 v85, v85, v246, s[28:29]
	v_max3_f32 v38, v38, v84, v85
	v_add_u32_e32 v39, 18, v36
	v_add_u32_e32 v36, 19, v36
	v_cmp_gt_u32_e64 s[30:31], v39, v175
	v_cmp_gt_u32_e64 s[34:35], v36, v175
	v_add_u32_e32 v60, 3, v37
	v_cndmask_b32_e64 v86, v86, v246, s[30:31]
	v_cndmask_b32_e64 v87, v87, v246, s[34:35]
	v_max3_f32 v36, v38, v86, v87
	v_add_u32_e32 v39, 1, v37
	v_cmp_gt_u32_e64 s[40:41], v39, v252
	v_cndmask_b32_e64 v56, v56, v246, s[38:39]
	v_max_f32_e32 v38, 0xf149f2ca, v56
	v_cndmask_b32_e64 v57, v57, v246, s[40:41]
	v_max_f32_e32 v38, v38, v57
	v_add_u32_e32 v39, 2, v37
	v_cmp_gt_u32_e64 s[42:43], v39, v252
	v_cmp_gt_u32_e64 s[44:45], v60, v252
	s_nop 0
	v_cndmask_b32_e64 v58, v58, v246, s[42:43]
	v_cndmask_b32_e64 v59, v59, v246, s[44:45]
	v_max3_f32 v38, v38, v58, v59
	v_add_u32_e32 v39, 16, v37
	v_add_u32_e32 v60, 17, v37
	v_cmp_gt_u32_e64 s[46:47], v39, v252
	v_cmp_gt_u32_e64 s[48:49], v60, v252
	s_nop 0
	v_cndmask_b32_e64 v32, v32, v246, s[46:47]
	v_cndmask_b32_e64 v33, v33, v246, s[48:49]
	v_max3_f32 v38, v38, v32, v33
	v_add_u32_e32 v39, 18, v37
	v_add_u32_e32 v37, 19, v37
	v_cmp_gt_u32_e64 s[50:51], v39, v252
	v_cmp_gt_u32_e64 s[52:53], v37, v252
	s_nop 0
	v_cndmask_b32_e64 v34, v34, v246, s[50:51]
	v_cndmask_b32_e64 v35, v35, v246, s[52:53]
	v_max3_f32 v37, v38, v34, v35
	v_mov_b32_e32 v38, v36
	s_nop 1
	v_permlane32_swap_b32_e32 v38, v36
	v_max_f32_e32 v36, v36, v38
	v_mov_b32_e32 v38, v37
	s_nop 1
	v_permlane32_swap_b32_e32 v38, v37
	v_max_f32_e32 v37, v37, v38
	v_mov_b32_e32 v38, v36
	s_nop 1
	v_permlane16_swap_b32_e32 v38, v36
	v_max_f32_e32 v36, v36, v38
	v_mov_b32_e32 v38, v37
	v_max_f32_e32 v144, v177, v36
	s_nop 0
	v_permlane16_swap_b32_e32 v38, v37
	v_sub_f32_e32 v36, v177, v144
	v_exp_f32_e32 v60, v36
	v_sub_f32_e32 v36, v80, v144
	v_max_f32_e32 v62, v37, v38
	v_exp_f32_e32 v36, v36
	v_sub_f32_e32 v38, v81, v144
	v_exp_f32_e32 v38, v38
	v_sub_f32_e32 v39, v82, v144
	v_exp_f32_e32 v39, v39
	v_sub_f32_e32 v63, v83, v144
	v_max_f32_e32 v146, v179, v62
	v_exp_f32_e32 v63, v63
	v_sub_f32_e32 v80, v84, v144
	v_sub_f32_e32 v56, v56, v146
	v_exp_f32_e32 v80, v80
	v_sub_f32_e32 v81, v85, v144
	v_exp_f32_e32 v56, v56
	v_sub_f32_e32 v57, v57, v146
	v_add_f32_e32 v37, 0, v36
	v_exp_f32_e32 v81, v81
	v_sub_f32_e32 v82, v86, v144
	v_exp_f32_e32 v57, v57
	v_sub_f32_e32 v58, v58, v146
	v_add_f32_e32 v37, v38, v37
	v_exp_f32_e32 v82, v82
	v_sub_f32_e32 v83, v87, v144
	v_exp_f32_e32 v58, v58
	v_sub_f32_e32 v59, v59, v146
	v_add_f32_e32 v37, v39, v37
	v_exp_f32_e32 v83, v83
	v_exp_f32_e32 v59, v59
	v_sub_f32_e32 v32, v32, v146
	v_add_f32_e32 v37, v63, v37
	v_sub_f32_e32 v61, v179, v146
	v_exp_f32_e32 v32, v32
	v_sub_f32_e32 v33, v33, v146
	v_add_f32_e32 v37, v80, v37
	v_exp_f32_e32 v62, v61
	v_add_f32_e32 v61, 0, v56
	v_exp_f32_e32 v33, v33
	v_add_f32_e32 v37, v81, v37
	v_add_f32_e32 v61, v57, v61
	v_add_f32_e32 v37, v82, v37
	v_add_f32_e32 v61, v58, v61
	v_add_f32_e32 v145, v83, v37
	v_cvt_pk_bf16_f32 v37, v39, v63
	v_add_f32_e32 v61, v59, v61
	v_cndmask_b32_e64 v63, v32, 0, s[46:47]
	v_add_f32_e32 v32, v63, v61
	v_cndmask_b32_e64 v61, v33, 0, s[48:49]
	v_sub_f32_e32 v33, v34, v146
	v_exp_f32_e32 v33, v33
	v_cvt_pk_bf16_f32 v36, v36, v38
	v_cvt_pk_bf16_f32 v38, v80, v81
	v_add_f32_e32 v32, v61, v32
	v_cndmask_b32_e64 v80, v33, 0, s[50:51]
	v_sub_f32_e32 v33, v35, v146
	v_exp_f32_e32 v33, v33
	v_cvt_pk_bf16_f32 v39, v82, v83
	v_add_f32_e32 v32, v80, v32
	v_pk_mul_f32 v[26:27], v[26:27], v[60:61] op_sel_hi:[1,0]
	v_cndmask_b32_e64 v35, v33, 0, s[52:53]
	v_pk_mul_f32 v[24:25], v[24:25], v[60:61] op_sel_hi:[1,0]
	v_add_f32_e32 v147, v35, v32
	v_cvt_pk_bf16_f32 v32, v56, v57
	v_cvt_pk_bf16_f32 v33, v58, v59
	v_cvt_pk_bf16_f32 v34, v63, v61
	v_cvt_pk_bf16_f32 v35, v80, v35
	s_waitcnt lgkmcnt(10)
	v_mfma_f32_16x16x32_bf16 v[92:95], v[140:143], v[36:39], v[24:27]
	v_fmac_f32_e32 v145, v178, v60
	v_fmac_f32_e32 v147, v180, v62
	s_nop 0
	v_pk_mul_f32 v[26:27], v[102:103], v[62:63] op_sel_hi:[1,0]
	v_pk_mul_f32 v[24:25], v[100:101], v[62:63] op_sel_hi:[1,0]
	s_nop 1
	v_mfma_f32_16x16x32_bf16 v[100:103], v[140:143], v[32:35], v[24:27]
	s_nop 2
	v_mul_f32_e64 v26, v106, v60
	v_mul_f32_e64 v27, v107, v60
	v_pk_mul_f32 v[24:25], v[104:105], v[60:61] op_sel_hi:[1,0]
	s_waitcnt lgkmcnt(8)
	s_nop 0
	v_mfma_f32_16x16x32_bf16 v[104:107], v[136:139], v[36:39], v[24:27]
	s_nop 2
	v_mul_f32_e64 v26, v110, v62
	v_mul_f32_e64 v27, v111, v62
	v_pk_mul_f32 v[24:25], v[108:109], v[62:63] op_sel_hi:[1,0]
	s_nop 1
	v_mfma_f32_16x16x32_bf16 v[108:111], v[136:139], v[32:35], v[24:27]
	s_nop 2
	v_mul_f32_e64 v26, v114, v60
	v_mul_f32_e64 v27, v115, v60
	v_pk_mul_f32 v[24:25], v[112:113], v[60:61] op_sel_hi:[1,0]
	s_waitcnt lgkmcnt(6)
	s_nop 0
	v_mfma_f32_16x16x32_bf16 v[112:115], v[132:135], v[36:39], v[24:27]
	s_nop 2
	v_mul_f32_e64 v26, v118, v62
	v_mul_f32_e64 v27, v119, v62
	v_pk_mul_f32 v[24:25], v[116:117], v[62:63] op_sel_hi:[1,0]
	s_nop 1
	v_mfma_f32_16x16x32_bf16 v[116:119], v[132:135], v[32:35], v[24:27]
	s_nop 2
	v_mul_f32_e64 v26, v122, v60
	v_mul_f32_e64 v27, v123, v60
	v_pk_mul_f32 v[24:25], v[120:121], v[60:61] op_sel_hi:[1,0]
	s_waitcnt lgkmcnt(4)
	s_nop 0
	v_mfma_f32_16x16x32_bf16 v[120:123], v[128:131], v[36:39], v[24:27]
	s_nop 2
	v_mul_f32_e64 v26, v126, v62
	v_mul_f32_e64 v27, v127, v62
	v_pk_mul_f32 v[24:25], v[124:125], v[62:63] op_sel_hi:[1,0]
	s_nop 1
	v_mfma_f32_16x16x32_bf16 v[124:127], v[128:131], v[32:35], v[24:27]
	s_nop 2
	v_add_u32_e32 v24, s76, v214
	v_med3_i32 v24, v24, 0, s75
	v_lshl_add_u32 v24, v24, 9, v152
	global_load_dwordx4 v[60:63], v24, s[98:99]
	v_add_u32_e32 v24, s76, v216
	v_med3_i32 v24, v24, 0, s75
	v_lshl_add_u32 v24, v24, 9, v152
	global_load_dwordx4 v[80:83], v24, s[98:99]
	v_add_u32_e32 v24, s76, v218
	v_med3_i32 v24, v24, 0, s75
	v_lshl_add_u32 v24, v24, 9, v152
	global_load_dwordx4 v[84:87], v24, s[98:99]
	v_add_u32_e32 v24, s76, v220
	v_med3_i32 v24, v24, 0, s75
	v_lshl_add_u32 v24, v24, 9, v152
	global_load_dwordx4 v[88:91], v24, s[98:99]
	v_add_u32_e32 v24, s76, v221
	v_med3_i32 v24, v24, 0, s75
	v_lshl_add_u32 v24, v24, 9, v158
	global_load_dwordx4 v[56:59], v24, s[100:101]
	global_load_dwordx4 v[36:39], v24, s[100:101] offset:64
	v_or_b32_e32 v24, 0x100, v221
	v_add_u32_e32 v24, s76, v24
	v_med3_i32 v24, v24, 0, s75
	v_lshl_add_u32 v24, v24, 9, v158
	global_load_dwordx4 v[32:35], v24, s[100:101]
	s_nop 0
	global_load_dwordx4 v[24:27], v24, s[100:101] offset:64
	ds_read_b64_tr_b16 v[142:143], v169 offset:2304
	ds_read_b64_tr_b16 v[140:141], v169
	ds_read_b64_tr_b16 v[136:137], v169 offset:32
	ds_read_b64_tr_b16 v[138:139], v169 offset:2336
	ds_read_b64_tr_b16 v[132:133], v169 offset:64
	ds_read_b64_tr_b16 v[134:135], v169 offset:2368
	ds_read_b64_tr_b16 v[128:129], v169 offset:96
	ds_read_b64_tr_b16 v[130:131], v169 offset:2400
	s_waitcnt vmcnt(15)
	ds_write_b128 v241, v[68:71] offset:4608
	s_waitcnt vmcnt(14)
	ds_write_b128 v242, v[72:75] offset:4608
	s_waitcnt vmcnt(13)
	ds_write_b128 v243, v[76:79] offset:4608
	s_waitcnt vmcnt(12)
	ds_write_b128 v244, v[96:99] offset:4608
	v_mfma_f32_16x16x32_bf16 v[68:71], v[52:55], v[4:7], 0
	v_mfma_f32_16x16x32_bf16 v[72:75], v[28:31], v[4:7], 0
	v_mfma_f32_16x16x32_bf16 v[28:31], v[28:31], v[12:15], 0
	v_mfma_f32_16x16x32_bf16 v[68:71], v[44:47], v[8:11], v[68:71]
	v_mfma_f32_16x16x32_bf16 v[72:75], v[20:23], v[8:11], v[72:75]
	v_mfma_f32_16x16x32_bf16 v[20:23], v[20:23], v[0:3], v[28:31]
	s_nop 4
	v_sub_u32_e32 v28, v198, v176
	v_mfma_f32_16x16x32_bf16 v[52:55], v[52:55], v[12:15], 0
	v_add_u32_e32 v31, 1, v28
	v_cmp_gt_u32_e64 s[0:1], v31, v175
	v_cmp_gt_u32_e32 vcc, v28, v175
	s_nop 0
	v_cndmask_b32_e64 v69, v69, v246, s[0:1]
	s_nop 0
	v_cndmask_b32_e32 v68, v68, v246, vcc
	v_max_f32_e32 v30, 0xf149f2ca, v68
	v_mfma_f32_16x16x32_bf16 v[44:47], v[44:47], v[0:3], v[52:55]
	v_max_f32_e32 v30, v30, v69
	v_add_u32_e32 v31, 2, v28
	v_cmp_gt_u32_e64 s[22:23], v31, v175
	v_add_u32_e32 v52, 3, v28
	v_cmp_gt_u32_e64 s[24:25], v52, v175
	v_cndmask_b32_e64 v70, v70, v246, s[22:23]
	v_sub_u32_e32 v29, v198, v181
	v_cndmask_b32_e64 v71, v71, v246, s[24:25]
	v_max3_f32 v30, v30, v70, v71
	v_add_u32_e32 v31, 16, v28
	v_add_u32_e32 v52, 17, v28
	v_cmp_gt_u32_e64 s[26:27], v31, v175
	v_cmp_gt_u32_e64 s[28:29], v52, v175
	v_cmp_gt_u32_e64 s[38:39], v29, v252
	v_cndmask_b32_e64 v72, v72, v246, s[26:27]
	v_cndmask_b32_e64 v73, v73, v246, s[28:29]
	v_max3_f32 v30, v30, v72, v73
	v_add_u32_e32 v31, 18, v28
	v_add_u32_e32 v28, 19, v28
	v_cmp_gt_u32_e64 s[30:31], v31, v175
	v_cmp_gt_u32_e64 s[34:35], v28, v175
	v_add_u32_e32 v52, 3, v29
	v_cndmask_b32_e64 v74, v74, v246, s[30:31]
	v_cndmask_b32_e64 v75, v75, v246, s[34:35]
	v_max3_f32 v28, v30, v74, v75
	v_add_u32_e32 v31, 1, v29
	v_cmp_gt_u32_e64 s[40:41], v31, v252
	v_cndmask_b32_e64 v44, v44, v246, s[38:39]
	v_max_f32_e32 v30, 0xf149f2ca, v44
	v_cndmask_b32_e64 v45, v45, v246, s[40:41]
	v_max_f32_e32 v30, v30, v45
	v_add_u32_e32 v31, 2, v29
	v_cmp_gt_u32_e64 s[42:43], v31, v252
	v_cmp_gt_u32_e64 s[44:45], v52, v252
	s_nop 0
	v_cndmask_b32_e64 v46, v46, v246, s[42:43]
	v_cndmask_b32_e64 v47, v47, v246, s[44:45]
	v_max3_f32 v30, v30, v46, v47
	v_add_u32_e32 v31, 16, v29
	v_add_u32_e32 v52, 17, v29
	v_cmp_gt_u32_e64 s[46:47], v31, v252
	v_cmp_gt_u32_e64 s[48:49], v52, v252
	s_nop 0
	v_cndmask_b32_e64 v20, v20, v246, s[46:47]
	v_cndmask_b32_e64 v21, v21, v246, s[48:49]
	v_max3_f32 v30, v30, v20, v21
	v_add_u32_e32 v31, 18, v29
	v_add_u32_e32 v29, 19, v29
	v_cmp_gt_u32_e64 s[50:51], v31, v252
	v_cmp_gt_u32_e64 s[52:53], v29, v252
	s_nop 0
	v_cndmask_b32_e64 v22, v22, v246, s[50:51]
	v_cndmask_b32_e64 v23, v23, v246, s[52:53]
	v_max3_f32 v29, v30, v22, v23
	v_mov_b32_e32 v30, v28
	s_nop 1
	v_permlane32_swap_b32_e32 v30, v28
	v_max_f32_e32 v28, v28, v30
	v_mov_b32_e32 v30, v29
	s_nop 1
	v_permlane32_swap_b32_e32 v30, v29
	v_max_f32_e32 v29, v29, v30
	v_mov_b32_e32 v30, v28
	s_nop 1
	v_permlane16_swap_b32_e32 v30, v28
	v_max_f32_e32 v28, v28, v30
	v_mov_b32_e32 v30, v29
	v_max_f32_e32 v148, v144, v28
	s_nop 0
	v_permlane16_swap_b32_e32 v30, v29
	v_sub_f32_e32 v28, v144, v148
	v_exp_f32_e32 v52, v28
	v_sub_f32_e32 v28, v68, v148
	v_max_f32_e32 v54, v29, v30
	v_exp_f32_e32 v28, v28
	v_sub_f32_e32 v30, v69, v148
	v_exp_f32_e32 v30, v30
	v_sub_f32_e32 v31, v70, v148
	v_exp_f32_e32 v31, v31
	v_sub_f32_e32 v55, v71, v148
	v_max_f32_e32 v149, v146, v54
	v_exp_f32_e32 v55, v55
	v_sub_f32_e32 v68, v72, v148
	v_sub_f32_e32 v44, v44, v149
	v_exp_f32_e32 v68, v68
	v_sub_f32_e32 v69, v73, v148
	v_exp_f32_e32 v44, v44
	v_sub_f32_e32 v45, v45, v149
	v_add_f32_e32 v29, 0, v28
	v_exp_f32_e32 v69, v69
	v_sub_f32_e32 v70, v74, v148
	v_exp_f32_e32 v45, v45
	v_sub_f32_e32 v46, v46, v149
	v_add_f32_e32 v29, v30, v29
	v_exp_f32_e32 v70, v70
	v_sub_f32_e32 v71, v75, v148
	v_exp_f32_e32 v46, v46
	v_sub_f32_e32 v47, v47, v149
	v_add_f32_e32 v29, v31, v29
	v_exp_f32_e32 v71, v71
	v_exp_f32_e32 v47, v47
	v_sub_f32_e32 v20, v20, v149
	v_add_f32_e32 v29, v55, v29
	v_sub_f32_e32 v53, v146, v149
	v_exp_f32_e32 v20, v20
	v_sub_f32_e32 v21, v21, v149
	v_add_f32_e32 v29, v68, v29
	v_exp_f32_e32 v54, v53
	v_add_f32_e32 v53, 0, v44
	v_exp_f32_e32 v21, v21
	v_add_f32_e32 v29, v69, v29
	v_add_f32_e32 v53, v45, v53
	v_add_f32_e32 v29, v70, v29
	v_add_f32_e32 v53, v46, v53
	v_add_f32_e32 v144, v71, v29
	v_cvt_pk_bf16_f32 v29, v31, v55
	v_add_f32_e32 v53, v47, v53
	v_cndmask_b32_e64 v55, v20, 0, s[46:47]
	v_add_f32_e32 v20, v55, v53
	v_cndmask_b32_e64 v53, v21, 0, s[48:49]
	v_sub_f32_e32 v21, v22, v149
	v_exp_f32_e32 v21, v21
	v_cvt_pk_bf16_f32 v28, v28, v30
	v_cvt_pk_bf16_f32 v30, v68, v69
	v_add_f32_e32 v20, v53, v20
	v_cndmask_b32_e64 v68, v21, 0, s[50:51]
	v_sub_f32_e32 v21, v23, v149
	v_exp_f32_e32 v21, v21
	v_add_f32_e32 v20, v68, v20
	v_fmac_f32_e32 v144, v145, v52
	v_cvt_pk_bf16_f32 v31, v70, v71
	v_cndmask_b32_e64 v23, v21, 0, s[52:53]
	v_add_f32_e32 v145, v23, v20
	v_cvt_pk_bf16_f32 v20, v44, v45
	v_cvt_pk_bf16_f32 v21, v46, v47
	v_pk_mul_f32 v[46:47], v[94:95], v[52:53] op_sel_hi:[1,0]
	v_pk_mul_f32 v[44:45], v[92:93], v[52:53] op_sel_hi:[1,0]
	v_cvt_pk_bf16_f32 v22, v55, v53
	v_cvt_pk_bf16_f32 v23, v68, v23
	s_waitcnt lgkmcnt(10)
	v_mfma_f32_16x16x32_bf16 v[96:99], v[140:143], v[28:31], v[44:47]
	v_fmac_f32_e32 v145, v147, v54
	s_nop 1
	v_pk_mul_f32 v[46:47], v[102:103], v[54:55] op_sel_hi:[1,0]
	v_pk_mul_f32 v[44:45], v[100:101], v[54:55] op_sel_hi:[1,0]
	s_nop 1
	v_mfma_f32_16x16x32_bf16 v[100:103], v[140:143], v[20:23], v[44:47]
	s_nop 2
	v_mul_f32_e64 v46, v106, v52
	v_mul_f32_e64 v47, v107, v52
	v_pk_mul_f32 v[44:45], v[104:105], v[52:53] op_sel_hi:[1,0]
	s_waitcnt lgkmcnt(8)
	s_nop 0
	v_mfma_f32_16x16x32_bf16 v[104:107], v[136:139], v[28:31], v[44:47]
	s_nop 2
	v_mul_f32_e64 v46, v110, v54
	v_mul_f32_e64 v47, v111, v54
	v_pk_mul_f32 v[44:45], v[108:109], v[54:55] op_sel_hi:[1,0]
	s_nop 1
	v_mfma_f32_16x16x32_bf16 v[108:111], v[136:139], v[20:23], v[44:47]
	s_nop 2
	v_mul_f32_e64 v46, v114, v52
	v_mul_f32_e64 v47, v115, v52
	v_pk_mul_f32 v[44:45], v[112:113], v[52:53] op_sel_hi:[1,0]
	s_waitcnt lgkmcnt(6)
	s_nop 0
	v_mfma_f32_16x16x32_bf16 v[112:115], v[132:135], v[28:31], v[44:47]
	s_nop 2
	v_mul_f32_e64 v46, v118, v54
	v_mul_f32_e64 v47, v119, v54
	v_pk_mul_f32 v[44:45], v[116:117], v[54:55] op_sel_hi:[1,0]
	s_nop 1
	v_mfma_f32_16x16x32_bf16 v[116:119], v[132:135], v[20:23], v[44:47]
	s_nop 2
	v_mul_f32_e64 v46, v122, v52
	v_mul_f32_e64 v47, v123, v52
	v_pk_mul_f32 v[44:45], v[120:121], v[52:53] op_sel_hi:[1,0]
	s_waitcnt lgkmcnt(4)
	s_nop 0
	v_mfma_f32_16x16x32_bf16 v[120:123], v[128:131], v[28:31], v[44:47]
	v_mul_f32_e64 v30, v126, v54
	v_mul_f32_e64 v31, v127, v54
	v_pk_mul_f32 v[28:29], v[124:125], v[54:55] op_sel_hi:[1,0]
	s_nop 1
	v_mfma_f32_16x16x32_bf16 v[124:127], v[128:131], v[20:23], v[28:31]
	v_add_u32_e32 v20, s76, v222
	v_med3_i32 v20, v20, 0, s75
	v_lshl_add_u32 v20, v20, 9, v152
	global_load_dwordx4 v[68:71], v20, s[98:99]
	v_add_u32_e32 v20, s76, v223
	v_med3_i32 v20, v20, 0, s75
	v_lshl_add_u32 v20, v20, 9, v152
	global_load_dwordx4 v[72:75], v20, s[98:99]
	v_add_u32_e32 v20, s76, v224
	v_med3_i32 v20, v20, 0, s75
	v_lshl_add_u32 v20, v20, 9, v152
	global_load_dwordx4 v[76:79], v20, s[98:99]
	v_add_u32_e32 v20, s76, v225
	v_med3_i32 v20, v20, 0, s75
	v_lshl_add_u32 v20, v20, 9, v152
	global_load_dwordx4 v[92:95], v20, s[98:99]
	v_add_u32_e32 v20, s76, v226
	v_med3_i32 v20, v20, 0, s75
	v_lshl_add_u32 v20, v20, 9, v158
	global_load_dwordx4 v[52:55], v20, s[100:101]
	global_load_dwordx4 v[44:47], v20, s[100:101] offset:64
	v_add_u32_e32 v20, s76, v227
	v_med3_i32 v20, v20, 0, s75
	v_lshl_add_u32 v20, v20, 9, v158
	global_load_dwordx4 v[28:31], v20, s[100:101]
	s_nop 0
	global_load_dwordx4 v[20:23], v20, s[100:101] offset:64
	ds_read_b64_tr_b16 v[142:143], v169 offset:6912
	ds_read_b64_tr_b16 v[140:141], v169 offset:4608
	ds_read_b64_tr_b16 v[136:137], v169 offset:4640
	ds_read_b64_tr_b16 v[138:139], v169 offset:6944
	ds_read_b64_tr_b16 v[132:133], v169 offset:4672
	ds_read_b64_tr_b16 v[134:135], v169 offset:6976
	ds_read_b64_tr_b16 v[128:129], v169 offset:4704
	ds_read_b64_tr_b16 v[130:131], v169 offset:7008
	s_waitcnt vmcnt(15)
	ds_write_b128 v241, v[60:63]
	s_waitcnt vmcnt(14)
	ds_write_b128 v242, v[80:83]
	s_waitcnt vmcnt(13)
	ds_write_b128 v243, v[84:87]
	s_waitcnt vmcnt(12)
	ds_write_b128 v244, v[88:91]
	v_mfma_f32_16x16x32_bf16 v[60:63], v[64:67], v[4:7], 0
	v_mfma_f32_16x16x32_bf16 v[80:83], v[40:43], v[4:7], 0
	v_mfma_f32_16x16x32_bf16 v[40:43], v[40:43], v[12:15], 0
	v_mfma_f32_16x16x32_bf16 v[60:63], v[48:51], v[8:11], v[60:63]
	v_mfma_f32_16x16x32_bf16 v[80:83], v[16:19], v[8:11], v[80:83]
	v_mfma_f32_16x16x32_bf16 v[16:19], v[16:19], v[0:3], v[40:43]
	s_nop 4
	v_sub_u32_e32 v40, v199, v176
	v_mfma_f32_16x16x32_bf16 v[64:67], v[64:67], v[12:15], 0
	v_add_u32_e32 v43, 1, v40
	v_cmp_gt_u32_e64 s[0:1], v43, v175
	v_cmp_gt_u32_e32 vcc, v40, v175
	s_nop 0
	v_cndmask_b32_e64 v61, v61, v246, s[0:1]
	s_nop 0
	v_cndmask_b32_e32 v60, v60, v246, vcc
	v_max_f32_e32 v42, 0xf149f2ca, v60
	v_mfma_f32_16x16x32_bf16 v[48:51], v[48:51], v[0:3], v[64:67]
	v_max_f32_e32 v42, v42, v61
	v_add_u32_e32 v43, 2, v40
	v_cmp_gt_u32_e64 s[22:23], v43, v175
	v_add_u32_e32 v64, 3, v40
	v_cmp_gt_u32_e64 s[24:25], v64, v175
	v_cndmask_b32_e64 v62, v62, v246, s[22:23]
	v_sub_u32_e32 v41, v199, v181
	v_cndmask_b32_e64 v63, v63, v246, s[24:25]
	v_max3_f32 v42, v42, v62, v63
	v_add_u32_e32 v43, 16, v40
	v_add_u32_e32 v64, 17, v40
	v_cmp_gt_u32_e64 s[26:27], v43, v175
	v_cmp_gt_u32_e64 s[28:29], v64, v175
	v_cmp_gt_u32_e64 s[38:39], v41, v252
	v_cndmask_b32_e64 v80, v80, v246, s[26:27]
	v_cndmask_b32_e64 v81, v81, v246, s[28:29]
	v_max3_f32 v42, v42, v80, v81
	v_add_u32_e32 v43, 18, v40
	v_add_u32_e32 v40, 19, v40
	v_cmp_gt_u32_e64 s[30:31], v43, v175
	v_cmp_gt_u32_e64 s[34:35], v40, v175
	v_add_u32_e32 v64, 3, v41
	v_cndmask_b32_e64 v82, v82, v246, s[30:31]
	v_cndmask_b32_e64 v83, v83, v246, s[34:35]
	v_max3_f32 v40, v42, v82, v83
	v_add_u32_e32 v43, 1, v41
	v_cmp_gt_u32_e64 s[40:41], v43, v252
	v_cndmask_b32_e64 v48, v48, v246, s[38:39]
	v_max_f32_e32 v42, 0xf149f2ca, v48
	v_cndmask_b32_e64 v49, v49, v246, s[40:41]
	v_max_f32_e32 v42, v42, v49
	v_add_u32_e32 v43, 2, v41
	v_cmp_gt_u32_e64 s[42:43], v43, v252
	v_cmp_gt_u32_e64 s[44:45], v64, v252
	s_nop 0
	v_cndmask_b32_e64 v50, v50, v246, s[42:43]
	v_cndmask_b32_e64 v51, v51, v246, s[44:45]
	v_max3_f32 v42, v42, v50, v51
	v_add_u32_e32 v43, 16, v41
	v_add_u32_e32 v64, 17, v41
	v_cmp_gt_u32_e64 s[46:47], v43, v252
	v_cmp_gt_u32_e64 s[48:49], v64, v252
	s_nop 0
	v_cndmask_b32_e64 v16, v16, v246, s[46:47]
	v_cndmask_b32_e64 v17, v17, v246, s[48:49]
	v_max3_f32 v42, v42, v16, v17
	v_add_u32_e32 v43, 18, v41
	v_add_u32_e32 v41, 19, v41
	v_cmp_gt_u32_e64 s[50:51], v43, v252
	v_cmp_gt_u32_e64 s[52:53], v41, v252
	s_nop 0
	v_cndmask_b32_e64 v18, v18, v246, s[50:51]
	v_cndmask_b32_e64 v19, v19, v246, s[52:53]
	v_max3_f32 v41, v42, v18, v19
	v_mov_b32_e32 v42, v40
	s_nop 1
	v_permlane32_swap_b32_e32 v42, v40
	v_max_f32_e32 v40, v40, v42
	v_mov_b32_e32 v42, v41
	s_nop 1
	v_permlane32_swap_b32_e32 v42, v41
	v_max_f32_e32 v41, v41, v42
	v_mov_b32_e32 v42, v40
	s_nop 1
	v_permlane16_swap_b32_e32 v42, v40
	v_max3_f32 v147, v148, v40, v42
	v_sub_f32_e32 v40, v148, v147
	v_exp_f32_e32 v84, v40
	v_sub_f32_e32 v40, v60, v147
	v_exp_f32_e32 v40, v40
	v_mov_b32_e32 v42, v41
	s_nop 1
	v_permlane16_swap_b32_e32 v42, v41
	v_cndmask_b32_e64 v85, v40, 0, vcc
	v_sub_f32_e32 v40, v61, v147
	v_exp_f32_e32 v40, v40
	v_max3_f32 v146, v149, v41, v42
	v_cndmask_b32_e64 v61, v40, 0, s[0:1]
	v_sub_f32_e32 v40, v62, v147
	v_exp_f32_e32 v40, v40
	v_sub_f32_e32 v48, v48, v146
	v_sub_f32_e32 v16, v16, v146
	v_exp_f32_e32 v48, v48
	v_cndmask_b32_e64 v62, v40, 0, s[22:23]
	v_sub_f32_e32 v40, v63, v147
	v_exp_f32_e32 v40, v40
	v_exp_f32_e32 v16, v16
	v_cndmask_b32_e64 v86, v48, 0, s[38:39]
	v_sub_f32_e32 v48, v49, v146
	v_cndmask_b32_e64 v63, v40, 0, s[24:25]
	v_sub_f32_e32 v40, v80, v147
	v_exp_f32_e32 v40, v40
	v_cndmask_b32_e64 v90, v16, 0, s[46:47]
	v_sub_f32_e32 v16, v17, v146
	v_exp_f32_e32 v48, v48
	v_cndmask_b32_e64 v80, v40, 0, s[26:27]
	v_sub_f32_e32 v40, v81, v147
	v_exp_f32_e32 v40, v40
	v_exp_f32_e32 v16, v16
	v_cndmask_b32_e64 v87, v48, 0, s[40:41]
	v_sub_f32_e32 v48, v50, v146
	v_cndmask_b32_e64 v81, v40, 0, s[28:29]
	v_sub_f32_e32 v40, v82, v147
	v_exp_f32_e32 v40, v40
	v_cndmask_b32_e64 v91, v16, 0, s[48:49]
	v_sub_f32_e32 v16, v18, v146
	v_exp_f32_e32 v48, v48
	v_exp_f32_e32 v16, v16
	v_cndmask_b32_e64 v82, v40, 0, s[30:31]
	v_sub_f32_e32 v40, v83, v147
	v_exp_f32_e32 v40, v40
	v_cndmask_b32_e64 v88, v48, 0, s[42:43]
	v_sub_f32_e32 v48, v51, v146
	v_cndmask_b32_e64 v148, v16, 0, s[50:51]
	v_sub_f32_e32 v16, v19, v146
	v_sub_f32_e32 v60, v149, v146
	v_exp_f32_e32 v48, v48
	v_exp_f32_e32 v16, v16
	v_exp_f32_e32 v60, v60
	v_cndmask_b32_e64 v83, v40, 0, s[34:35]
	v_cvt_pk_bf16_f32 v40, v85, v61
	v_cvt_pk_bf16_f32 v41, v62, v63
	v_cvt_pk_bf16_f32 v42, v80, v81
	v_cvt_pk_bf16_f32 v43, v82, v83
	v_cndmask_b32_e64 v89, v48, 0, s[44:45]
	v_cndmask_b32_e64 v149, v16, 0, s[52:53]
	v_pk_mul_f32 v[50:51], v[98:99], v[84:85] op_sel_hi:[1,0]
	v_pk_mul_f32 v[48:49], v[96:97], v[84:85] op_sel_hi:[1,0]
	v_cvt_pk_bf16_f32 v16, v86, v87
	v_cvt_pk_bf16_f32 v17, v88, v89
	v_cvt_pk_bf16_f32 v18, v90, v91
	v_cvt_pk_bf16_f32 v19, v148, v149
	s_waitcnt lgkmcnt(10)
	v_mfma_f32_16x16x32_bf16 v[64:67], v[140:143], v[40:43], v[48:51]
	s_cselect_b64 s[38:39], -1, 0
	s_add_i32 s0, s76, 0xfffffc00
	s_min_i32 s1, s0, 0
	v_pk_mul_f32 v[50:51], v[102:103], v[60:61] op_sel_hi:[1,0]
	v_pk_mul_f32 v[48:49], v[100:101], v[60:61] op_sel_hi:[1,0]
	s_sub_i32 s1, 15, s1
	s_ashr_i32 s1, s1, 4
	v_mfma_f32_16x16x32_bf16 v[100:103], v[140:143], v[16:19], v[48:51]
	s_sub_i32 s0, s75, s0
	s_ashr_i32 s0, s0, 4
	s_or_b32 s40, s76, 8
	v_pk_mul_f32 v[50:51], v[106:107], v[84:85] op_sel_hi:[1,0]
	v_pk_mul_f32 v[48:49], v[104:105], v[84:85] op_sel_hi:[1,0]
	s_lshl_b32 s56, s56, 7
	s_add_i32 s71, s71, s78
	s_waitcnt lgkmcnt(8)
	v_mfma_f32_16x16x32_bf16 v[104:107], v[136:139], v[40:43], v[48:51]
	s_nop 2
	v_mul_f32_e64 v50, v110, v60
	v_mul_f32_e64 v51, v111, v60
	v_pk_mul_f32 v[48:49], v[108:109], v[60:61] op_sel_hi:[1,0]
	s_nop 1
	v_mfma_f32_16x16x32_bf16 v[108:111], v[136:139], v[16:19], v[48:51]
	s_nop 2
	v_mul_f32_e64 v50, v114, v84
	v_mul_f32_e64 v51, v115, v84
	v_pk_mul_f32 v[48:49], v[112:113], v[84:85] op_sel_hi:[1,0]
	s_waitcnt lgkmcnt(6)
	s_nop 0
	v_mfma_f32_16x16x32_bf16 v[112:115], v[132:135], v[40:43], v[48:51]
	s_nop 2
	v_mul_f32_e64 v50, v118, v60
	v_mul_f32_e64 v51, v119, v60
	v_pk_mul_f32 v[48:49], v[116:117], v[60:61] op_sel_hi:[1,0]
	s_nop 1
	v_mfma_f32_16x16x32_bf16 v[116:119], v[132:135], v[16:19], v[48:51]
	s_nop 2
	v_mul_f32_e64 v50, v122, v84
	v_mul_f32_e64 v51, v123, v84
	v_pk_mul_f32 v[48:49], v[120:121], v[84:85] op_sel_hi:[1,0]
	s_waitcnt lgkmcnt(4)
	s_nop 0
	v_mfma_f32_16x16x32_bf16 v[120:123], v[128:131], v[40:43], v[48:51]
	v_mul_f32_e64 v42, v126, v60
	v_mul_f32_e64 v43, v127, v60
	v_pk_mul_f32 v[40:41], v[124:125], v[60:61] op_sel_hi:[1,0]
	s_nop 1
	v_mfma_f32_16x16x32_bf16 v[124:127], v[128:131], v[16:19], v[40:43]
	v_add_f32_e32 v16, 0, v86
	v_add_f32_e32 v16, v87, v16
	v_add_f32_e32 v16, v88, v16
	v_add_f32_e32 v16, v89, v16
	v_add_f32_e32 v16, v90, v16
	v_add_f32_e32 v16, v91, v16
	v_add_f32_e32 v16, v148, v16
	v_add_f32_e32 v151, v149, v16
	v_add_f32_e32 v16, 0, v85
	v_add_f32_e32 v16, v61, v16
	v_add_f32_e32 v16, v62, v16
	v_add_f32_e32 v16, v63, v16
	v_add_f32_e32 v16, v80, v16
	v_add_f32_e32 v16, v81, v16
	v_add_f32_e32 v16, v82, v16
	v_fmac_f32_e32 v151, v145, v60
	v_add_f32_e32 v145, v83, v16
	v_add_u32_e32 v16, s76, v213
	v_fmac_f32_e32 v145, v144, v84
	v_ashrrev_i32_e32 v148, 4, v250
	v_med3_i32 v16, v16, 0, s75
	v_lshl_add_u32 v16, v16, 9, v152
	global_load_dwordx4 v[80:83], v16, s[98:99]
	v_add_u32_e32 v16, s76, v215
	v_max_i32_e32 v150, s1, v148
	s_nop 0
	v_med3_i32 v16, v16, 0, s75
	v_lshl_add_u32 v16, v16, 9, v152
	global_load_dwordx4 v[84:87], v16, s[98:99]
	v_add_u32_e32 v16, s76, v217
	v_med3_i32 v16, v16, 0, s75
	v_lshl_add_u32 v16, v16, 9, v152
	global_load_dwordx4 v[88:91], v16, s[98:99]
	v_add_u32_e32 v16, s76, v219
	v_med3_i32 v16, v16, 0, s75
	v_lshl_add_u32 v16, v16, 9, v152
	global_load_dwordx4 v[96:99], v16, s[98:99]
	v_min_i32_e32 v16, s75, v251
	v_cndmask_b32_e64 v16, v16, 0, s[38:39]
	v_lshl_add_u32 v16, v16, 9, v158
	global_load_dwordx4 v[48:51], v16, s[100:101]
	global_load_dwordx4 v[60:63], v16, s[100:101] offset:64
	v_add_u32_e32 v16, s76, v228
	v_med3_i32 v16, v16, 0, s75
	v_lshl_add_u32 v16, v16, 9, v158
	global_load_dwordx4 v[40:43], v16, s[100:101]
	s_nop 0
	global_load_dwordx4 v[16:19], v16, s[100:101] offset:64
	ds_read_b64_tr_b16 v[142:143], v169 offset:2304
	ds_read_b64_tr_b16 v[140:141], v169
	ds_read_b64_tr_b16 v[136:137], v169 offset:32
	ds_read_b64_tr_b16 v[138:139], v169 offset:2336
	ds_read_b64_tr_b16 v[132:133], v169 offset:64
	ds_read_b64_tr_b16 v[134:135], v169 offset:2368
	ds_read_b64_tr_b16 v[128:129], v169 offset:96
	ds_read_b64_tr_b16 v[130:131], v169 offset:2400
	s_waitcnt vmcnt(15)
	ds_write_b128 v241, v[68:71] offset:4608
	s_waitcnt vmcnt(14)
	ds_write_b128 v242, v[72:75] offset:4608
	s_waitcnt vmcnt(13)
	ds_write_b128 v243, v[76:79] offset:4608
	s_waitcnt vmcnt(12)
	ds_write_b128 v244, v[92:95] offset:4608
	v_mfma_f32_16x16x32_bf16 v[72:75], v[32:35], v[4:7], 0
	v_mfma_f32_16x16x32_bf16 v[68:71], v[56:59], v[4:7], 0
	v_mfma_f32_16x16x32_bf16 v[72:75], v[24:27], v[8:11], v[72:75]
	v_mfma_f32_16x16x32_bf16 v[68:71], v[36:39], v[8:11], v[68:71]
	s_nop 5
	v_add_u32_e32 v25, 0x800, v250
	v_ashrrev_i32_e32 v25, 4, v25
	v_min3_i32 v25, v25, s0, v248
	v_sub_u32_e32 v26, v154, v150
	v_sub_u32_e32 v149, v25, v150
	v_add_u32_e32 v27, 1, v26
	v_cmp_gt_u32_e64 s[0:1], v27, v149
	v_cmp_gt_u32_e32 vcc, v26, v149
	s_nop 0
	v_cndmask_b32_e64 v69, v69, v246, s[0:1]
	s_nop 0
	v_cndmask_b32_e32 v68, v68, v246, vcc
	v_max_f32_e32 v25, 0xf149f2ca, v68
	v_max_f32_e32 v25, v25, v69
	v_add_u32_e32 v27, 2, v26
	v_add_u32_e32 v32, 3, v26
	v_cmp_gt_u32_e64 s[22:23], v27, v149
	v_cmp_gt_u32_e64 s[24:25], v32, v149
	s_nop 0
	v_cndmask_b32_e64 v70, v70, v246, s[22:23]
	s_nop 0
	v_cndmask_b32_e64 v71, v71, v246, s[24:25]
	v_max3_f32 v25, v25, v70, v71
	v_add_u32_e32 v27, 16, v26
	v_add_u32_e32 v32, 17, v26
	v_cmp_gt_u32_e64 s[26:27], v27, v149
	v_cmp_gt_u32_e64 s[28:29], v32, v149
	s_nop 0
	v_cndmask_b32_e64 v72, v72, v246, s[26:27]
	v_cndmask_b32_e64 v73, v73, v246, s[28:29]
	v_max3_f32 v25, v25, v72, v73
	v_add_u32_e32 v27, 18, v26
	v_add_u32_e32 v26, 19, v26
	v_cmp_gt_u32_e64 s[30:31], v27, v149
	v_cmp_gt_u32_e64 s[34:35], v26, v149
	s_nop 0
	v_cndmask_b32_e64 v74, v74, v246, s[30:31]
	v_cndmask_b32_e64 v75, v75, v246, s[34:35]
	v_max3_f32 v25, v25, v74, v75
	v_mov_b32_e32 v27, v25
	s_nop 1
	v_permlane32_swap_b32_e32 v27, v25
	v_max_f32_e32 v25, v25, v27
	s_nop 1
	v_mov_b32_e32 v27, v25
	s_nop 1
	v_permlane16_swap_b32_e32 v27, v25
	v_max3_f32 v144, v147, v25, v27
	v_sub_f32_e32 v25, v147, v144
	v_exp_f32_e32 v56, v25
	v_sub_f32_e32 v25, v68, v144
	v_exp_f32_e32 v25, v25
	v_sub_f32_e32 v32, v69, v144
	v_exp_f32_e32 v32, v32
	v_sub_f32_e32 v33, v70, v144
	v_exp_f32_e32 v33, v33
	v_sub_f32_e32 v34, v71, v144
	v_exp_f32_e32 v34, v34
	v_sub_f32_e32 v35, v72, v144
	v_exp_f32_e32 v35, v35
	v_sub_f32_e32 v38, v73, v144
	v_add_f32_e32 v27, 0, v25
	v_exp_f32_e32 v38, v38
	v_sub_f32_e32 v39, v74, v144
	v_add_f32_e32 v27, v32, v27
	v_exp_f32_e32 v39, v39
	v_sub_f32_e32 v57, v75, v144
	v_add_f32_e32 v27, v33, v27
	v_exp_f32_e32 v57, v57
	v_add_f32_e32 v27, v34, v27
	v_add_f32_e32 v27, v35, v27
	v_add_f32_e32 v27, v38, v27
	v_add_f32_e32 v27, v39, v27
	v_add_f32_e32 v147, v57, v27
	v_fmac_f32_e32 v147, v145, v56
	v_mov_b32_e32 v145, v146
	v_cvt_pk_bf16_f32 v32, v25, v32
	v_mov_b32_e32 v58, 1.0
	v_cvt_pk_bf16_f32 v33, v33, v34
	v_mov_b32_e32 v25, 0
	v_cvt_pk_bf16_f32 v34, v35, v38
	v_cvt_pk_bf16_f32 v35, v39, v57
	v_add_f32_e32 v26, 0, v25
	v_mov_b32_e32 v27, 0
	v_pk_mul_f32 v[38:39], v[66:67], v[56:57] op_sel_hi:[1,0]
	v_pk_mul_f32 v[36:37], v[64:65], v[56:57] op_sel_hi:[1,0]
	v_add_f32_e32 v146, v27, v26
	v_cvt_pk_bf16_f32 v24, v25, 0
	v_cvt_pk_bf16_f32 v26, v27, 0
	v_mov_b32_e32 v25, v153
	v_mov_b32_e32 v27, v153
	s_waitcnt lgkmcnt(10)
	v_mfma_f32_16x16x32_bf16 v[76:79], v[140:143], v[32:35], v[36:39]
	v_fmac_f32_e32 v146, v151, v58
	s_nop 1
	v_pk_mul_f32 v[38:39], v[102:103], v[58:59] op_sel_hi:[1,0]
	v_pk_mul_f32 v[36:37], v[100:101], v[58:59] op_sel_hi:[1,0]
	s_nop 1
	v_mfma_f32_16x16x32_bf16 v[100:103], v[140:143], v[24:27], v[36:39]
	s_nop 2
	v_mul_f32_e64 v38, v106, v56
	v_mul_f32_e64 v39, v107, v56
	v_pk_mul_f32 v[36:37], v[104:105], v[56:57] op_sel_hi:[1,0]
	s_waitcnt lgkmcnt(8)
	s_nop 0
	v_mfma_f32_16x16x32_bf16 v[104:107], v[136:139], v[32:35], v[36:39]
	s_nop 2
	v_mul_f32_e64 v38, v110, v58
	v_mul_f32_e64 v39, v111, v58
	v_pk_mul_f32 v[36:37], v[108:109], v[58:59] op_sel_hi:[1,0]
	s_nop 1
	v_mfma_f32_16x16x32_bf16 v[108:111], v[136:139], v[24:27], v[36:39]
	s_nop 2
	v_mul_f32_e64 v38, v114, v56
	v_mul_f32_e64 v39, v115, v56
	v_pk_mul_f32 v[36:37], v[112:113], v[56:57] op_sel_hi:[1,0]
	s_waitcnt lgkmcnt(6)
	s_nop 0
	v_mfma_f32_16x16x32_bf16 v[112:115], v[132:135], v[32:35], v[36:39]
	s_nop 2
	v_mul_f32_e64 v38, v118, v58
	v_mul_f32_e64 v39, v119, v58
	v_pk_mul_f32 v[36:37], v[116:117], v[58:59] op_sel_hi:[1,0]
	s_nop 1
	v_mfma_f32_16x16x32_bf16 v[116:119], v[132:135], v[24:27], v[36:39]
	s_nop 2
	v_mul_f32_e64 v38, v122, v56
	v_mul_f32_e64 v39, v123, v56
	v_pk_mul_f32 v[36:37], v[120:121], v[56:57] op_sel_hi:[1,0]
	v_add_u32_e32 v56, s76, v232
	s_waitcnt lgkmcnt(4)
	v_mfma_f32_16x16x32_bf16 v[120:123], v[128:131], v[32:35], v[36:39]
	v_mul_f32_e64 v34, v126, v58
	v_mul_f32_e64 v35, v127, v58
	v_pk_mul_f32 v[32:33], v[124:125], v[58:59] op_sel_hi:[1,0]
	v_add_u32_e32 v36, s76, v231
	s_nop 0
	v_mfma_f32_16x16x32_bf16 v[124:127], v[128:131], v[24:27], v[32:35]
	v_add_u32_e32 v24, s76, v229
	s_nop 1
	v_add_u32_e32 v32, s76, v230
	v_med3_i32 v24, v24, 0, s75
	v_med3_i32 v32, v32, 0, s75
	v_med3_i32 v36, v36, 0, s75
	v_med3_i32 v56, v56, 0, s75
	v_lshl_add_u32 v36, v36, 9, v152
	v_lshl_add_u32 v56, v56, 9, v152
	global_load_dwordx4 v[36:39], v36, s[98:99]
	global_load_dwordx4 v[92:95], v56, s[98:99]
	v_add_u32_e32 v56, s76, v233
	v_med3_i32 v56, v56, 0, s75
	v_lshl_add_u32 v24, v24, 9, v152
	v_lshl_add_u32 v32, v32, 9, v152
	v_lshl_add_u32 v56, v56, 9, v158
	global_load_dwordx4 v[24:27], v24, s[98:99]
	s_nop 0
	global_load_dwordx4 v[32:35], v32, s[98:99]
	s_nop 0
	global_load_dwordx4 v[72:75], v56, s[100:101]
	global_load_dwordx4 v[68:71], v56, s[100:101] offset:64
	v_add_u32_e32 v56, s76, v234
	v_med3_i32 v56, v56, 0, s75
	v_lshl_add_u32 v56, v56, 9, v158
	global_load_dwordx4 v[64:67], v56, s[100:101]
	s_nop 0
	global_load_dwordx4 v[56:59], v56, s[100:101] offset:64
	ds_read_b64_tr_b16 v[142:143], v169 offset:6912
	ds_read_b64_tr_b16 v[140:141], v169 offset:4608
	ds_read_b64_tr_b16 v[136:137], v169 offset:4640
	ds_read_b64_tr_b16 v[138:139], v169 offset:6944
	ds_read_b64_tr_b16 v[132:133], v169 offset:4672
	ds_read_b64_tr_b16 v[134:135], v169 offset:6976
	ds_read_b64_tr_b16 v[128:129], v169 offset:4704
	ds_read_b64_tr_b16 v[130:131], v169 offset:7008
	s_waitcnt vmcnt(15)
	ds_write_b128 v241, v[80:83]
	s_waitcnt vmcnt(14)
	ds_write_b128 v242, v[84:87]
	s_waitcnt vmcnt(13)
	ds_write_b128 v243, v[88:91]
	s_waitcnt vmcnt(12)
	ds_write_b128 v244, v[96:99]
	v_mfma_f32_16x16x32_bf16 v[80:83], v[52:55], v[4:7], 0
	v_mfma_f32_16x16x32_bf16 v[84:87], v[28:31], v[4:7], 0
	v_mfma_f32_16x16x32_bf16 v[80:83], v[44:47], v[8:11], v[80:83]
	v_mfma_f32_16x16x32_bf16 v[84:87], v[20:23], v[8:11], v[84:87]
	s_nop 5
	v_sub_u32_e32 v21, v187, v150
	v_add_u32_e32 v23, 1, v21
	v_cmp_gt_u32_e64 s[0:1], v23, v149
	v_cmp_gt_u32_e32 vcc, v21, v149
	s_nop 0
	v_cndmask_b32_e64 v81, v81, v246, s[0:1]
	s_nop 0
	v_cndmask_b32_e32 v80, v80, v246, vcc
	v_max_f32_e32 v22, 0xf149f2ca, v80
	v_max_f32_e32 v22, v22, v81
	v_add_u32_e32 v23, 2, v21
	v_add_u32_e32 v28, 3, v21
	v_cmp_gt_u32_e64 s[22:23], v23, v149
	v_cmp_gt_u32_e64 s[24:25], v28, v149
	s_nop 0
	v_cndmask_b32_e64 v82, v82, v246, s[22:23]
	v_cndmask_b32_e64 v83, v83, v246, s[24:25]
	v_max3_f32 v22, v22, v82, v83
	v_add_u32_e32 v23, 16, v21
	v_add_u32_e32 v28, 17, v21
	v_cmp_gt_u32_e64 s[26:27], v23, v149
	v_cmp_gt_u32_e64 s[28:29], v28, v149
	s_nop 0
	v_cndmask_b32_e64 v84, v84, v246, s[26:27]
	v_cndmask_b32_e64 v85, v85, v246, s[28:29]
	v_max3_f32 v22, v22, v84, v85
	v_add_u32_e32 v23, 18, v21
	v_add_u32_e32 v21, 19, v21
	v_cmp_gt_u32_e64 s[30:31], v23, v149
	v_cmp_gt_u32_e64 s[34:35], v21, v149
	s_nop 0
	v_cndmask_b32_e64 v86, v86, v246, s[30:31]
	v_cndmask_b32_e64 v87, v87, v246, s[34:35]
	v_max3_f32 v21, v22, v86, v87
	v_mov_b32_e32 v23, v21
	s_nop 1
	v_permlane32_swap_b32_e32 v23, v21
	v_max_f32_e32 v21, v21, v23
	s_nop 1
	v_mov_b32_e32 v23, v21
	s_nop 1
	v_permlane16_swap_b32_e32 v23, v21
	v_max3_f32 v175, v144, v21, v23
	v_sub_f32_e32 v21, v144, v175
	v_exp_f32_e32 v144, v21
	v_sub_f32_e32 v21, v80, v175
	v_sub_f32_e32 v28, v81, v175
	v_exp_f32_e32 v21, v21
	v_exp_f32_e32 v28, v28
	v_sub_f32_e32 v30, v82, v175
	v_exp_f32_e32 v30, v30
	v_sub_f32_e32 v31, v83, v175
	v_exp_f32_e32 v31, v31
	v_sub_f32_e32 v45, v84, v175
	v_exp_f32_e32 v45, v45
	v_sub_f32_e32 v46, v85, v175
	v_mov_b32_e32 v176, v145
	v_add_f32_e32 v23, 0, v21
	v_exp_f32_e32 v46, v46
	v_sub_f32_e32 v47, v86, v175
	v_cvt_pk_bf16_f32 v80, v21, v28
	v_add_f32_e32 v23, v28, v23
	v_exp_f32_e32 v47, v47
	v_sub_f32_e32 v52, v87, v175
	v_mov_b32_e32 v84, 1.0
	v_add_f32_e32 v23, v30, v23
	v_exp_f32_e32 v52, v52
	v_add_f32_e32 v23, v31, v23
	v_add_f32_e32 v23, v45, v23
	v_add_f32_e32 v23, v46, v23
	v_add_f32_e32 v23, v47, v23
	v_mov_b32_e32 v21, 0
	v_add_f32_e32 v151, v52, v23
	v_add_f32_e32 v22, 0, v21
	v_mov_b32_e32 v23, 0
	v_fmac_f32_e32 v151, v147, v144
	v_cvt_pk_bf16_f32 v81, v30, v31
	v_add_f32_e32 v147, v23, v22
	v_cvt_pk_bf16_f32 v20, v21, 0
	v_cvt_pk_bf16_f32 v22, v23, 0
	v_mov_b32_e32 v21, v153
	v_mov_b32_e32 v23, v153
	v_pk_mul_f32 v[30:31], v[78:79], v[144:145] op_sel_hi:[1,0]
	v_pk_mul_f32 v[28:29], v[76:77], v[144:145] op_sel_hi:[1,0]
	v_pk_mul_f32 v[78:79], v[110:111], v[84:85] op_sel_hi:[1,0]
	v_pk_mul_f32 v[76:77], v[108:109], v[84:85] op_sel_hi:[1,0]
	v_cvt_pk_bf16_f32 v82, v45, v46
	v_cvt_pk_bf16_f32 v83, v47, v52
	s_waitcnt lgkmcnt(8)
	v_mfma_f32_16x16x32_bf16 v[88:91], v[136:139], v[20:23], v[76:79]
	v_mul_f32_e64 v46, v102, v84
	v_mul_f32_e64 v47, v103, v84
	v_pk_mul_f32 v[44:45], v[100:101], v[84:85] op_sel_hi:[1,0]
	v_pk_mul_f32 v[54:55], v[106:107], v[144:145] op_sel_hi:[1,0]
	v_pk_mul_f32 v[78:79], v[114:115], v[144:145] op_sel_hi:[1,0]
	v_pk_mul_f32 v[76:77], v[112:113], v[144:145] op_sel_hi:[1,0]
	v_pk_mul_f32 v[52:53], v[104:105], v[144:145] op_sel_hi:[1,0]
	v_mfma_f32_16x16x32_bf16 v[44:47], v[140:143], v[20:23], v[44:47]
	v_fmac_f32_e32 v147, v146, v84
	s_waitcnt lgkmcnt(6)
	v_mfma_f32_16x16x32_bf16 v[96:99], v[132:135], v[80:83], v[76:79]
	s_nop 2
	v_mul_f32_e64 v78, v118, v84
	v_mul_f32_e64 v79, v119, v84
	v_pk_mul_f32 v[76:77], v[116:117], v[84:85] op_sel_hi:[1,0]
	v_mfma_f32_16x16x32_bf16 v[28:31], v[140:143], v[80:83], v[28:31]
	s_nop 0
	v_mfma_f32_16x16x32_bf16 v[100:103], v[132:135], v[20:23], v[76:79]
	s_nop 2
	v_mul_f32_e64 v78, v122, v144
	v_mul_f32_e64 v79, v123, v144
	v_pk_mul_f32 v[76:77], v[120:121], v[144:145] op_sel_hi:[1,0]
	v_mfma_f32_16x16x32_bf16 v[52:55], v[136:139], v[80:83], v[52:55]
	s_waitcnt lgkmcnt(4)
	v_mfma_f32_16x16x32_bf16 v[104:107], v[128:131], v[80:83], v[76:79]
	s_nop 2
	v_mul_f32_e64 v78, v126, v84
	v_mul_f32_e64 v79, v127, v84
	v_pk_mul_f32 v[76:77], v[124:125], v[84:85] op_sel_hi:[1,0]
	s_nop 1
	v_mfma_f32_16x16x32_bf16 v[108:111], v[128:131], v[20:23], v[76:79]
	v_add_u32_e32 v20, s76, v235
	v_med3_i32 v20, v20, 0, s75
	v_lshl_add_u32 v20, v20, 9, v152
	global_load_dwordx4 v[112:115], v20, s[98:99]
	v_add_u32_e32 v20, s76, v236
	v_med3_i32 v20, v20, 0, s75
	v_lshl_add_u32 v20, v20, 9, v152
	global_load_dwordx4 v[116:119], v20, s[98:99]
	v_add_u32_e32 v20, s76, v237
	v_med3_i32 v20, v20, 0, s75
	v_lshl_add_u32 v20, v20, 9, v152
	global_load_dwordx4 v[120:123], v20, s[98:99]
	v_add_u32_e32 v20, s76, v238
	v_med3_i32 v20, v20, 0, s75
	v_lshl_add_u32 v20, v20, 9, v152
	global_load_dwordx4 v[124:127], v20, s[98:99]
	v_add_u32_e32 v20, s76, v239
	v_med3_i32 v20, v20, 0, s75
	v_lshl_add_u32 v20, v20, 9, v158
	global_load_dwordx4 v[84:87], v20, s[100:101]
	global_load_dwordx4 v[80:83], v20, s[100:101] offset:64
	v_add_u32_e32 v20, s76, v240
	s_addk_i32 s76, 0xfc08
	s_nop 0
	v_med3_i32 v20, v20, 0, s75
	v_lshl_add_u32 v20, v20, 9, v158
	global_load_dwordx4 v[76:79], v20, s[100:101]
	s_nop 0
	global_load_dwordx4 v[20:23], v20, s[100:101] offset:64
	ds_read_b64_tr_b16 v[142:143], v169 offset:2304
	ds_read_b64_tr_b16 v[140:141], v169
	ds_read_b64_tr_b16 v[136:137], v169 offset:32
	ds_read_b64_tr_b16 v[138:139], v169 offset:2336
	ds_read_b64_tr_b16 v[132:133], v169 offset:64
	ds_read_b64_tr_b16 v[134:135], v169 offset:2368
	ds_read_b64_tr_b16 v[128:129], v169 offset:96
	ds_read_b64_tr_b16 v[130:131], v169 offset:2400
	s_waitcnt vmcnt(13)
	ds_write_b128 v241, v[24:27] offset:4608
	s_waitcnt vmcnt(12)
	ds_write_b128 v242, v[32:35] offset:4608
	ds_write_b128 v243, v[36:39] offset:4608
	ds_write_b128 v244, v[92:95] offset:4608
	v_mfma_f32_16x16x32_bf16 v[24:27], v[48:51], v[4:7], 0
	v_mfma_f32_16x16x32_bf16 v[32:35], v[40:43], v[4:7], 0
	v_mfma_f32_16x16x32_bf16 v[24:27], v[60:63], v[8:11], v[24:27]
	v_mfma_f32_16x16x32_bf16 v[32:35], v[16:19], v[8:11], v[32:35]
	s_nop 7
	v_sub_u32_e32 v17, v192, v150
	v_add_u32_e32 v19, 1, v17
	v_cmp_gt_u32_e64 s[0:1], v19, v149
	v_cmp_gt_u32_e32 vcc, v17, v149
	s_nop 0
	v_cndmask_b32_e64 v25, v25, v246, s[0:1]
	s_nop 0
	v_cndmask_b32_e32 v24, v24, v246, vcc
	v_max_f32_e32 v18, 0xf149f2ca, v24
	v_max_f32_e32 v18, v18, v25
	v_add_u32_e32 v19, 2, v17
	v_add_u32_e32 v37, 3, v17
	v_cmp_gt_u32_e64 s[22:23], v19, v149
	v_cmp_gt_u32_e64 s[24:25], v37, v149
	s_nop 0
	v_cndmask_b32_e64 v26, v26, v246, s[22:23]
	v_cndmask_b32_e64 v27, v27, v246, s[24:25]
	v_max3_f32 v18, v18, v26, v27
	v_add_u32_e32 v19, 16, v17
	v_add_u32_e32 v37, 17, v17
	v_cmp_gt_u32_e64 s[26:27], v19, v149
	v_cmp_gt_u32_e64 s[28:29], v37, v149
	s_nop 0
	v_cndmask_b32_e64 v32, v32, v246, s[26:27]
	v_cndmask_b32_e64 v33, v33, v246, s[28:29]
	v_max3_f32 v18, v18, v32, v33
	v_add_u32_e32 v19, 18, v17
	v_add_u32_e32 v17, 19, v17
	v_cmp_gt_u32_e64 s[30:31], v19, v149
	v_cmp_gt_u32_e64 s[34:35], v17, v149
	s_nop 0
	v_cndmask_b32_e64 v34, v34, v246, s[30:31]
	v_cndmask_b32_e64 v35, v35, v246, s[34:35]
	v_max3_f32 v17, v18, v34, v35
	v_mov_b32_e32 v19, v17
	s_nop 1
	v_permlane32_swap_b32_e32 v19, v17
	v_max_f32_e32 v17, v17, v19
	s_nop 1
	v_mov_b32_e32 v19, v17
	s_nop 1
	v_permlane16_swap_b32_e32 v19, v17
	v_max3_f32 v145, v175, v17, v19
	v_sub_f32_e32 v17, v175, v145
	v_exp_f32_e32 v38, v17
	v_sub_f32_e32 v17, v24, v145
	v_exp_f32_e32 v17, v17
	s_nop 1
	v_cndmask_b32_e64 v37, v17, 0, vcc
	v_sub_f32_e32 v17, v25, v145
	v_exp_f32_e32 v17, v17
	v_mov_b32_e32 v144, v176
	v_cndmask_b32_e64 v60, v17, 0, s[0:1]
	v_sub_f32_e32 v17, v26, v145
	v_exp_f32_e32 v17, v17
	v_cvt_pk_bf16_f32 v24, v37, v60
	v_cndmask_b32_e64 v61, v17, 0, s[22:23]
	v_sub_f32_e32 v17, v27, v145
	v_exp_f32_e32 v17, v17
	v_mov_b32_e32 v39, 0
	v_pk_mul_f32 v[30:31], v[30:31], v[38:39] op_sel_hi:[1,0]
	v_pk_mul_f32 v[28:29], v[28:29], v[38:39] op_sel_hi:[1,0]
	v_cndmask_b32_e64 v62, v17, 0, s[24:25]
	v_sub_f32_e32 v17, v32, v145
	v_exp_f32_e32 v17, v17
	v_cvt_pk_bf16_f32 v25, v61, v62
	v_cvt_pk_bf16_f32 v18, v39, 0
	v_mov_b32_e32 v19, v153
	v_cndmask_b32_e64 v63, v17, 0, s[26:27]
	v_sub_f32_e32 v17, v33, v145
	v_exp_f32_e32 v17, v17
	s_nop 0
	v_cndmask_b32_e64 v33, v17, 0, s[28:29]
	v_sub_f32_e32 v17, v34, v145
	v_exp_f32_e32 v17, v17
	v_cvt_pk_bf16_f32 v26, v63, v33
	v_cndmask_b32_e64 v34, v17, 0, s[30:31]
	v_sub_f32_e32 v17, v35, v145
	v_exp_f32_e32 v17, v17
	s_nop 0
	v_cndmask_b32_e64 v35, v17, 0, s[34:35]
	v_mov_b32_e32 v32, 1.0
	v_cvt_pk_bf16_f32 v27, v34, v35
	v_mov_b32_e32 v36, 0
	v_cvt_pk_bf16_f32 v16, v36, 0
	v_mov_b32_e32 v17, v153
	s_waitcnt lgkmcnt(10)
	v_mfma_f32_16x16x32_bf16 v[40:43], v[140:143], v[24:27], v[28:31]
	s_nop 2
	v_mul_f32_e64 v30, v46, v32
	v_mul_f32_e64 v31, v47, v32
	v_pk_mul_f32 v[28:29], v[44:45], v[32:33] op_sel_hi:[1,0]
	s_nop 1
	v_mfma_f32_16x16x32_bf16 v[44:47], v[140:143], v[16:19], v[28:31]
	s_nop 2
	v_mul_f32_e64 v30, v54, v38
	v_mul_f32_e64 v31, v55, v38
	v_pk_mul_f32 v[28:29], v[52:53], v[38:39] op_sel_hi:[1,0]
	s_waitcnt lgkmcnt(8)
	s_nop 0
	v_mfma_f32_16x16x32_bf16 v[48:51], v[136:139], v[24:27], v[28:31]
	s_nop 2
	v_mul_f32_e64 v30, v90, v32
	v_mul_f32_e64 v31, v91, v32
	v_pk_mul_f32 v[28:29], v[88:89], v[32:33] op_sel_hi:[1,0]
	s_nop 1
	v_mfma_f32_16x16x32_bf16 v[52:55], v[136:139], v[16:19], v[28:31]
	s_nop 2
	v_mul_f32_e64 v30, v98, v38
	v_mul_f32_e64 v31, v99, v38
	v_pk_mul_f32 v[28:29], v[96:97], v[38:39] op_sel_hi:[1,0]
	s_waitcnt lgkmcnt(6)
	s_nop 0
	v_mfma_f32_16x16x32_bf16 v[88:91], v[132:135], v[24:27], v[28:31]
	s_nop 2
	v_mul_f32_e64 v30, v102, v32
	v_mul_f32_e64 v31, v103, v32
	v_pk_mul_f32 v[28:29], v[100:101], v[32:33] op_sel_hi:[1,0]
	s_nop 1
	v_mfma_f32_16x16x32_bf16 v[100:103], v[132:135], v[16:19], v[28:31]
	s_nop 2
	v_mul_f32_e64 v30, v106, v38
	v_mul_f32_e64 v31, v107, v38
	v_pk_mul_f32 v[28:29], v[104:105], v[38:39] op_sel_hi:[1,0]
	s_waitcnt lgkmcnt(4)
	s_nop 0
	v_mfma_f32_16x16x32_bf16 v[104:107], v[128:131], v[24:27], v[28:31]
	v_mul_f32_e64 v26, v110, v32
	v_mul_f32_e64 v27, v111, v32
	v_pk_mul_f32 v[24:25], v[108:109], v[32:33] op_sel_hi:[1,0]
	s_nop 1
	v_mfma_f32_16x16x32_bf16 v[108:111], v[128:131], v[16:19], v[24:27]
	v_add_f32_e32 v16, 0, v36
	v_add_f32_e32 v146, v39, v16
	v_add_f32_e32 v16, 0, v37
	v_add_f32_e32 v16, v60, v16
	v_add_f32_e32 v16, v61, v16
	v_add_f32_e32 v16, v62, v16
	v_add_f32_e32 v16, v63, v16
	v_add_f32_e32 v16, v33, v16
	v_add_f32_e32 v16, v34, v16
	v_fmac_f32_e32 v146, v147, v32
	v_add_f32_e32 v147, v35, v16
	v_add_u32_e32 v16, s40, v214
	v_add_u32_e32 v24, s40, v216
	v_med3_i32 v16, v16, 0, s75
	v_med3_i32 v24, v24, 0, s75
	v_lshl_add_u32 v16, v16, 9, v152
	v_lshl_add_u32 v24, v24, 9, v152
	global_load_dwordx4 v[16:19], v16, s[98:99]
	v_or_b32_e32 v32, 0xfffffd00, v167
	global_load_dwordx4 v[60:63], v24, s[98:99]
	v_add_u32_e32 v24, s40, v218
	v_add_u32_e32 v32, s40, v32
	v_med3_i32 v24, v24, 0, s75
	v_lshl_add_u32 v24, v24, 9, v152
	global_load_dwordx4 v[92:95], v24, s[98:99]
	v_add_u32_e32 v24, s40, v220
	v_fmac_f32_e32 v147, v151, v38
	s_nop 0
	v_med3_i32 v24, v24, 0, s75
	v_lshl_add_u32 v24, v24, 9, v152
	global_load_dwordx4 v[96:99], v24, s[98:99]
	v_add_u32_e32 v24, s40, v221
	v_med3_i32 v24, v24, 0, s75
	v_med3_i32 v32, v32, 0, s75
	v_lshl_add_u32 v28, v24, 9, v158
	v_lshl_add_u32 v36, v32, 9, v158
	global_load_dwordx4 v[24:27], v28, s[100:101]
	s_nop 0
	global_load_dwordx4 v[28:31], v28, s[100:101] offset:64
	s_nop 0
	global_load_dwordx4 v[32:35], v36, s[100:101]
	s_nop 0
	global_load_dwordx4 v[36:39], v36, s[100:101] offset:64
	ds_read_b64_tr_b16 v[142:143], v169 offset:6912
	ds_read_b64_tr_b16 v[140:141], v169 offset:4608
	ds_read_b64_tr_b16 v[132:133], v169 offset:4640
	ds_read_b64_tr_b16 v[134:135], v169 offset:6944
	ds_read_b64_tr_b16 v[128:129], v169 offset:4672
	ds_read_b64_tr_b16 v[130:131], v169 offset:6976
	ds_read_b64_tr_b16 v[136:137], v169 offset:4704
	ds_read_b64_tr_b16 v[138:139], v169 offset:7008
	s_waitcnt vmcnt(15)
	ds_write_b128 v241, v[112:115]
	s_waitcnt vmcnt(14)
	ds_write_b128 v242, v[116:119]
	s_waitcnt vmcnt(13)
	ds_write_b128 v243, v[120:123]
	s_waitcnt vmcnt(12)
	ds_write_b128 v244, v[124:127]
	v_mfma_f32_16x16x32_bf16 v[112:115], v[72:75], v[4:7], 0
	v_mfma_f32_16x16x32_bf16 v[116:119], v[64:67], v[4:7], 0
	v_mfma_f32_16x16x32_bf16 v[112:115], v[68:71], v[8:11], v[112:115]
	v_mfma_f32_16x16x32_bf16 v[116:119], v[56:59], v[8:11], v[116:119]
	s_nop 5
	v_sub_u32_e32 v57, v197, v150
	v_add_u32_e32 v59, 1, v57
	v_cmp_gt_u32_e64 s[0:1], v59, v149
	v_cmp_gt_u32_e32 vcc, v57, v149
	s_nop 0
	v_cndmask_b32_e64 v113, v113, v246, s[0:1]
	s_nop 0
	v_cndmask_b32_e32 v112, v112, v246, vcc
	v_max_f32_e32 v58, 0xf149f2ca, v112
	v_max_f32_e32 v58, v58, v113
	v_add_u32_e32 v59, 2, v57
	v_add_u32_e32 v64, 3, v57
	v_cmp_gt_u32_e64 s[22:23], v59, v149
	v_cmp_gt_u32_e64 s[24:25], v64, v149
	s_nop 0
	v_cndmask_b32_e64 v114, v114, v246, s[22:23]
	v_cndmask_b32_e64 v115, v115, v246, s[24:25]
	v_max3_f32 v58, v58, v114, v115
	v_add_u32_e32 v59, 16, v57
	v_add_u32_e32 v64, 17, v57
	v_cmp_gt_u32_e64 s[26:27], v59, v149
	v_cmp_gt_u32_e64 s[28:29], v64, v149
	s_nop 0
	v_cndmask_b32_e64 v116, v116, v246, s[26:27]
	v_cndmask_b32_e64 v117, v117, v246, s[28:29]
	v_max3_f32 v58, v58, v116, v117
	v_add_u32_e32 v59, 18, v57
	v_add_u32_e32 v57, 19, v57
	v_cmp_gt_u32_e64 s[30:31], v59, v149
	v_cmp_gt_u32_e64 s[34:35], v57, v149
	s_nop 0
	v_cndmask_b32_e64 v118, v118, v246, s[30:31]
	v_cndmask_b32_e64 v119, v119, v246, s[34:35]
	v_max3_f32 v57, v58, v118, v119
	v_mov_b32_e32 v59, v57
	s_nop 1
	v_permlane32_swap_b32_e32 v59, v57
	v_max_f32_e32 v57, v57, v59
	s_nop 1
	v_mov_b32_e32 v59, v57
	s_nop 1
	v_permlane16_swap_b32_e32 v59, v57
	v_max3_f32 v175, v145, v57, v59
	v_sub_f32_e32 v57, v145, v175
	v_exp_f32_e32 v72, v57
	v_sub_f32_e32 v57, v112, v175
	v_exp_f32_e32 v57, v57
	v_sub_f32_e32 v64, v113, v175
	v_exp_f32_e32 v64, v64
	s_nop 0
	v_sub_f32_e32 v65, v114, v175
	v_exp_f32_e32 v65, v65
	v_sub_f32_e32 v66, v115, v175
	v_add_f32_e32 v59, 0, v57
	v_exp_f32_e32 v66, v66
	v_sub_f32_e32 v67, v116, v175
	v_mov_b32_e32 v177, v144
	v_add_f32_e32 v59, v64, v59
	v_exp_f32_e32 v67, v67
	v_sub_f32_e32 v70, v117, v175
	v_cvt_pk_bf16_f32 v64, v57, v64
	v_exp_f32_e32 v70, v70
	v_sub_f32_e32 v71, v118, v175
	v_sub_f32_e32 v73, v119, v175
	v_mov_b32_e32 v74, 1.0
	v_exp_f32_e32 v71, v71
	v_exp_f32_e32 v73, v73
	v_add_f32_e32 v59, v65, v59
	v_add_f32_e32 v59, v66, v59
	v_add_f32_e32 v59, v67, v59
	v_add_f32_e32 v59, v70, v59
	v_mov_b32_e32 v57, 0
	v_add_f32_e32 v59, v71, v59
	v_cvt_pk_bf16_f32 v65, v65, v66
	v_cvt_pk_bf16_f32 v66, v67, v70
	v_cvt_pk_bf16_f32 v67, v71, v73
	v_add_f32_e32 v58, 0, v57
	v_mov_b32_e32 v56, 0
	v_pk_mul_f32 v[42:43], v[42:43], v[72:73] op_sel_hi:[1,0]
	v_pk_mul_f32 v[40:41], v[40:41], v[72:73] op_sel_hi:[1,0]
	v_add_f32_e32 v176, v73, v59
	v_add_f32_e32 v178, v56, v58
	v_cvt_pk_bf16_f32 v68, v57, 0
	v_cvt_pk_bf16_f32 v70, v56, 0
	v_mov_b32_e32 v69, v153
	v_mov_b32_e32 v71, v153
	s_waitcnt lgkmcnt(10)
	v_mfma_f32_16x16x32_bf16 v[56:59], v[140:143], v[64:67], v[40:43]
	v_fmac_f32_e32 v176, v147, v72
	v_fmac_f32_e32 v178, v146, v74
	s_nop 0
	v_pk_mul_f32 v[42:43], v[46:47], v[74:75] op_sel_hi:[1,0]
	v_pk_mul_f32 v[40:41], v[44:45], v[74:75] op_sel_hi:[1,0]
	s_nop 1
	v_mfma_f32_16x16x32_bf16 v[112:115], v[140:143], v[68:71], v[40:43]
	s_nop 2
	v_mul_f32_e64 v42, v50, v72
	v_mul_f32_e64 v43, v51, v72
	v_pk_mul_f32 v[40:41], v[48:49], v[72:73] op_sel_hi:[1,0]
	v_add_u32_e32 v48, s40, v227
	v_min_i32_e32 v49, s75, v48
	s_waitcnt lgkmcnt(8)
	v_mfma_f32_16x16x32_bf16 v[116:119], v[132:135], v[64:67], v[40:43]
	s_nop 2
	v_mul_f32_e64 v42, v54, v74
	v_mul_f32_e64 v43, v55, v74
	v_pk_mul_f32 v[40:41], v[52:53], v[74:75] op_sel_hi:[1,0]
	s_nop 1
	v_mfma_f32_16x16x32_bf16 v[120:123], v[132:135], v[68:71], v[40:43]
	s_nop 2
	v_mul_f32_e64 v42, v90, v72
	v_mul_f32_e64 v43, v91, v72
	v_pk_mul_f32 v[40:41], v[88:89], v[72:73] op_sel_hi:[1,0]
	s_waitcnt lgkmcnt(6)
	s_nop 0
	v_mfma_f32_16x16x32_bf16 v[124:127], v[128:131], v[64:67], v[40:43]
	s_nop 2
	v_mul_f32_e64 v42, v102, v74
	v_mul_f32_e64 v43, v103, v74
	v_pk_mul_f32 v[40:41], v[100:101], v[74:75] op_sel_hi:[1,0]
	s_nop 1
	v_mfma_f32_16x16x32_bf16 v[128:131], v[128:131], v[68:71], v[40:43]
	s_nop 2
	v_mul_f32_e64 v42, v106, v72
	v_mul_f32_e64 v43, v107, v72
	v_pk_mul_f32 v[40:41], v[104:105], v[72:73] op_sel_hi:[1,0]
	s_waitcnt lgkmcnt(4)
	s_nop 0
	v_mfma_f32_16x16x32_bf16 v[132:135], v[136:139], v[64:67], v[40:43]
	s_nop 2
	v_mul_f32_e64 v42, v110, v74
	v_mul_f32_e64 v43, v111, v74
	v_pk_mul_f32 v[40:41], v[108:109], v[74:75] op_sel_hi:[1,0]
	s_nop 1
	v_mfma_f32_16x16x32_bf16 v[136:139], v[136:139], v[68:71], v[40:43]
	s_nop 2
	v_add_u32_e32 v40, s40, v222
	v_med3_i32 v40, v40, 0, s75
	v_lshl_add_u32 v40, v40, 9, v152
	global_load_dwordx4 v[64:67], v40, s[98:99]
	v_add_u32_e32 v40, s40, v223
	v_med3_i32 v40, v40, 0, s75
	v_lshl_add_u32 v40, v40, 9, v152
	global_load_dwordx4 v[68:71], v40, s[98:99]
	v_add_u32_e32 v40, s40, v224
	v_med3_i32 v40, v40, 0, s75
	v_lshl_add_u32 v40, v40, 9, v152
	global_load_dwordx4 v[72:75], v40, s[98:99]
	v_add_u32_e32 v40, s40, v225
	v_med3_i32 v40, v40, 0, s75
	v_lshl_add_u32 v40, v40, 9, v152
	global_load_dwordx4 v[88:91], v40, s[98:99]
	v_add_u32_e32 v40, s40, v226
	v_med3_i32 v40, v40, 0, s75
	v_cmp_lt_i32_e32 vcc, -1, v48
	s_nop 1
	v_cndmask_b32_e32 v48, 0, v49, vcc
	v_lshl_add_u32 v44, v40, 9, v158
	v_lshl_add_u32 v52, v48, 9, v158
	global_load_dwordx4 v[40:43], v44, s[100:101]
	s_nop 0
	global_load_dwordx4 v[44:47], v44, s[100:101] offset:64
	s_nop 0
	global_load_dwordx4 v[48:51], v52, s[100:101]
	s_nop 0
	global_load_dwordx4 v[52:55], v52, s[100:101] offset:64
	ds_read_b64_tr_b16 v[102:103], v169 offset:2304
	ds_read_b64_tr_b16 v[100:101], v169
	ds_read_b64_tr_b16 v[108:109], v169 offset:32
	ds_read_b64_tr_b16 v[110:111], v169 offset:2336
	ds_read_b64_tr_b16 v[144:145], v169 offset:64
	ds_read_b64_tr_b16 v[146:147], v169 offset:2368
	ds_read_b64_tr_b16 v[140:141], v169 offset:96
	ds_read_b64_tr_b16 v[142:143], v169 offset:2400
	s_waitcnt vmcnt(15)
	ds_write_b128 v241, v[16:19] offset:4608
	s_waitcnt vmcnt(14)
	ds_write_b128 v242, v[60:63] offset:4608
	s_waitcnt vmcnt(13)
	ds_write_b128 v243, v[92:95] offset:4608
	s_waitcnt vmcnt(12)
	ds_write_b128 v244, v[96:99] offset:4608
	v_mfma_f32_16x16x32_bf16 v[16:19], v[84:87], v[4:7], 0
	v_mfma_f32_16x16x32_bf16 v[60:63], v[76:79], v[4:7], 0
	v_mfma_f32_16x16x32_bf16 v[16:19], v[80:83], v[8:11], v[16:19]
	v_mfma_f32_16x16x32_bf16 v[60:63], v[20:23], v[8:11], v[60:63]
	s_nop 5
	v_sub_u32_e32 v21, v198, v150
	v_add_u32_e32 v23, 1, v21
	v_cmp_gt_u32_e64 s[0:1], v23, v149
	v_cmp_gt_u32_e32 vcc, v21, v149
	s_nop 0
	v_cndmask_b32_e64 v17, v17, v246, s[0:1]
	s_nop 0
	v_cndmask_b32_e32 v16, v16, v246, vcc
	v_max_f32_e32 v22, 0xf149f2ca, v16
	v_max_f32_e32 v22, v22, v17
	v_add_u32_e32 v23, 2, v21
	v_add_u32_e32 v76, 3, v21
	v_cmp_gt_u32_e64 s[22:23], v23, v149
	v_cmp_gt_u32_e64 s[24:25], v76, v149
	s_nop 0
	v_cndmask_b32_e64 v18, v18, v246, s[22:23]
	v_cndmask_b32_e64 v19, v19, v246, s[24:25]
	v_max3_f32 v22, v22, v18, v19
	v_add_u32_e32 v23, 16, v21
	v_add_u32_e32 v76, 17, v21
	v_cmp_gt_u32_e64 s[26:27], v23, v149
	v_cmp_gt_u32_e64 s[28:29], v76, v149
	s_nop 0
	v_cndmask_b32_e64 v60, v60, v246, s[26:27]
	v_cndmask_b32_e64 v61, v61, v246, s[28:29]
	v_max3_f32 v22, v22, v60, v61
	v_add_u32_e32 v23, 18, v21
	v_add_u32_e32 v21, 19, v21
	v_cmp_gt_u32_e64 s[30:31], v23, v149
	v_cmp_gt_u32_e64 s[34:35], v21, v149
	s_nop 0
	v_cndmask_b32_e64 v62, v62, v246, s[30:31]
	v_cndmask_b32_e64 v63, v63, v246, s[34:35]
	v_max3_f32 v21, v22, v62, v63
	v_mov_b32_e32 v23, v21
	s_nop 1
	v_permlane32_swap_b32_e32 v23, v21
	v_max_f32_e32 v21, v21, v23
	s_nop 1
	v_mov_b32_e32 v23, v21
	s_nop 1
	v_permlane16_swap_b32_e32 v23, v21
	v_max3_f32 v151, v175, v21, v23
	v_sub_f32_e32 v16, v16, v151
	v_exp_f32_e32 v16, v16
	v_sub_f32_e32 v17, v17, v151
	v_exp_f32_e32 v17, v17
	v_sub_f32_e32 v18, v18, v151
	v_exp_f32_e32 v18, v18
	v_sub_f32_e32 v19, v19, v151
	v_exp_f32_e32 v19, v19
	v_sub_f32_e32 v23, v60, v151
	v_sub_f32_e32 v21, v175, v151
	v_exp_f32_e32 v23, v23
	v_sub_f32_e32 v60, v61, v151
	v_exp_f32_e32 v76, v21
	v_add_f32_e32 v21, 0, v16
	v_exp_f32_e32 v60, v60
	v_sub_f32_e32 v61, v62, v151
	v_add_f32_e32 v21, v17, v21
	v_exp_f32_e32 v61, v61
	v_sub_f32_e32 v62, v63, v151
	v_add_f32_e32 v21, v18, v21
	v_exp_f32_e32 v62, v62
	v_add_f32_e32 v21, v19, v21
	v_add_f32_e32 v21, v23, v21
	v_add_f32_e32 v21, v60, v21
	v_add_f32_e32 v21, v61, v21
	v_mov_b32_e32 v175, v177
	v_add_f32_e32 v149, v62, v21
	v_cvt_pk_bf16_f32 v16, v16, v17
	v_cvt_pk_bf16_f32 v17, v18, v19
	v_cvt_pk_bf16_f32 v18, v23, v60
	v_mov_b32_e32 v60, 1.0
	v_cvt_pk_bf16_f32 v19, v61, v62
	v_mov_b32_e32 v21, 0
	v_add_f32_e32 v22, 0, v21
	v_mov_b32_e32 v23, 0
	v_pk_mul_f32 v[58:59], v[58:59], v[76:77] op_sel_hi:[1,0]
	v_pk_mul_f32 v[56:57], v[56:57], v[76:77] op_sel_hi:[1,0]
	v_add_f32_e32 v150, v23, v22
	v_cvt_pk_bf16_f32 v20, v21, 0
	v_cvt_pk_bf16_f32 v22, v23, 0
	v_mov_b32_e32 v21, v153
	v_mov_b32_e32 v23, v153
	s_waitcnt lgkmcnt(10)
	v_mfma_f32_16x16x32_bf16 v[96:99], v[100:103], v[16:19], v[56:59]
	v_fmac_f32_e32 v149, v176, v76
	v_fmac_f32_e32 v150, v178, v60
	s_min_i32 s0, s76, 0
	v_pk_mul_f32 v[58:59], v[114:115], v[60:61] op_sel_hi:[1,0]
	v_pk_mul_f32 v[56:57], v[112:113], v[60:61] op_sel_hi:[1,0]
	s_sub_i32 s0, 15, s0
	s_sub_i32 s1, s75, s76
	v_mfma_f32_16x16x32_bf16 v[100:103], v[100:103], v[20:23], v[56:59]
	s_ashr_i32 s0, s0, 4
	s_ashr_i32 s1, s1, 4
	s_cmpk_lt_i32 s71, 0x3000
	v_pk_mul_f32 v[58:59], v[118:119], v[76:77] op_sel_hi:[1,0]
	v_pk_mul_f32 v[56:57], v[116:117], v[76:77] op_sel_hi:[1,0]
	s_waitcnt lgkmcnt(8)
	s_nop 0
	v_mfma_f32_16x16x32_bf16 v[104:107], v[108:111], v[16:19], v[56:59]
	s_nop 2
	v_mul_f32_e64 v58, v122, v60
	v_mul_f32_e64 v59, v123, v60
	v_pk_mul_f32 v[56:57], v[120:121], v[60:61] op_sel_hi:[1,0]
	s_nop 1
	v_mfma_f32_16x16x32_bf16 v[108:111], v[108:111], v[20:23], v[56:59]
	s_nop 2
	v_mul_f32_e64 v58, v126, v76
	v_mul_f32_e64 v59, v127, v76
	v_pk_mul_f32 v[56:57], v[124:125], v[76:77] op_sel_hi:[1,0]
	s_waitcnt lgkmcnt(6)
	s_nop 0
	v_mfma_f32_16x16x32_bf16 v[112:115], v[144:147], v[16:19], v[56:59]
	s_nop 2
	v_mul_f32_e64 v58, v130, v60
	v_mul_f32_e64 v59, v131, v60
	v_pk_mul_f32 v[56:57], v[128:129], v[60:61] op_sel_hi:[1,0]
	s_nop 1
	v_mfma_f32_16x16x32_bf16 v[116:119], v[144:147], v[20:23], v[56:59]
	v_max_i32_e32 v145, s0, v148
	s_nop 1
	v_pk_mul_f32 v[58:59], v[134:135], v[76:77] op_sel_hi:[1,0]
	v_pk_mul_f32 v[56:57], v[132:133], v[76:77] op_sel_hi:[1,0]
	s_waitcnt lgkmcnt(4)
	s_nop 0
	v_mfma_f32_16x16x32_bf16 v[120:123], v[140:143], v[16:19], v[56:59]
	v_mul_f32_e64 v18, v138, v60
	v_mul_f32_e64 v19, v139, v60
	v_pk_mul_f32 v[16:17], v[136:137], v[60:61] op_sel_hi:[1,0]
	v_add_u32_e32 v56, s40, v228
	s_nop 0
	v_mfma_f32_16x16x32_bf16 v[124:127], v[140:143], v[20:23], v[16:19]
	s_nop 1
	s_nop 0
	v_add_u32_e32 v16, s40, v213
	v_med3_i32 v16, v16, 0, s75
	v_lshl_add_u32 v16, v16, 9, v152
	global_load_dwordx4 v[76:79], v16, s[98:99]
	v_add_u32_e32 v16, s40, v215
	v_med3_i32 v16, v16, 0, s75
	v_lshl_add_u32 v16, v16, 9, v152
	global_load_dwordx4 v[80:83], v16, s[98:99]
	v_add_u32_e32 v16, s40, v217
	v_med3_i32 v16, v16, 0, s75
	v_lshl_add_u32 v16, v16, 9, v152
	global_load_dwordx4 v[84:87], v16, s[98:99]
	v_add_u32_e32 v16, s40, v219
	v_med3_i32 v16, v16, 0, s75
	v_lshl_add_u32 v16, v16, 9, v152
	global_load_dwordx4 v[92:95], v16, s[98:99]
	v_or_b32_e32 v16, s40, v167
	v_min_i32_e32 v16, s75, v16
	v_cndmask_b32_e64 v16, v16, 0, s[38:39]
	v_med3_i32 v56, v56, 0, s75
	v_lshl_add_u32 v20, v16, 9, v158
	v_lshl_add_u32 v60, v56, 9, v158
	global_load_dwordx4 v[16:19], v20, s[100:101]
	s_nop 0
	global_load_dwordx4 v[20:23], v20, s[100:101] offset:64
	s_nop 0
	global_load_dwordx4 v[56:59], v60, s[100:101]
	s_nop 0
	global_load_dwordx4 v[60:63], v60, s[100:101] offset:64
	ds_read_b64_tr_b16 v[132:133], v169 offset:6912
	ds_read_b64_tr_b16 v[130:131], v169 offset:4608
	ds_read_b64_tr_b16 v[134:135], v169 offset:4640
	ds_read_b64_tr_b16 v[136:137], v169 offset:6944
	ds_read_b64_tr_b16 v[138:139], v169 offset:4672
	ds_read_b64_tr_b16 v[140:141], v169 offset:6976
	ds_read_b64_tr_b16 v[176:177], v169 offset:4704
	ds_read_b64_tr_b16 v[178:179], v169 offset:7008
	s_waitcnt vmcnt(15)
	ds_write_b128 v241, v[64:67]
	s_waitcnt vmcnt(14)
	ds_write_b128 v242, v[68:71]
	s_waitcnt vmcnt(13)
	ds_write_b128 v243, v[72:75]
	s_waitcnt vmcnt(12)
	ds_write_b128 v244, v[88:91]
	v_mfma_f32_16x16x32_bf16 v[24:27], v[24:27], v[12:15], 0
	v_mfma_f32_16x16x32_bf16 v[24:27], v[28:31], v[0:3], v[24:27]
	v_mfma_f32_16x16x32_bf16 v[28:31], v[32:35], v[12:15], 0
	v_add_u32_e32 v32, 0x7f8, v249
	v_ashrrev_i32_e32 v32, 4, v32
	v_min3_i32 v32, v32, s1, v248
	v_sub_u32_e32 v144, v32, v145
	v_sub_u32_e32 v33, v154, v145
	s_nop 2
	v_add_u32_e32 v35, 1, v33
	v_cmp_gt_u32_e64 s[0:1], v35, v144
	v_cmp_gt_u32_e32 vcc, v33, v144
	s_nop 0
	v_cndmask_b32_e64 v25, v25, v246, s[0:1]
	s_nop 0
	v_cndmask_b32_e32 v24, v24, v246, vcc
	v_max_f32_e32 v34, 0xf149f2ca, v24
	v_mfma_f32_16x16x32_bf16 v[28:31], v[36:39], v[0:3], v[28:31]
	v_max_f32_e32 v34, v34, v25
	v_add_u32_e32 v35, 2, v33
	v_add_u32_e32 v36, 3, v33
	v_cmp_gt_u32_e64 s[22:23], v35, v144
	v_cmp_gt_u32_e64 s[24:25], v36, v144
	s_nop 0
	v_cndmask_b32_e64 v26, v26, v246, s[22:23]
	v_cndmask_b32_e64 v27, v27, v246, s[24:25]
	v_max3_f32 v34, v34, v26, v27
	v_add_u32_e32 v35, 16, v33
	v_add_u32_e32 v36, 17, v33
	v_cmp_gt_u32_e64 s[26:27], v35, v144
	v_cmp_gt_u32_e64 s[28:29], v36, v144
	s_nop 0
	v_cndmask_b32_e64 v28, v28, v246, s[26:27]
	v_cndmask_b32_e64 v29, v29, v246, s[28:29]
	v_max3_f32 v34, v34, v28, v29
	v_add_u32_e32 v35, 18, v33
	v_add_u32_e32 v33, 19, v33
	v_cmp_gt_u32_e64 s[30:31], v35, v144
	v_cmp_gt_u32_e64 s[34:35], v33, v144
	s_nop 0
	v_cndmask_b32_e64 v30, v30, v246, s[30:31]
	v_cndmask_b32_e64 v31, v31, v246, s[34:35]
	v_max3_f32 v33, v34, v30, v31
	s_nop 1
	v_mov_b32_e32 v34, v33
	s_nop 1
	v_permlane32_swap_b32_e32 v34, v33
	v_max_f32_e32 v33, v33, v34
	s_nop 1
	v_mov_b32_e32 v34, v33
	s_nop 1
	v_permlane16_swap_b32_e32 v34, v33
	v_max3_f32 v128, v175, v33, v34
	v_sub_f32_e32 v24, v24, v128
	v_exp_f32_e32 v24, v24
	v_sub_f32_e32 v37, v175, v128
	v_exp_f32_e32 v38, v37
	v_mov_b32_e32 v129, v151
	v_cndmask_b32_e64 v37, v24, 0, vcc
	v_sub_f32_e32 v24, v25, v128
	v_exp_f32_e32 v24, v24
	v_mov_b32_e32 v36, 1.0
	v_cndmask_b32_e64 v65, v24, 0, s[0:1]
	v_sub_f32_e32 v24, v26, v128
	v_exp_f32_e32 v24, v24
	v_mov_b32_e32 v33, v153
	v_mov_b32_e32 v35, v153
	v_mov_b32_e32 v39, 0
	v_cndmask_b32_e64 v66, v24, 0, s[22:23]
	v_sub_f32_e32 v24, v27, v128
	v_exp_f32_e32 v24, v24
	s_nop 0
	v_cndmask_b32_e64 v67, v24, 0, s[24:25]
	v_sub_f32_e32 v24, v28, v128
	v_exp_f32_e32 v24, v24
	v_mov_b32_e32 v64, 0
	v_cvt_pk_bf16_f32 v32, v39, 0
	v_cvt_pk_bf16_f32 v34, v64, 0
	v_cndmask_b32_e64 v68, v24, 0, s[26:27]
	v_sub_f32_e32 v24, v29, v128
	v_exp_f32_e32 v24, v24
	v_pk_mul_f32 v[28:29], v[96:97], v[36:37] op_sel_hi:[1,0]
	v_cvt_pk_bf16_f32 v25, v66, v67
	v_cndmask_b32_e64 v69, v24, 0, s[28:29]
	v_sub_f32_e32 v24, v30, v128
	v_exp_f32_e32 v24, v24
	v_cvt_pk_bf16_f32 v26, v68, v69
	v_cndmask_b32_e64 v70, v24, 0, s[30:31]
	v_sub_f32_e32 v24, v31, v128
	v_exp_f32_e32 v24, v24
	v_pk_mul_f32 v[30:31], v[98:99], v[36:37] op_sel_hi:[1,0]
	v_cndmask_b32_e64 v71, v24, 0, s[34:35]
	v_cvt_pk_bf16_f32 v24, v37, v65
	v_cvt_pk_bf16_f32 v27, v70, v71
	s_waitcnt lgkmcnt(10)
	v_mfma_f32_16x16x32_bf16 v[96:99], v[130:133], v[32:35], v[28:31]
	s_nop 2
	v_mul_f32_e64 v30, v102, v38
	v_mul_f32_e64 v31, v103, v38
	v_pk_mul_f32 v[28:29], v[100:101], v[38:39] op_sel_hi:[1,0]
	s_nop 1
	v_mfma_f32_16x16x32_bf16 v[100:103], v[130:133], v[24:27], v[28:31]
	s_nop 2
	v_mul_f32_e64 v30, v106, v36
	v_mul_f32_e64 v31, v107, v36
	v_pk_mul_f32 v[28:29], v[104:105], v[36:37] op_sel_hi:[1,0]
	s_waitcnt lgkmcnt(8)
	s_nop 0
	v_mfma_f32_16x16x32_bf16 v[104:107], v[134:137], v[32:35], v[28:31]
	s_nop 2
	v_mul_f32_e64 v30, v110, v38
	v_mul_f32_e64 v31, v111, v38
	v_pk_mul_f32 v[28:29], v[108:109], v[38:39] op_sel_hi:[1,0]
	s_nop 1
	v_mfma_f32_16x16x32_bf16 v[108:111], v[134:137], v[24:27], v[28:31]
	s_nop 2
	v_mul_f32_e64 v30, v114, v36
	v_mul_f32_e64 v31, v115, v36
	v_pk_mul_f32 v[28:29], v[112:113], v[36:37] op_sel_hi:[1,0]
	s_waitcnt lgkmcnt(6)
	s_nop 0
	v_mfma_f32_16x16x32_bf16 v[112:115], v[138:141], v[32:35], v[28:31]
	s_nop 2
	v_mul_f32_e64 v30, v118, v38
	v_mul_f32_e64 v31, v119, v38
	v_pk_mul_f32 v[28:29], v[116:117], v[38:39] op_sel_hi:[1,0]
	s_nop 1
	v_mfma_f32_16x16x32_bf16 v[116:119], v[138:141], v[24:27], v[28:31]
	s_nop 2
	v_mul_f32_e64 v30, v122, v36
	v_mul_f32_e64 v31, v123, v36
	v_pk_mul_f32 v[28:29], v[120:121], v[36:37] op_sel_hi:[1,0]
	s_waitcnt lgkmcnt(4)
	s_nop 0
	v_mfma_f32_16x16x32_bf16 v[120:123], v[176:179], v[32:35], v[28:31]
	v_add_u32_e32 v32, s40, v234
	s_nop 0
	s_nop 0
	v_pk_mul_f32 v[30:31], v[126:127], v[38:39] op_sel_hi:[1,0]
	v_pk_mul_f32 v[28:29], v[124:125], v[38:39] op_sel_hi:[1,0]
	s_nop 1
	v_mfma_f32_16x16x32_bf16 v[124:127], v[176:179], v[24:27], v[28:31]
	v_add_f32_e32 v24, 0, v37
	v_add_f32_e32 v24, v65, v24
	v_add_f32_e32 v24, v66, v24
	v_add_f32_e32 v24, v67, v24
	v_add_f32_e32 v24, v68, v24
	v_add_f32_e32 v24, v69, v24
	v_add_f32_e32 v24, v70, v24
	v_add_f32_e32 v130, v71, v24
	v_add_f32_e32 v24, 0, v39
	v_add_f32_e32 v131, v64, v24
	v_add_u32_e32 v24, s40, v229
	v_fmac_f32_e32 v131, v149, v36
	v_fmac_f32_e32 v130, v150, v38
	v_med3_i32 v24, v24, 0, s75
	v_lshl_add_u32 v24, v24, 9, v152
	global_load_dwordx4 v[64:67], v24, s[98:99]
	v_add_u32_e32 v24, s40, v230
	v_med3_i32 v24, v24, 0, s75
	v_lshl_add_u32 v24, v24, 9, v152
	global_load_dwordx4 v[68:71], v24, s[98:99]
	v_add_u32_e32 v24, s40, v231
	v_med3_i32 v24, v24, 0, s75
	v_lshl_add_u32 v24, v24, 9, v152
	global_load_dwordx4 v[72:75], v24, s[98:99]
	v_add_u32_e32 v24, s40, v232
	v_med3_i32 v24, v24, 0, s75
	v_lshl_add_u32 v24, v24, 9, v152
	global_load_dwordx4 v[88:91], v24, s[98:99]
	v_add_u32_e32 v24, s40, v233
	v_med3_i32 v24, v24, 0, s75
	v_med3_i32 v32, v32, 0, s75
	v_lshl_add_u32 v28, v24, 9, v158
	v_lshl_add_u32 v36, v32, 9, v158
	global_load_dwordx4 v[24:27], v28, s[100:101]
	s_nop 0
	global_load_dwordx4 v[28:31], v28, s[100:101] offset:64
	s_nop 0
	global_load_dwordx4 v[32:35], v36, s[100:101]
	s_nop 0
	global_load_dwordx4 v[36:39], v36, s[100:101] offset:64
	ds_read_b64_tr_b16 v[134:135], v169 offset:2304
	ds_read_b64_tr_b16 v[132:133], v169
	ds_read_b64_tr_b16 v[136:137], v169 offset:32
	ds_read_b64_tr_b16 v[138:139], v169 offset:2336
	ds_read_b64_tr_b16 v[140:141], v169 offset:64
	ds_read_b64_tr_b16 v[142:143], v169 offset:2368
	ds_read_b64_tr_b16 v[176:177], v169 offset:96
	ds_read_b64_tr_b16 v[178:179], v169 offset:2400
	s_waitcnt vmcnt(15)
	ds_write_b128 v241, v[76:79] offset:4608
	s_waitcnt vmcnt(14)
	ds_write_b128 v242, v[80:83] offset:4608
	s_waitcnt vmcnt(13)
	ds_write_b128 v243, v[84:87] offset:4608
	s_waitcnt vmcnt(12)
	ds_write_b128 v244, v[92:95] offset:4608
	v_mfma_f32_16x16x32_bf16 v[40:43], v[40:43], v[12:15], 0
	s_nop 5
	v_mov_b32_e32 v77, v153
	v_mfma_f32_16x16x32_bf16 v[40:43], v[44:47], v[0:3], v[40:43]
	v_mfma_f32_16x16x32_bf16 v[44:47], v[48:51], v[12:15], 0
	v_sub_u32_e32 v48, v187, v145
	s_nop 1
	v_add_u32_e32 v51, 1, v48
	v_cmp_gt_u32_e64 s[0:1], v51, v144
	v_cmp_gt_u32_e32 vcc, v48, v144
	s_nop 0
	v_cndmask_b32_e64 v41, v41, v246, s[0:1]
	s_nop 0
	v_cndmask_b32_e32 v40, v40, v246, vcc
	v_max_f32_e32 v50, 0xf149f2ca, v40
	v_mfma_f32_16x16x32_bf16 v[44:47], v[52:55], v[0:3], v[44:47]
	v_max_f32_e32 v50, v50, v41
	v_add_u32_e32 v51, 2, v48
	v_add_u32_e32 v52, 3, v48
	v_cmp_gt_u32_e64 s[22:23], v51, v144
	v_cmp_gt_u32_e64 s[24:25], v52, v144
	v_mov_b32_e32 v79, v153
	v_cndmask_b32_e64 v42, v42, v246, s[22:23]
	v_cndmask_b32_e64 v43, v43, v246, s[24:25]
	v_max3_f32 v50, v50, v42, v43
	v_add_u32_e32 v51, 16, v48
	v_add_u32_e32 v52, 17, v48
	v_cmp_gt_u32_e64 s[26:27], v51, v144
	v_cmp_gt_u32_e64 s[28:29], v52, v144
	s_nop 0
	v_cndmask_b32_e64 v44, v44, v246, s[26:27]
	v_cndmask_b32_e64 v45, v45, v246, s[28:29]
	v_max3_f32 v50, v50, v44, v45
	v_add_u32_e32 v51, 18, v48
	v_add_u32_e32 v48, 19, v48
	v_cmp_gt_u32_e64 s[30:31], v51, v144
	v_cmp_gt_u32_e64 s[34:35], v48, v144
	s_nop 0
	v_cndmask_b32_e64 v46, v46, v246, s[30:31]
	v_cndmask_b32_e64 v47, v47, v246, s[34:35]
	v_max3_f32 v48, v50, v46, v47
	s_nop 1
	v_mov_b32_e32 v50, v48
	s_nop 1
	v_permlane32_swap_b32_e32 v50, v48
	v_max_f32_e32 v48, v48, v50
	s_nop 1
	v_mov_b32_e32 v50, v48
	s_nop 1
	v_permlane16_swap_b32_e32 v50, v48
	v_max3_f32 v148, v128, v48, v50
	v_sub_f32_e32 v40, v40, v148
	v_exp_f32_e32 v40, v40
	v_sub_f32_e32 v41, v41, v148
	v_exp_f32_e32 v41, v41
	v_sub_f32_e32 v42, v42, v148
	v_exp_f32_e32 v42, v42
	v_sub_f32_e32 v43, v43, v148
	v_exp_f32_e32 v43, v43
	v_sub_f32_e32 v44, v44, v148
	v_mov_b32_e32 v146, v129
	v_sub_f32_e32 v48, v128, v148
	v_exp_f32_e32 v44, v44
	v_sub_f32_e32 v45, v45, v148
	v_exp_f32_e32 v86, v48
	v_add_f32_e32 v48, 0, v40
	v_exp_f32_e32 v45, v45
	v_sub_f32_e32 v46, v46, v148
	v_sub_f32_e32 v47, v47, v148
	v_mov_b32_e32 v84, 1.0
	v_add_f32_e32 v48, v41, v48
	v_exp_f32_e32 v46, v46
	v_exp_f32_e32 v47, v47
	v_add_f32_e32 v48, v42, v48
	v_add_f32_e32 v48, v43, v48
	v_add_f32_e32 v48, v44, v48
	v_add_f32_e32 v48, v45, v48
	v_mov_b32_e32 v49, 0
	v_mov_b32_e32 v51, 0
	v_add_f32_e32 v48, v46, v48
	v_cvt_pk_bf16_f32 v40, v40, v41
	v_cvt_pk_bf16_f32 v41, v42, v43
	v_cvt_pk_bf16_f32 v42, v44, v45
	v_cvt_pk_bf16_f32 v43, v46, v47
	v_pk_mul_f32 v[82:83], v[110:111], v[86:87] op_sel_hi:[1,0]
	v_pk_mul_f32 v[80:81], v[108:109], v[86:87] op_sel_hi:[1,0]
	v_add_f32_e32 v50, 0, v49
	v_cvt_pk_bf16_f32 v76, v49, 0
	v_cvt_pk_bf16_f32 v78, v51, 0
	v_add_f32_e32 v149, v47, v48
	v_pk_mul_f32 v[46:47], v[98:99], v[84:85] op_sel_hi:[1,0]
	v_pk_mul_f32 v[44:45], v[96:97], v[84:85] op_sel_hi:[1,0]
	s_waitcnt lgkmcnt(8)
	v_mfma_f32_16x16x32_bf16 v[96:99], v[136:139], v[40:43], v[80:83]
	v_add_f32_e32 v147, v51, v50
	v_pk_mul_f32 v[50:51], v[102:103], v[86:87] op_sel_hi:[1,0]
	v_pk_mul_f32 v[48:49], v[100:101], v[86:87] op_sel_hi:[1,0]
	v_pk_mul_f32 v[82:83], v[114:115], v[84:85] op_sel_hi:[1,0]
	v_pk_mul_f32 v[80:81], v[112:113], v[84:85] op_sel_hi:[1,0]
	v_pk_mul_f32 v[54:55], v[106:107], v[84:85] op_sel_hi:[1,0]
	v_pk_mul_f32 v[52:53], v[104:105], v[84:85] op_sel_hi:[1,0]
	s_waitcnt lgkmcnt(6)
	v_mfma_f32_16x16x32_bf16 v[100:103], v[140:143], v[76:79], v[80:83]
	v_fmac_f32_e32 v147, v131, v84
	v_fmac_f32_e32 v149, v130, v86
	s_nop 0
	v_pk_mul_f32 v[82:83], v[118:119], v[86:87] op_sel_hi:[1,0]
	v_pk_mul_f32 v[80:81], v[116:117], v[86:87] op_sel_hi:[1,0]
	v_mfma_f32_16x16x32_bf16 v[44:47], v[132:135], v[76:79], v[44:47]
	s_nop 0
	v_mfma_f32_16x16x32_bf16 v[104:107], v[140:143], v[40:43], v[80:83]
	s_nop 2
	v_mul_f32_e64 v82, v122, v84
	v_mul_f32_e64 v83, v123, v84
	v_pk_mul_f32 v[80:81], v[120:121], v[84:85] op_sel_hi:[1,0]
	v_mfma_f32_16x16x32_bf16 v[52:55], v[136:139], v[76:79], v[52:55]
	v_add_u32_e32 v84, s40, v240
	s_waitcnt lgkmcnt(4)
	v_mfma_f32_16x16x32_bf16 v[108:111], v[176:179], v[76:79], v[80:83]
	v_mul_f32_e64 v78, v126, v86
	v_mul_f32_e64 v79, v127, v86
	v_pk_mul_f32 v[76:77], v[124:125], v[86:87] op_sel_hi:[1,0]
	v_mfma_f32_16x16x32_bf16 v[48:51], v[132:135], v[40:43], v[48:51]
	s_nop 0
	v_mfma_f32_16x16x32_bf16 v[112:115], v[176:179], v[40:43], v[76:79]
	v_add_u32_e32 v40, s40, v235
	s_nop 1
	v_add_u32_e32 v76, s40, v236
	v_med3_i32 v40, v40, 0, s75
	v_med3_i32 v76, v76, 0, s75
	v_lshl_add_u32 v40, v40, 9, v152
	v_lshl_add_u32 v76, v76, 9, v152
	global_load_dwordx4 v[40:43], v40, s[98:99]
	s_nop 0
	global_load_dwordx4 v[116:119], v76, s[98:99]
	v_add_u32_e32 v76, s40, v237
	v_med3_i32 v76, v76, 0, s75
	v_lshl_add_u32 v76, v76, 9, v152
	global_load_dwordx4 v[120:123], v76, s[98:99]
	v_add_u32_e32 v76, s40, v238
	v_med3_i32 v76, v76, 0, s75
	v_lshl_add_u32 v76, v76, 9, v152
	global_load_dwordx4 v[124:127], v76, s[98:99]
	v_add_u32_e32 v76, s40, v239
	v_med3_i32 v76, v76, 0, s75
	v_med3_i32 v84, v84, 0, s75
	v_lshl_add_u32 v80, v76, 9, v158
	v_lshl_add_u32 v84, v84, 9, v158
	global_load_dwordx4 v[76:79], v80, s[100:101]
	s_nop 0
	global_load_dwordx4 v[80:83], v80, s[100:101] offset:64
	s_nop 0
	global_load_dwordx4 v[92:95], v84, s[100:101]
	s_nop 0
	global_load_dwordx4 v[84:87], v84, s[100:101] offset:64
	ds_read_b64_tr_b16 v[142:143], v169 offset:6912
	ds_read_b64_tr_b16 v[140:141], v169 offset:4608
	ds_read_b64_tr_b16 v[136:137], v169 offset:4640
	ds_read_b64_tr_b16 v[138:139], v169 offset:6944
	ds_read_b64_tr_b16 v[132:133], v169 offset:4672
	ds_read_b64_tr_b16 v[134:135], v169 offset:6976
	ds_read_b64_tr_b16 v[128:129], v169 offset:4704
	ds_read_b64_tr_b16 v[130:131], v169 offset:7008
	s_waitcnt vmcnt(15)
	ds_write_b128 v241, v[64:67]
	s_waitcnt vmcnt(14)
	ds_write_b128 v242, v[68:71]
	s_waitcnt vmcnt(13)
	ds_write_b128 v243, v[72:75]
	s_waitcnt vmcnt(12)
	ds_write_b128 v244, v[88:91]
	v_mfma_f32_16x16x32_bf16 v[16:19], v[16:19], v[12:15], 0
	v_mfma_f32_16x16x32_bf16 v[16:19], v[20:23], v[0:3], v[16:19]
	v_mfma_f32_16x16x32_bf16 v[20:23], v[56:59], v[12:15], 0
	s_nop 2
	v_sub_u32_e32 v56, v192, v145
	v_add_u32_e32 v59, 1, v56
	v_cmp_gt_u32_e64 s[0:1], v59, v144
	v_cmp_gt_u32_e32 vcc, v56, v144
	s_nop 0
	v_cndmask_b32_e64 v17, v17, v246, s[0:1]
	s_nop 0
	v_cndmask_b32_e32 v16, v16, v246, vcc
	v_max_f32_e32 v58, 0xf149f2ca, v16
	v_mfma_f32_16x16x32_bf16 v[20:23], v[60:63], v[0:3], v[20:23]
	v_max_f32_e32 v58, v58, v17
	v_add_u32_e32 v59, 2, v56
	v_add_u32_e32 v60, 3, v56
	v_cmp_gt_u32_e64 s[22:23], v59, v144
	v_cmp_gt_u32_e64 s[24:25], v60, v144
	v_mov_b32_e32 v61, v153
	v_cndmask_b32_e64 v18, v18, v246, s[22:23]
	v_cndmask_b32_e64 v19, v19, v246, s[24:25]
	v_max3_f32 v58, v58, v18, v19
	v_add_u32_e32 v59, 16, v56
	v_add_u32_e32 v60, 17, v56
	v_cmp_gt_u32_e64 s[26:27], v59, v144
	v_cmp_gt_u32_e64 s[28:29], v60, v144
	v_mov_b32_e32 v63, v153
	v_cndmask_b32_e64 v20, v20, v246, s[26:27]
	v_cndmask_b32_e64 v60, v21, v246, s[28:29]
	v_max3_f32 v58, v58, v20, v60
	v_add_u32_e32 v59, 18, v56
	v_add_u32_e32 v56, 19, v56
	v_cmp_gt_u32_e64 s[30:31], v59, v144
	v_cmp_gt_u32_e64 s[34:35], v56, v144
	s_nop 0
	v_cndmask_b32_e64 v22, v22, v246, s[30:31]
	v_cndmask_b32_e64 v23, v23, v246, s[34:35]
	v_max3_f32 v56, v58, v22, v23
	s_nop 1
	v_mov_b32_e32 v58, v56
	s_nop 1
	v_permlane32_swap_b32_e32 v58, v56
	v_max_f32_e32 v56, v56, v58
	s_nop 1
	v_mov_b32_e32 v58, v56
	s_nop 1
	v_permlane16_swap_b32_e32 v58, v56
	v_max3_f32 v151, v148, v56, v58
	v_sub_f32_e32 v16, v16, v151
	v_exp_f32_e32 v16, v16
	v_sub_f32_e32 v17, v17, v151
	v_mov_b32_e32 v150, v146
	v_exp_f32_e32 v17, v17
	v_sub_f32_e32 v18, v18, v151
	v_exp_f32_e32 v18, v18
	v_sub_f32_e32 v19, v19, v151
	v_mov_b32_e32 v68, 1.0
	v_exp_f32_e32 v19, v19
	v_sub_f32_e32 v20, v20, v151
	v_sub_f32_e32 v56, v148, v151
	v_exp_f32_e32 v20, v20
	v_sub_f32_e32 v21, v21, v151
	v_exp_f32_e32 v72, v56
	v_add_f32_e32 v56, 0, v16
	v_exp_f32_e32 v21, v21
	v_sub_f32_e32 v22, v22, v151
	v_add_f32_e32 v56, v17, v56
	v_exp_f32_e32 v22, v22
	v_sub_f32_e32 v23, v23, v151
	v_add_f32_e32 v56, v18, v56
	v_exp_f32_e32 v23, v23
	v_mov_b32_e32 v57, 0
	v_add_f32_e32 v56, v19, v56
	v_add_f32_e32 v58, 0, v57
	v_mov_b32_e32 v59, 0
	v_add_f32_e32 v56, v20, v56
	v_cndmask_b32_e64 v21, v21, 0, s[28:29]
	v_add_f32_e32 v146, v59, v58
	v_add_f32_e32 v56, v21, v56
	v_fmac_f32_e32 v146, v147, v68
	v_cvt_pk_bf16_f32 v60, v57, 0
	v_cvt_pk_bf16_f32 v62, v59, 0
	v_add_f32_e32 v56, v22, v56
	v_cvt_pk_bf16_f32 v64, v16, v17
	v_cvt_pk_bf16_f32 v65, v18, v19
	v_pk_mul_f32 v[18:19], v[46:47], v[68:69] op_sel_hi:[1,0]
	v_pk_mul_f32 v[16:17], v[44:45], v[68:69] op_sel_hi:[1,0]
	v_pk_mul_f32 v[46:47], v[54:55], v[68:69] op_sel_hi:[1,0]
	v_pk_mul_f32 v[44:45], v[52:53], v[68:69] op_sel_hi:[1,0]
	v_pk_mul_f32 v[54:55], v[102:103], v[68:69] op_sel_hi:[1,0]
	v_pk_mul_f32 v[52:53], v[100:101], v[68:69] op_sel_hi:[1,0]
	v_pk_mul_f32 v[70:71], v[110:111], v[68:69] op_sel_hi:[1,0]
	v_pk_mul_f32 v[68:69], v[108:109], v[68:69] op_sel_hi:[1,0]
	v_add_f32_e32 v147, v23, v56
	v_cvt_pk_bf16_f32 v66, v20, v21
	v_cvt_pk_bf16_f32 v67, v22, v23
	s_waitcnt lgkmcnt(10)
	v_mfma_f32_16x16x32_bf16 v[16:19], v[140:143], v[60:63], v[16:19]
	v_mul_f32_e64 v22, v50, v72
	v_mul_f32_e64 v23, v51, v72
	v_pk_mul_f32 v[20:21], v[48:49], v[72:73] op_sel_hi:[1,0]
	v_pk_mul_f32 v[50:51], v[98:99], v[72:73] op_sel_hi:[1,0]
	s_waitcnt lgkmcnt(8)
	v_mfma_f32_16x16x32_bf16 v[44:47], v[136:139], v[60:63], v[44:47]
	v_mul_f32_e64 v48, v96, v72
	v_mul_f32_e64 v49, v97, v72
	v_pk_mul_f32 v[58:59], v[106:107], v[72:73] op_sel_hi:[1,0]
	v_pk_mul_f32 v[56:57], v[104:105], v[72:73] op_sel_hi:[1,0]
	s_waitcnt lgkmcnt(6)
	v_mfma_f32_16x16x32_bf16 v[52:55], v[132:135], v[60:63], v[52:55]
	v_fmac_f32_e32 v147, v149, v72
	s_waitcnt lgkmcnt(4)
	v_mfma_f32_16x16x32_bf16 v[60:63], v[128:131], v[60:63], v[68:71]
	s_nop 2
	v_mul_f32_e64 v70, v114, v72
	v_mul_f32_e64 v71, v115, v72
	v_pk_mul_f32 v[68:69], v[112:113], v[72:73] op_sel_hi:[1,0]
	v_mfma_f32_16x16x32_bf16 v[20:23], v[140:143], v[64:67], v[20:23]
	v_mfma_f32_16x16x32_bf16 v[48:51], v[136:139], v[64:67], v[48:51]
	v_mfma_f32_16x16x32_bf16 v[56:59], v[132:135], v[64:67], v[56:59]
	v_mfma_f32_16x16x32_bf16 v[64:67], v[128:131], v[64:67], v[68:71]
	ds_read_b64_tr_b16 v[98:99], v169 offset:2304
	ds_read_b64_tr_b16 v[96:97], v169
	ds_read_b64_tr_b16 v[88:89], v169 offset:32
	ds_read_b64_tr_b16 v[90:91], v169 offset:2336
	ds_read_b64_tr_b16 v[72:73], v169 offset:64
	ds_read_b64_tr_b16 v[74:75], v169 offset:2368
	ds_read_b64_tr_b16 v[68:69], v169 offset:96
	ds_read_b64_tr_b16 v[70:71], v169 offset:2400
	s_waitcnt vmcnt(7)
	ds_write_b128 v241, v[40:43] offset:4608
	s_waitcnt vmcnt(6)
	ds_write_b128 v242, v[116:119] offset:4608
	s_waitcnt vmcnt(5)
	ds_write_b128 v243, v[120:123] offset:4608
	s_waitcnt vmcnt(4)
	ds_write_b128 v244, v[124:127] offset:4608
	v_mfma_f32_16x16x32_bf16 v[24:27], v[24:27], v[12:15], 0
	v_mfma_f32_16x16x32_bf16 v[24:27], v[28:31], v[0:3], v[24:27]
	s_nop 5
	v_mov_b32_e32 v41, v153
	v_mov_b32_e32 v43, v153
	v_mfma_f32_16x16x32_bf16 v[28:31], v[32:35], v[12:15], 0
	v_sub_u32_e32 v32, v197, v145
	v_add_u32_e32 v35, 1, v32
	v_cmp_gt_u32_e64 s[0:1], v35, v144
	v_cmp_gt_u32_e32 vcc, v32, v144
	s_nop 0
	v_cndmask_b32_e64 v25, v25, v246, s[0:1]
	s_nop 0
	v_cndmask_b32_e32 v24, v24, v246, vcc
	v_max_f32_e32 v34, 0xf149f2ca, v24
	v_mfma_f32_16x16x32_bf16 v[28:31], v[36:39], v[0:3], v[28:31]
	v_max_f32_e32 v34, v34, v25
	v_add_u32_e32 v35, 2, v32
	v_add_u32_e32 v36, 3, v32
	v_cmp_gt_u32_e64 s[22:23], v35, v144
	v_cmp_gt_u32_e64 s[24:25], v36, v144
	s_nop 0
	v_cndmask_b32_e64 v26, v26, v246, s[22:23]
	v_cndmask_b32_e64 v27, v27, v246, s[24:25]
	v_max3_f32 v34, v34, v26, v27
	v_add_u32_e32 v35, 16, v32
	v_add_u32_e32 v36, 17, v32
	v_cmp_gt_u32_e64 s[26:27], v35, v144
	v_cmp_gt_u32_e64 s[28:29], v36, v144
	s_nop 0
	v_cndmask_b32_e64 v28, v28, v246, s[26:27]
	v_cndmask_b32_e64 v29, v29, v246, s[28:29]
	v_max3_f32 v34, v34, v28, v29
	v_add_u32_e32 v35, 18, v32
	v_add_u32_e32 v32, 19, v32
	v_cmp_gt_u32_e64 s[30:31], v35, v144
	v_cmp_gt_u32_e64 s[34:35], v32, v144
	s_nop 0
	v_cndmask_b32_e64 v30, v30, v246, s[30:31]
	v_cndmask_b32_e64 v31, v31, v246, s[34:35]
	v_max3_f32 v32, v34, v30, v31
	s_nop 1
	v_mov_b32_e32 v34, v32
	s_nop 1
	v_permlane32_swap_b32_e32 v34, v32
	v_max_f32_e32 v32, v32, v34
	s_nop 1
	v_mov_b32_e32 v101, v150
	v_mov_b32_e32 v106, 1.0
	v_mov_b32_e32 v34, v32
	s_nop 0
	s_nop 0
	v_permlane16_swap_b32_e32 v34, v32
	v_mov_b32_e32 v107, 0
	v_max3_f32 v100, v151, v32, v34
	v_sub_f32_e32 v24, v24, v100
	v_exp_f32_e32 v24, v24
	v_sub_f32_e32 v32, v151, v100
	v_exp_f32_e32 v108, v32
	v_cndmask_b32_e64 v110, v24, 0, vcc
	v_sub_f32_e32 v24, v25, v100
	v_exp_f32_e32 v24, v24
	v_mov_b32_e32 v109, 0
	v_cvt_pk_bf16_f32 v40, v107, 0
	v_cvt_pk_bf16_f32 v42, v109, 0
	v_cndmask_b32_e64 v111, v24, 0, s[0:1]
	v_sub_f32_e32 v24, v26, v100
	v_exp_f32_e32 v24, v24
	v_pk_mul_f32 v[18:19], v[18:19], v[106:107] op_sel_hi:[1,0]
	v_pk_mul_f32 v[16:17], v[16:17], v[106:107] op_sel_hi:[1,0]
	v_pk_mul_f32 v[34:35], v[54:55], v[106:107] op_sel_hi:[1,0]
	v_cndmask_b32_e64 v112, v24, 0, s[22:23]
	v_sub_f32_e32 v24, v27, v100
	v_exp_f32_e32 v24, v24
	v_pk_mul_f32 v[26:27], v[46:47], v[106:107] op_sel_hi:[1,0]
	v_pk_mul_f32 v[32:33], v[52:53], v[106:107] op_sel_hi:[1,0]
	v_pk_mul_f32 v[46:47], v[62:63], v[106:107] op_sel_hi:[1,0]
	v_cndmask_b32_e64 v113, v24, 0, s[24:25]
	v_sub_f32_e32 v24, v28, v100
	v_exp_f32_e32 v24, v24
	s_waitcnt lgkmcnt(10)
	v_mfma_f32_16x16x32_bf16 v[16:19], v[96:99], v[40:43], v[16:19]
	v_cvt_pk_bf16_f32 v102, v110, v111
	v_cvt_pk_bf16_f32 v103, v112, v113
	v_cndmask_b32_e64 v114, v24, 0, s[26:27]
	v_sub_f32_e32 v24, v29, v100
	v_exp_f32_e32 v24, v24
	s_waitcnt lgkmcnt(6)
	v_mfma_f32_16x16x32_bf16 v[32:35], v[72:75], v[40:43], v[32:35]
	v_mul_f32_e64 v28, v48, v108
	v_mul_f32_e64 v29, v49, v108
	v_add_f32_e32 v48, 0, v110
	v_cndmask_b32_e64 v115, v24, 0, s[28:29]
	v_sub_f32_e32 v24, v30, v100
	v_exp_f32_e32 v24, v24
	v_add_f32_e32 v48, v111, v48
	v_add_f32_e32 v48, v112, v48
	v_add_f32_e32 v48, v113, v48
	v_cndmask_b32_e64 v116, v24, 0, s[30:31]
	v_sub_f32_e32 v24, v31, v100
	v_exp_f32_e32 v24, v24
	v_add_f32_e32 v48, v114, v48
	v_add_f32_e32 v48, v115, v48
	v_cvt_pk_bf16_f32 v104, v114, v115
	v_cndmask_b32_e64 v117, v24, 0, s[34:35]
	v_pk_mul_f32 v[24:25], v[44:45], v[106:107] op_sel_hi:[1,0]
	v_pk_mul_f32 v[44:45], v[60:61], v[106:107] op_sel_hi:[1,0]
	v_cvt_pk_bf16_f32 v105, v116, v117
	v_mfma_f32_16x16x32_bf16 v[24:27], v[88:91], v[40:43], v[24:27]
	v_add_f32_e32 v48, v116, v48
	v_pk_mul_f32 v[38:39], v[58:59], v[108:109] op_sel_hi:[1,0]
	v_pk_mul_f32 v[36:37], v[56:57], v[108:109] op_sel_hi:[1,0]
	s_waitcnt lgkmcnt(4)
	v_mfma_f32_16x16x32_bf16 v[40:43], v[68:71], v[40:43], v[44:47]
	v_mul_f32_e64 v30, v50, v108
	v_mul_f32_e64 v31, v51, v108
	v_pk_mul_f32 v[22:23], v[22:23], v[108:109] op_sel_hi:[1,0]
	v_pk_mul_f32 v[20:21], v[20:21], v[108:109] op_sel_hi:[1,0]
	v_pk_mul_f32 v[46:47], v[66:67], v[108:109] op_sel_hi:[1,0]
	v_pk_mul_f32 v[44:45], v[64:65], v[108:109] op_sel_hi:[1,0]
	s_waitcnt vmcnt(3)
	s_waitcnt vmcnt(1)
	s_waitcnt vmcnt(0)
	v_mfma_f32_16x16x32_bf16 v[4:7], v[76:79], v[12:15], 0
	v_mfma_f32_16x16x32_bf16 v[10:13], v[92:95], v[12:15], 0
	s_nop 5
	v_sub_u32_e32 v9, v198, v145
	v_cmp_gt_u32_e64 s[34:35], v9, v144
	v_mov_b32_e32 v15, v153
	v_mfma_f32_16x16x32_bf16 v[4:7], v[80:83], v[0:3], v[4:7]
	v_mfma_f32_16x16x32_bf16 v[0:3], v[84:87], v[0:3], v[10:13]
	s_nop 2
	v_add_u32_e32 v12, 1, v9
	v_cmp_gt_u32_e64 s[30:31], v12, v144
	s_nop 1
	v_cndmask_b32_e64 v4, v4, v246, s[34:35]
	v_max_f32_e32 v11, 0xf149f2ca, v4
	v_cndmask_b32_e64 v5, v5, v246, s[30:31]
	v_max_f32_e32 v11, v11, v5
	v_add_u32_e32 v12, 2, v9
	v_add_u32_e32 v13, 3, v9
	v_cmp_gt_u32_e64 s[28:29], v12, v144
	v_cmp_gt_u32_e64 s[26:27], v13, v144
	v_mfma_f32_16x16x32_bf16 v[44:47], v[68:71], v[102:105], v[44:47]
	v_cndmask_b32_e64 v6, v6, v246, s[28:29]
	v_cndmask_b32_e64 v7, v7, v246, s[26:27]
	v_max3_f32 v11, v11, v6, v7
	v_add_u32_e32 v12, 16, v9
	v_add_u32_e32 v13, 17, v9
	v_cmp_gt_u32_e64 s[24:25], v12, v144
	v_cmp_gt_u32_e64 s[22:23], v13, v144
	v_add_f32_e32 v68, v117, v48
	v_cndmask_b32_e64 v0, v0, v246, s[24:25]
	v_cndmask_b32_e64 v13, v1, v246, s[22:23]
	v_max3_f32 v11, v11, v0, v13
	v_add_u32_e32 v12, 18, v9
	v_add_u32_e32 v9, 19, v9
	v_cmp_gt_u32_e64 s[0:1], v12, v144
	v_cmp_gt_u32_e32 vcc, v9, v144
	v_add_f32_e32 v48, 0, v107
	v_cndmask_b32_e64 v2, v2, v246, s[0:1]
	v_cndmask_b32_e64 v3, v3, v246, vcc
	v_max3_f32 v9, v11, v2, v3
	s_nop 1
	v_mov_b32_e32 v11, v9
	s_nop 1
	v_permlane32_swap_b32_e32 v11, v9
	v_max_f32_e32 v9, v9, v11
	s_nop 1
	v_mov_b32_e32 v11, v9
	s_nop 1
	v_permlane16_swap_b32_e32 v11, v9
	v_max_f32_e32 v9, v9, v11
	v_mov_b32_e32 v66, 1.0
	v_add_f32_e32 v69, v109, v48
	v_mov_b32_e32 v11, 0
	v_add_f32_e32 v12, 0, v11
	v_mov_b32_e32 v8, 0
	v_fmac_f32_e32 v69, v146, v106
	v_add_f32_e32 v65, v8, v12
	v_cvt_pk_bf16_f32 v14, v8, 0
	v_max_f32_e32 v8, v100, v9
	v_fmac_f32_e32 v65, v69, v66
	v_sub_f32_e32 v4, v4, v8
	v_cvt_pk_bf16_f32 v12, v11, 0
	v_exp_f32_e32 v4, v4
	v_sub_f32_e32 v5, v5, v8
	v_pk_mul_f32 v[10:11], v[34:35], v[66:67] op_sel_hi:[1,0]
	ds_bpermute_b32 v34, v170, v65
	v_exp_f32_e32 v5, v5
	v_sub_f32_e32 v6, v6, v8
	v_exp_f32_e32 v6, v6
	v_sub_f32_e32 v7, v7, v8
	v_exp_f32_e32 v7, v7
	v_sub_f32_e32 v0, v0, v8
	v_sub_f32_e32 v9, v100, v8
	v_exp_f32_e32 v0, v0
	v_sub_f32_e32 v1, v1, v8
	v_mfma_f32_16x16x32_bf16 v[36:39], v[72:75], v[102:105], v[36:39]
	v_exp_f32_e32 v72, v9
	v_add_f32_e32 v9, 0, v4
	v_exp_f32_e32 v1, v1
	v_sub_f32_e32 v2, v2, v8
	s_waitcnt lgkmcnt(0)
	v_add_f32_e32 v34, v65, v34
	v_add_f32_e32 v9, v5, v9
	v_exp_f32_e32 v2, v2
	v_sub_f32_e32 v3, v3, v8
	ds_bpermute_b32 v35, v171, v34
	v_add_f32_e32 v9, v6, v9
	v_exp_f32_e32 v3, v3
	v_add_f32_e32 v9, v7, v9
	v_add_f32_e32 v9, v0, v9
	v_cndmask_b32_e64 v1, v1, 0, s[22:23]
	ds_read_b64_tr_b16 v[62:63], v169 offset:6912
	ds_read_b64_tr_b16 v[60:61], v169 offset:4608
	ds_read_b64_tr_b16 v[56:57], v169 offset:4640
	ds_read_b64_tr_b16 v[58:59], v169 offset:6944
	ds_read_b64_tr_b16 v[52:53], v169 offset:4672
	ds_read_b64_tr_b16 v[54:55], v169 offset:6976
	ds_read_b64_tr_b16 v[48:49], v169 offset:4704
	ds_read_b64_tr_b16 v[50:51], v169 offset:7008
	v_add_f32_e32 v9, v1, v9
	v_add_f32_e32 v9, v2, v9
	s_waitcnt lgkmcnt(8)
	v_add_f32_e32 v34, v34, v35
	v_fmac_f32_e32 v68, v147, v108
	v_mov_b32_e32 v13, v153
	v_add_f32_e32 v64, v3, v9
	v_pk_mul_f32 v[8:9], v[32:33], v[66:67] op_sel_hi:[1,0]
	v_div_scale_f32 v35, s[0:1], v34, v34, 1.0
	v_fmac_f32_e32 v64, v68, v72
	v_cvt_pk_bf16_f32 v68, v4, v5
	v_cvt_pk_bf16_f32 v69, v6, v7
	v_pk_mul_f32 v[6:7], v[26:27], v[66:67] op_sel_hi:[1,0]
	v_pk_mul_f32 v[4:5], v[24:25], v[66:67] op_sel_hi:[1,0]
	s_waitcnt lgkmcnt(2)
	v_mfma_f32_16x16x32_bf16 v[24:27], v[52:55], v[12:15], v[8:11]
	v_cvt_pk_bf16_f32 v70, v0, v1
	v_cvt_pk_bf16_f32 v71, v2, v3
	v_pk_mul_f32 v[2:3], v[18:19], v[66:67] op_sel_hi:[1,0]
	v_pk_mul_f32 v[8:9], v[36:37], v[72:73] op_sel_hi:[1,0]
	v_rcp_f32_e32 v36, v35
	v_mfma_f32_16x16x32_bf16 v[20:23], v[96:99], v[102:105], v[20:23]
	v_mul_f32_e64 v10, v38, v72
	v_mul_f32_e64 v11, v39, v72
	v_pk_mul_f32 v[0:1], v[16:17], v[66:67] op_sel_hi:[1,0]
	v_fma_f32 v37, -v35, v36, 1.0
	v_fmac_f32_e32 v36, v37, v36
	v_div_scale_f32 v37, vcc, 1.0, v34, 1.0
	v_mul_f32_e32 v38, v37, v36
	v_fma_f32 v39, -v35, v38, v37
	v_mfma_f32_16x16x32_bf16 v[16:19], v[60:63], v[12:15], v[0:3]
	v_fmac_f32_e32 v38, v39, v36
	v_fma_f32 v35, -v35, v38, v37
	v_div_fmas_f32 v35, v35, v36, v38
	v_mfma_f32_16x16x32_bf16 v[28:31], v[88:91], v[102:105], v[28:31]
	v_mul_f32_e64 v2, v22, v72
	v_mul_f32_e64 v3, v23, v72
	v_pk_mul_f32 v[0:1], v[20:21], v[72:73] op_sel_hi:[1,0]
	v_div_fixup_f32 v34, v35, v34, 1.0
	v_mfma_f32_16x16x32_bf16 v[20:23], v[56:59], v[12:15], v[4:7]
	v_lshl_add_u64 v[32:33], v[156:157], 0, s[56:57]
	v_lshlrev_b64 v[36:37], 11, v[162:163]
	v_pk_mul_f32 v[16:17], v[16:17], v[34:35] op_sel_hi:[1,0]
	v_pk_mul_f32 v[18:19], v[18:19], v[34:35] op_sel_hi:[1,0]
	v_pk_mul_f32 v[6:7], v[30:31], v[72:73] op_sel_hi:[1,0]
	v_pk_mul_f32 v[4:5], v[28:29], v[72:73] op_sel_hi:[1,0]
	v_pk_mul_f32 v[30:31], v[42:43], v[66:67] op_sel_hi:[1,0]
	v_pk_mul_f32 v[28:29], v[40:41], v[66:67] op_sel_hi:[1,0]
	v_lshl_add_u64 v[36:37], v[32:33], 0, v[36:37]
	v_cvt_pk_bf16_f32 v16, v16, v17
	v_cvt_pk_bf16_f32 v17, v18, v19
	s_waitcnt lgkmcnt(0)
	v_mfma_f32_16x16x32_bf16 v[28:31], v[48:51], v[12:15], v[28:31]
	global_store_dwordx2 v[36:37], v[16:17], off
	v_pk_mul_f32 v[16:17], v[20:21], v[34:35] op_sel_hi:[1,0]
	v_pk_mul_f32 v[18:19], v[22:23], v[34:35] op_sel_hi:[1,0]
	v_cvt_pk_bf16_f32 v16, v16, v17
	v_cvt_pk_bf16_f32 v17, v18, v19
	global_store_dwordx2 v[36:37], v[16:17], off offset:32
	v_pk_mul_f32 v[16:17], v[24:25], v[34:35] op_sel_hi:[1,0]
	v_pk_mul_f32 v[18:19], v[26:27], v[34:35] op_sel_hi:[1,0]
	v_cvt_pk_bf16_f32 v16, v16, v17
	v_cvt_pk_bf16_f32 v17, v18, v19
	global_store_dwordx2 v[36:37], v[16:17], off offset:64
	v_pk_mul_f32 v[16:17], v[28:29], v[34:35] op_sel_hi:[1,0]
	v_pk_mul_f32 v[18:19], v[30:31], v[34:35] op_sel_hi:[1,0]
	v_cvt_pk_bf16_f32 v16, v16, v17
	v_cvt_pk_bf16_f32 v17, v18, v19
	global_store_dwordx2 v[36:37], v[16:17], off offset:96
	ds_bpermute_b32 v16, v170, v64
	v_mfma_f32_16x16x32_bf16 v[0:3], v[60:63], v[68:71], v[0:3]
	v_mul_f32_e64 v14, v46, v72
	v_mul_f32_e64 v15, v47, v72
	v_pk_mul_f32 v[12:13], v[44:45], v[72:73] op_sel_hi:[1,0]
	s_waitcnt lgkmcnt(0)
	v_add_f32_e32 v16, v64, v16
	ds_bpermute_b32 v17, v171, v16
	v_mfma_f32_16x16x32_bf16 v[4:7], v[56:59], v[68:71], v[4:7]
	s_waitcnt lgkmcnt(0)
	v_add_f32_e32 v16, v16, v17
	v_div_scale_f32 v17, s[0:1], v16, v16, 1.0
	v_rcp_f32_e32 v18, v17
	v_mfma_f32_16x16x32_bf16 v[8:11], v[52:55], v[68:71], v[8:11]
	v_fma_f32 v19, -v17, v18, 1.0
	v_fmac_f32_e32 v18, v19, v18
	v_div_scale_f32 v19, vcc, 1.0, v16, 1.0
	v_mul_f32_e32 v20, v19, v18
	v_fma_f32 v21, -v17, v20, v19
	v_fmac_f32_e32 v20, v21, v18
	v_fma_f32 v17, -v17, v20, v19
	v_div_fmas_f32 v17, v17, v18, v20
	v_div_fixup_f32 v16, v17, v16, 1.0
	v_lshlrev_b64 v[18:19], 11, v[160:161]
	v_pk_mul_f32 v[0:1], v[0:1], v[16:17] op_sel_hi:[1,0]
	v_pk_mul_f32 v[2:3], v[2:3], v[16:17] op_sel_hi:[1,0]
	v_lshl_add_u64 v[18:19], v[32:33], 0, v[18:19]
	v_cvt_pk_bf16_f32 v0, v0, v1
	v_cvt_pk_bf16_f32 v1, v2, v3
	v_mfma_f32_16x16x32_bf16 v[12:15], v[48:51], v[68:71], v[12:15]
	global_store_dwordx2 v[18:19], v[0:1], off
	v_pk_mul_f32 v[0:1], v[4:5], v[16:17] op_sel_hi:[1,0]
	v_pk_mul_f32 v[2:3], v[6:7], v[16:17] op_sel_hi:[1,0]
	v_cvt_pk_bf16_f32 v0, v0, v1
	v_cvt_pk_bf16_f32 v1, v2, v3
	global_store_dwordx2 v[18:19], v[0:1], off offset:32
	v_pk_mul_f32 v[0:1], v[8:9], v[16:17] op_sel_hi:[1,0]
	v_pk_mul_f32 v[2:3], v[10:11], v[16:17] op_sel_hi:[1,0]
	v_cvt_pk_bf16_f32 v0, v0, v1
	v_cvt_pk_bf16_f32 v1, v2, v3
	global_store_dwordx2 v[18:19], v[0:1], off offset:64
	v_pk_mul_f32 v[0:1], v[12:13], v[16:17] op_sel_hi:[1,0]
	v_pk_mul_f32 v[2:3], v[14:15], v[16:17] op_sel_hi:[1,0]
	v_cvt_pk_bf16_f32 v0, v0, v1
	v_cvt_pk_bf16_f32 v1, v2, v3
	global_store_dwordx2 v[18:19], v[0:1], off offset:96
	s_cbranch_scc1 .LBB0_246
	s_mov_b32 s76, s79
	v_readlane_b32 s72, v253, 43
	v_xor_b32_e32 v240, 32, v174
	v_xor_b32_e32 v241, 16, v174
	v_xor_b32_e32 v242, 8, v174
	v_xor_b32_e32 v243, 4, v174
	v_xor_b32_e32 v244, 2, v174
	v_xor_b32_e32 v245, 1, v174
	v_and_b32_e32 v246, 64, v174
